# same A(1,1) DMA hoist above the epilogue stores + relaxed third wait applied to conv, KV-up, Q-up and out GEMM instances
# baseline (speedup 1.0000x reference)
; #define PG8_STAGE(bufoff, gbase, voff) do { _Pragma("unroll") for (int _i = 0; _i < 2; ++_i) \
;         __builtin_amdgcn_global_load_lds((const unsigned*)((const char*)(gbase) + (voff)[_i]), (PG8_LAS unsigned*)(lds + (bufoff) + ldsw + _i * 8192), 16, 0, 0); } while (0)
; #define PG8_WAIT_V(n) asm volatile("s_waitcnt vmcnt(" #n ")" ::: "memory")
; #define PG8_BAR __builtin_amdgcn_s_barrier()
; template <class Epi, class Sched, bool ALIGN_EPI = false, bool SP2 = false>
; __device__ __forceinline__ void gemm_phase(PG8_LAS unsigned char* lds, const Gemm g, const Sched& S, const Epi& E) {
;     ...
;     if constexpr (SP2) {
;         PG8_STAGE(PG8_SB(0, 0), cB, voffB); PG8_STAGE(PG8_SB(0, 1), cB + hstep, voffB); PG8_STAGE(PG8_SA(0, 0), cA, voffA); PG8_STAGE(PG8_SA(0, 1), cA + hstep, voffA);
;         if (wr == 1) PG8_BAR;
;         PG8_WAIT_V(2); PG8_BAR;
;         PG8_STAGE(PG8_SB(1, 0), cB + kstep, voffB); PG8_STAGE(PG8_SA(1, 0), cA + kstep, voffA); PG8_STAGE(PG8_SB(1, 1), cB + hstep + kstep, voffB);
;         PG8_WAIT_V(6); PG8_BAR;
;     } else {
;     __device__ __forceinline__ void operator()(const AccT& acc, const Unit& u, int wr, int wc, int fr_, int fq_) const {
;     ...
;         bf16_t* const KN = (bf16_t*)(ws + WS_RA); bf16_t* const VI = (bf16_t*)(ws + WS_VIMG); const float* const ssq_kv = (const float*)(ws + WS_SSQ) + T;
;         float ssv[2][4];
; #pragma unroll
;         for (int ai = 0; ai < 2; ++ai)
; #pragma unroll
;             for (int m = 0; m < 4; ++m) ssv[ai][m] = ssq_kv[(size_t)ROW_OF(ai, m)];
.LBB0_697:
	s_mov_b64 s[16:17], 0x80
	s_add_i32 m0, s40, 0x18000
	v_lshl_add_u64 v[8:9], v[8:9], 0, s[16:17]
	s_waitcnt vmcnt(2)
	s_barrier
	global_load_lds_dwordx4 v[8:9], off
	v_lshl_add_u64 v[4:5], v[4:5], 0, s[16:17]
	s_add_i32 m0, s40, 0x1a000
	s_add_i32 s45, s40, 0x8000
	global_load_lds_dwordx4 v[4:5], off
	v_lshl_add_u64 v[4:5], v[6:7], 0, s[16:17]
	s_mov_b32 m0, s45
	s_add_i32 s46, s40, 0xa000
	global_load_lds_dwordx4 v[4:5], off
	v_lshl_add_u64 v[4:5], v[10:11], 0, s[16:17]
	s_mov_b32 m0, s46
	v_lshl_add_u64 v[2:3], v[2:3], 0, s[16:17]
	global_load_lds_dwordx4 v[4:5], off
	s_add_i32 m0, s40, 0x1c000
	v_lshl_add_u64 v[0:1], v[0:1], 0, s[16:17]
	global_load_lds_dwordx4 v[2:3], off
	s_add_i32 m0, s40, 0x1e000
	s_lshr_b32 s1, s1, 26
	global_load_lds_dwordx4 v[0:1], off
	s_add_i32 s1, s0, s1
	s_and_b32 s4, s4, 3
	s_ashr_i32 s47, s1, 6
	s_lshl_b32 s48, s5, 6
	s_lshl_b32 s1, s5, 13
	s_cmp_gt_i32 s0, 63
	s_cselect_b64 s[18:19], -1, 0
	s_add_i32 s49, s47, -2
	v_lshlrev_b32_e32 v1, 2, v201
	s_cmpk_lt_u32 s20, 0x100
	v_lshl_or_b32 v0, v201, 6, v238
	v_and_b32_e32 v1, 32, v1
	s_cselect_b64 s[20:21], -1, 0
	s_add_u32 s22, s90, 0x5000000
	v_bitop3_b32 v0, v0, s1, v1 bitop3:0xde
	s_addc_u32 s23, s91, 0
	v_add_u32_e32 v1, v237, v235
	s_add_u32 s24, s90, 0x20000
	v_mul_lo_u32 v1, s0, v1
	s_addc_u32 s25, s91, 0
	s_lshl_b32 s1, s4, 9
	v_lshlrev_b32_e32 v1, 1, v1
	s_add_u32 s1, s90, s1
	v_add3_u32 v136, v233, v1, v234
	v_add_u32_e32 v1, v236, v235
	s_addc_u32 s5, s91, 0
	v_mul_lo_u32 v1, s0, v1
	s_waitcnt vmcnt(6)
	s_add_u32 s26, s1, 0x1b000000
	v_lshlrev_b32_e32 v1, 1, v1
	v_lshl_or_b32 v168, s4, 12, v239
	s_addc_u32 s27, s5, 0
	v_lshl_add_u64 v[138:139], s[10:11], 0, v[136:137]
	v_add3_u32 v136, v233, v1, v234
	s_add_i32 s53, 0, 0x10000
	s_add_i32 s54, 0, 0x14000
	s_lshl_b32 s50, s4, 2
	s_ashr_i32 s51, s83, 31
	s_ashr_i32 s52, s80, 31
	v_lshl_add_u64 v[140:141], s[10:11], 0, v[136:137]
	v_mov_b64_e32 v[142:143], 0x400
	v_mov_b64_e32 v[144:145], 0x3ff
	v_add_u32_e32 v169, s53, v168
	v_add_u32_e32 v170, s54, v168
	v_add_u32_e32 v171, 0, v0
	v_mov_b32_e32 v172, 0x358637bd
	s_mov_b32 s55, 0x80000
	s_barrier
	v_lshl_add_u32 v253, s35, 8, v201
	v_add_lshl_u32 v253, v253, s48, 2
	global_load_dword v245, v253, s[24:25]
	global_load_dword v246, v253, s[24:25] offset:64
	global_load_dword v247, v253, s[24:25] offset:128
	global_load_dword v248, v253, s[24:25] offset:192
	global_load_dword v249, v253, s[24:25] offset:512
	global_load_dword v250, v253, s[24:25] offset:576
	global_load_dword v251, v253, s[24:25] offset:640
	global_load_dword v252, v253, s[24:25] offset:704
	s_mov_b32 s101, 0
	s_mov_b32 s99, 0
	s_branch .LBB0_700

; #define PG8_STAGE(bufoff, gbase, voff) do { _Pragma("unroll") for (int _i = 0; _i < 2; ++_i) \
;         __builtin_amdgcn_global_load_lds((const unsigned*)((const char*)(gbase) + (voff)[_i]), (PG8_LAS unsigned*)(lds + (bufoff) + ldsw + _i * 8192), 16, 0, 0); } while (0)
; #define PG8_LDA(dst, b, h) do { _Pragma("unroll") for (int m = 0; m < 4; ++m) _Pragma("unroll") for (int k = 0; k < 2; ++k) dst[m][k] = *(const PG8_LAS bf16x8*)(lds + PG8_SA(b, h) + aoff + m * 2048 + k * 1024); } while (0)
; #define PG8_LDB(dst, b, h) do { _Pragma("unroll") for (int n = 0; n < 2; ++n) _Pragma("unroll") for (int k = 0; k < 2; ++k) dst[n][k] = *(const PG8_LAS bf16x8*)(lds + PG8_SB(b, h) + boff + n * 2048 + k * 1024); } while (0)
; #define PG8_SCHED __builtin_amdgcn_sched_barrier(0)
; template <class Epi, class Sched, bool ALIGN_EPI = false, bool SP2 = false>
; __device__ __forceinline__ void gemm_phase(PG8_LAS unsigned char* lds, const Gemm g, const Sched& S, const Epi& E) {
;     ...
;             const bool last = (t == nt - 2);
;             const char* a1 = cA + (size_t)(t + 1) * kstep;
;             const char* a2 = last ? nA : cA + (size_t)(t + 2) * kstep; const char* b2 = last ? nB : cB + (size_t)(t + 2) * kstep;
;             const char* a3 = a2 + kstep; const char* b3 = b2 + kstep;
;             if (last && has_next) S.a_ready(nxt);
;             if constexpr (SP2) {
;             PG8_LDB(B0, 0, 0); PG8_LDB(B1, 0, 1); PG8_SCHED; PG8_LDA(At, 0, 0); PG8_STAGE(PG8_SA(1, 1), a1 + hstep, voffA);
.LBB0_710:
	s_andn2_b64 vcc, exec, s[18:19]
	s_cbranch_vccnz .LBB0_713
	s_add_u32 s6, s6, 0x80
	s_addc_u32 s7, s7, 0
	s_add_u32 s58, s30, 0x100
	s_addc_u32 s59, s31, 0
	s_mov_b32 s30, 0
	ds_read_b128 v[146:149], v169
	ds_read_b128 v[150:153], v169 offset:1024
	ds_read_b128 v[154:157], v169 offset:2048
	ds_read_b128 v[158:161], v169 offset:3072
	ds_read_b128 v[162:165], v170
	ds_read_b128 v[174:177], v170 offset:1024
	ds_read_b128 v[178:181], v170 offset:2048
	ds_read_b128 v[182:185], v170 offset:3072
	s_add_i32 s60, s30, 2
	s_add_u32 s61, s6, 0x80
	s_addc_u32 s31, s7, 0
	s_cmp_eq_u32 s49, s30
	s_cselect_b32 s30, s0, s61
	s_cselect_b32 s31, s1, s31
	s_cselect_b32 s63, s29, s59
	s_cselect_b32 s62, s28, s58
	v_lshl_add_u64 v[166:167], s[6:7], 0, v[138:139]
	s_add_i32 m0, s40, 0xc000
	ds_read_b128 v[186:189], v171
	ds_read_b128 v[190:193], v171 offset:1024
	ds_read_b128 v[194:197], v171 offset:2048
	ds_read_b128 v[202:205], v171 offset:3072
	ds_read_b128 v[206:209], v171 offset:4096
	ds_read_b128 v[210:213], v171 offset:5120
	ds_read_b128 v[214:217], v171 offset:6144
	ds_read_b128 v[218:221], v171 offset:7168
	s_cmp_lg_u32 s101, 0
	s_cbranch_scc1 .Ly1_skip_1
	global_load_lds_dwordx4 v[166:167], off
	v_lshl_add_u64 v[166:167], s[6:7], 0, v[140:141]
	s_add_i32 m0, s40, 0xe000
	s_nop 0
	global_load_lds_dwordx4 v[166:167], off

; #define PG8_STAGE(bufoff, gbase, voff) do { _Pragma("unroll") for (int _i = 0; _i < 2; ++_i) \
;         __builtin_amdgcn_global_load_lds((const unsigned*)((const char*)(gbase) + (voff)[_i]), (PG8_LAS unsigned*)(lds + (bufoff) + ldsw + _i * 8192), 16, 0, 0); } while (0)
; #define PG8_LDA(dst, b, h) do { _Pragma("unroll") for (int m = 0; m < 4; ++m) _Pragma("unroll") for (int k = 0; k < 2; ++k) dst[m][k] = *(const PG8_LAS bf16x8*)(lds + PG8_SA(b, h) + aoff + m * 2048 + k * 1024); } while (0)
; #define PG8_LDB(dst, b, h) do { _Pragma("unroll") for (int n = 0; n < 2; ++n) _Pragma("unroll") for (int k = 0; k < 2; ++k) dst[n][k] = *(const PG8_LAS bf16x8*)(lds + PG8_SB(b, h) + boff + n * 2048 + k * 1024); } while (0)
; #define PG8_MMA(ai, bj, At, Bt) do { __builtin_amdgcn_s_setprio(1); _Pragma("unroll") for (int m = 0; m < 4; ++m) _Pragma("unroll") for (int n = 0; n < 2; ++n) _Pragma("unroll") for (int k = 0; k < 2; ++k) \
;         acc[ai][bj][m][n] = __builtin_amdgcn_mfma_f32_16x16x32_bf16(Bt[n][k], At[m][k], acc[ai][bj][m][n], 0, 0, 0); __builtin_amdgcn_s_setprio(0); } while (0)
; #define PG8_WAIT_V(n) asm volatile("s_waitcnt vmcnt(" #n ")" ::: "memory")
; #define PG8_WAIT_L(n) asm volatile("s_waitcnt lgkmcnt(" #n ")" ::: "memory")
; #define PG8_BAR __builtin_amdgcn_s_barrier()
; #define PG8_SCHED __builtin_amdgcn_sched_barrier(0)
; template <class Epi, class Sched, bool ALIGN_EPI = false, bool SP2 = false>
; __device__ __forceinline__ void gemm_phase(PG8_LAS unsigned char* lds, const Gemm g, const Sched& S, const Epi& E) {
;     ...
;             PG8_WAIT_V(8); PG8_WAIT_L(0); PG8_BAR; PG8_MMA(0, 0, At, B0); PG8_MMA(0, 1, At, B1); PG8_BAR; PG8_SCHED;
;             PG8_LDA(At, 0, 1); PG8_STAGE(PG8_SB(0, 0), b2, voffB); PG8_STAGE(PG8_SB(0, 1), b2 + hstep, voffB); PG8_STAGE(PG8_SA(0, 0), a2, voffA);
;             PG8_WAIT_V(8); PG8_WAIT_L(0); PG8_BAR; PG8_MMA(1, 0, At, B0); PG8_MMA(1, 1, At, B1); PG8_BAR; PG8_SCHED;
;             PG8_LDB(B0, 1, 0); PG8_LDB(B1, 1, 1); PG8_SCHED; PG8_LDA(At, 1, 0); PG8_STAGE(PG8_SA(0, 1), a2 + hstep, voffA);
;             PG8_WAIT_V(8); PG8_WAIT_L(0); PG8_BAR; PG8_MMA(0, 0, At, B0); PG8_MMA(0, 1, At, B1); PG8_BAR; PG8_SCHED;
.Lwj_1_1:
	s_waitcnt lgkmcnt(0)
	s_barrier
	s_setprio 1
	s_waitcnt lgkmcnt(0)
	v_mfma_f32_16x16x32_bf16 v[60:63], v[146:149], v[186:189], 0
	v_mfma_f32_16x16x32_bf16 v[56:59], v[154:157], v[186:189], 0
	v_mfma_f32_16x16x32_bf16 v[44:47], v[146:149], v[194:197], 0
	v_mfma_f32_16x16x32_bf16 v[40:43], v[154:157], v[194:197], 0
	v_mfma_f32_16x16x32_bf16 v[28:31], v[146:149], v[206:209], 0
	v_mfma_f32_16x16x32_bf16 v[24:27], v[154:157], v[206:209], 0
	v_mfma_f32_16x16x32_bf16 v[12:15], v[146:149], v[214:217], 0
	v_mfma_f32_16x16x32_bf16 v[8:11], v[154:157], v[214:217], 0
	v_mfma_f32_16x16x32_bf16 v[60:63], v[150:153], v[190:193], v[60:63]
	v_mfma_f32_16x16x32_bf16 v[56:59], v[158:161], v[190:193], v[56:59]
	v_mfma_f32_16x16x32_bf16 v[44:47], v[150:153], v[202:205], v[44:47]
	v_mfma_f32_16x16x32_bf16 v[40:43], v[158:161], v[202:205], v[40:43]
	v_mfma_f32_16x16x32_bf16 v[28:31], v[150:153], v[210:213], v[28:31]
	v_mfma_f32_16x16x32_bf16 v[24:27], v[158:161], v[210:213], v[24:27]
	v_mfma_f32_16x16x32_bf16 v[12:15], v[150:153], v[218:221], v[12:15]
	v_mfma_f32_16x16x32_bf16 v[8:11], v[158:161], v[218:221], v[8:11]
	s_setprio 0
	s_setprio 1
	v_mfma_f32_16x16x32_bf16 v[52:55], v[162:165], v[186:189], 0
	v_mfma_f32_16x16x32_bf16 v[48:51], v[178:181], v[186:189], 0
	v_mfma_f32_16x16x32_bf16 v[36:39], v[162:165], v[194:197], 0
	v_mfma_f32_16x16x32_bf16 v[32:35], v[178:181], v[194:197], 0
	v_mfma_f32_16x16x32_bf16 v[20:23], v[162:165], v[206:209], 0
	v_mfma_f32_16x16x32_bf16 v[16:19], v[178:181], v[206:209], 0
	v_mfma_f32_16x16x32_bf16 v[0:3], v[162:165], v[214:217], 0
	v_mfma_f32_16x16x32_bf16 v[4:7], v[178:181], v[214:217], 0
	v_mfma_f32_16x16x32_bf16 v[52:55], v[174:177], v[190:193], v[52:55]
	v_mfma_f32_16x16x32_bf16 v[48:51], v[182:185], v[190:193], v[48:51]
	v_mfma_f32_16x16x32_bf16 v[36:39], v[174:177], v[202:205], v[36:39]
	v_mfma_f32_16x16x32_bf16 v[32:35], v[182:185], v[202:205], v[32:35]
	v_mfma_f32_16x16x32_bf16 v[20:23], v[174:177], v[210:213], v[20:23]
	v_mfma_f32_16x16x32_bf16 v[16:19], v[182:185], v[210:213], v[16:19]
	v_mfma_f32_16x16x32_bf16 v[0:3], v[174:177], v[218:221], v[0:3]
	v_mfma_f32_16x16x32_bf16 v[4:7], v[182:185], v[218:221], v[4:7]
	s_setprio 0
	s_barrier
	s_add_i32 s61, 0, 0x18000
	v_add_u32_e32 v136, s61, v168
	s_add_i32 s62, 0, 0x1c000
	ds_read_b128 v[146:149], v136
	ds_read_b128 v[150:153], v136 offset:1024
	ds_read_b128 v[154:157], v136 offset:2048
	ds_read_b128 v[158:161], v136 offset:3072
	v_add_u32_e32 v136, s62, v168
	ds_read_b128 v[162:165], v136
	ds_read_b128 v[174:177], v136 offset:1024
	ds_read_b128 v[178:181], v136 offset:2048
	ds_read_b128 v[182:185], v136 offset:3072
	s_add_u32 s30, s30, s10
	s_addc_u32 s31, s31, s11
	s_mov_b32 m0, s42
	v_lshl_add_u64 v[230:231], s[30:31], 0, v[128:129]
	ds_read_b128 v[186:189], v171 offset:32768
	ds_read_b128 v[190:193], v171 offset:33792
	ds_read_b128 v[194:197], v171 offset:34816
	ds_read_b128 v[202:205], v171 offset:35840
	ds_read_b128 v[206:209], v171 offset:36864
	ds_read_b128 v[210:213], v171 offset:37888
	ds_read_b128 v[214:217], v171 offset:38912
	ds_read_b128 v[218:221], v171 offset:39936
	global_load_lds_dwordx4 v[230:231], off
	v_lshl_add_u64 v[230:231], s[30:31], 0, v[132:133]
	s_mov_b32 m0, s43
	s_nop 0
	global_load_lds_dwordx4 v[230:231], off
	s_cmp_eq_u32 s99, 0
	s_cbranch_scc1 .Lw8_1_2
	s_waitcnt vmcnt(16)
	s_branch .Lwj_1_2

; #define PG8_STAGE(bufoff, gbase, voff) do { _Pragma("unroll") for (int _i = 0; _i < 2; ++_i) \
;         __builtin_amdgcn_global_load_lds((const unsigned*)((const char*)(gbase) + (voff)[_i]), (PG8_LAS unsigned*)(lds + (bufoff) + ldsw + _i * 8192), 16, 0, 0); } while (0)
; #define PG8_LDA(dst, b, h) do { _Pragma("unroll") for (int m = 0; m < 4; ++m) _Pragma("unroll") for (int k = 0; k < 2; ++k) dst[m][k] = *(const PG8_LAS bf16x8*)(lds + PG8_SA(b, h) + aoff + m * 2048 + k * 1024); } while (0)
; #define PG8_LDB(dst, b, h) do { _Pragma("unroll") for (int n = 0; n < 2; ++n) _Pragma("unroll") for (int k = 0; k < 2; ++k) dst[n][k] = *(const PG8_LAS bf16x8*)(lds + PG8_SB(b, h) + boff + n * 2048 + k * 1024); } while (0)
; #define PG8_MMA(ai, bj, At, Bt) do { __builtin_amdgcn_s_setprio(1); _Pragma("unroll") for (int m = 0; m < 4; ++m) _Pragma("unroll") for (int n = 0; n < 2; ++n) _Pragma("unroll") for (int k = 0; k < 2; ++k) \
;         acc[ai][bj][m][n] = __builtin_amdgcn_mfma_f32_16x16x32_bf16(Bt[n][k], At[m][k], acc[ai][bj][m][n], 0, 0, 0); __builtin_amdgcn_s_setprio(0); } while (0)
; #define PG8_WAIT_V(n) asm volatile("s_waitcnt vmcnt(" #n ")" ::: "memory")
; #define PG8_WAIT_L(n) asm volatile("s_waitcnt lgkmcnt(" #n ")" ::: "memory")
; #define PG8_BAR __builtin_amdgcn_s_barrier()
; #define PG8_SCHED __builtin_amdgcn_sched_barrier(0)
; template <class Epi, class Sched, bool ALIGN_EPI = false, bool SP2 = false>
; __device__ __forceinline__ void gemm_phase(PG8_LAS unsigned char* lds, const Gemm g, const Sched& S, const Epi& E) {
;     ...
;             PG8_WAIT_V(8); PG8_WAIT_L(0); PG8_BAR; PG8_MMA(1, 0, At, B0); PG8_MMA(1, 1, At, B1); PG8_BAR; PG8_SCHED;
;             PG8_LDB(B0, 1, 0); PG8_LDB(B1, 1, 1); PG8_SCHED; PG8_LDA(At, 1, 0); PG8_STAGE(PG8_SA(0, 1), a2 + hstep, voffA);
;             PG8_WAIT_V(8); PG8_WAIT_L(0); PG8_BAR; PG8_MMA(0, 0, At, B0); PG8_MMA(0, 1, At, B1); PG8_BAR; PG8_SCHED;
;             PG8_LDA(At, 1, 1); PG8_STAGE(PG8_SB(1, 0), b3, voffB); PG8_STAGE(PG8_SB(1, 1), b3 + hstep, voffB); PG8_STAGE(PG8_SA(1, 0), a3, voffA);
;             PG8_WAIT_V(8); PG8_WAIT_L(0); PG8_BAR; PG8_MMA(1, 0, At, B0); PG8_MMA(1, 1, At, B1); PG8_BAR; PG8_SCHED;
.Lwj_1_2:
	s_waitcnt lgkmcnt(0)
	s_barrier
	s_setprio 1
	s_waitcnt lgkmcnt(0)
	v_mfma_f32_16x16x32_bf16 v[120:123], v[146:149], v[186:189], v[120:123]
	v_mfma_f32_16x16x32_bf16 v[124:127], v[154:157], v[186:189], v[124:127]
	v_mfma_f32_16x16x32_bf16 v[108:111], v[146:149], v[194:197], v[108:111]
	v_mfma_f32_16x16x32_bf16 v[104:107], v[154:157], v[194:197], v[104:107]
	v_mfma_f32_16x16x32_bf16 v[92:95], v[146:149], v[206:209], v[92:95]
	v_mfma_f32_16x16x32_bf16 v[88:91], v[154:157], v[206:209], v[88:91]
	v_mfma_f32_16x16x32_bf16 v[76:79], v[146:149], v[214:217], v[76:79]
	v_mfma_f32_16x16x32_bf16 v[72:75], v[154:157], v[214:217], v[72:75]
	v_mfma_f32_16x16x32_bf16 v[120:123], v[150:153], v[190:193], v[120:123]
	v_mfma_f32_16x16x32_bf16 v[124:127], v[158:161], v[190:193], v[124:127]
	v_mfma_f32_16x16x32_bf16 v[108:111], v[150:153], v[202:205], v[108:111]
	v_mfma_f32_16x16x32_bf16 v[104:107], v[158:161], v[202:205], v[104:107]
	v_mfma_f32_16x16x32_bf16 v[92:95], v[150:153], v[210:213], v[92:95]
	v_mfma_f32_16x16x32_bf16 v[88:91], v[158:161], v[210:213], v[88:91]
	v_mfma_f32_16x16x32_bf16 v[76:79], v[150:153], v[218:221], v[76:79]
	v_mfma_f32_16x16x32_bf16 v[72:75], v[158:161], v[218:221], v[72:75]
	s_setprio 0
	s_setprio 1
	v_mfma_f32_16x16x32_bf16 v[116:119], v[162:165], v[186:189], v[116:119]
	v_mfma_f32_16x16x32_bf16 v[112:115], v[178:181], v[186:189], v[112:115]
	v_mfma_f32_16x16x32_bf16 v[100:103], v[162:165], v[194:197], v[100:103]
	v_mfma_f32_16x16x32_bf16 v[96:99], v[178:181], v[194:197], v[96:99]
	v_mfma_f32_16x16x32_bf16 v[84:87], v[162:165], v[206:209], v[84:87]
	v_mfma_f32_16x16x32_bf16 v[80:83], v[178:181], v[206:209], v[80:83]
	v_mfma_f32_16x16x32_bf16 v[68:71], v[162:165], v[214:217], v[68:71]
	v_mfma_f32_16x16x32_bf16 v[64:67], v[178:181], v[214:217], v[64:67]
	v_mfma_f32_16x16x32_bf16 v[116:119], v[174:177], v[190:193], v[116:119]
	v_mfma_f32_16x16x32_bf16 v[112:115], v[182:185], v[190:193], v[112:115]
	v_mfma_f32_16x16x32_bf16 v[100:103], v[174:177], v[202:205], v[100:103]
	v_mfma_f32_16x16x32_bf16 v[96:99], v[182:185], v[202:205], v[96:99]
	v_mfma_f32_16x16x32_bf16 v[84:87], v[174:177], v[210:213], v[84:87]
	v_mfma_f32_16x16x32_bf16 v[80:83], v[182:185], v[210:213], v[80:83]
	v_mfma_f32_16x16x32_bf16 v[68:71], v[174:177], v[218:221], v[68:71]
	v_mfma_f32_16x16x32_bf16 v[64:67], v[182:185], v[218:221], v[64:67]
	s_setprio 0
	s_barrier
	s_add_i32 s30, s61, s39
	v_lshl_add_u64 v[166:167], v[166:167], 0, s[16:17]
	s_mov_b32 m0, s30
	ds_read_b128 v[186:189], v171 offset:49152
	ds_read_b128 v[190:193], v171 offset:50176
	ds_read_b128 v[194:197], v171 offset:51200
	ds_read_b128 v[202:205], v171 offset:52224
	ds_read_b128 v[206:209], v171 offset:53248
	ds_read_b128 v[210:213], v171 offset:54272
	ds_read_b128 v[214:217], v171 offset:55296
	ds_read_b128 v[218:221], v171 offset:56320
	global_load_lds_dwordx4 v[166:167], off
	v_lshl_add_u64 v[166:167], v[198:199], 0, s[16:17]
	s_add_i32 m0, s30, 0x2000
	s_add_i32 s30, s62, s39
	global_load_lds_dwordx4 v[166:167], off
	v_lshl_add_u64 v[166:167], v[222:223], 0, s[16:17]
	s_mov_b32 m0, s30
	s_nop 0
	global_load_lds_dwordx4 v[166:167], off
	v_lshl_add_u64 v[166:167], v[224:225], 0, s[16:17]
	s_add_i32 m0, s30, 0x2000
	s_nop 0
	global_load_lds_dwordx4 v[166:167], off
	v_lshl_add_u64 v[166:167], v[226:227], 0, s[16:17]
	s_mov_b32 m0, s45
	s_nop 0
	global_load_lds_dwordx4 v[166:167], off
	v_lshl_add_u64 v[166:167], v[228:229], 0, s[16:17]
	s_mov_b32 m0, s46
	s_nop 0
	global_load_lds_dwordx4 v[166:167], off
	s_waitcnt vmcnt(8)
	s_waitcnt lgkmcnt(0)
	s_barrier
	s_setprio 1
	s_waitcnt lgkmcnt(0)
	v_mfma_f32_16x16x32_bf16 v[60:63], v[146:149], v[186:189], v[60:63]
	v_mfma_f32_16x16x32_bf16 v[56:59], v[154:157], v[186:189], v[56:59]
	v_mfma_f32_16x16x32_bf16 v[44:47], v[146:149], v[194:197], v[44:47]
	v_mfma_f32_16x16x32_bf16 v[40:43], v[154:157], v[194:197], v[40:43]
	v_mfma_f32_16x16x32_bf16 v[28:31], v[146:149], v[206:209], v[28:31]
	v_mfma_f32_16x16x32_bf16 v[24:27], v[154:157], v[206:209], v[24:27]
	v_mfma_f32_16x16x32_bf16 v[12:15], v[146:149], v[214:217], v[12:15]
	v_mfma_f32_16x16x32_bf16 v[8:11], v[154:157], v[214:217], v[8:11]
	v_mfma_f32_16x16x32_bf16 v[60:63], v[150:153], v[190:193], v[60:63]
	v_mfma_f32_16x16x32_bf16 v[56:59], v[158:161], v[190:193], v[56:59]
	v_mfma_f32_16x16x32_bf16 v[44:47], v[150:153], v[202:205], v[44:47]
	v_mfma_f32_16x16x32_bf16 v[40:43], v[158:161], v[202:205], v[40:43]
	v_mfma_f32_16x16x32_bf16 v[28:31], v[150:153], v[210:213], v[28:31]
	v_mfma_f32_16x16x32_bf16 v[24:27], v[158:161], v[210:213], v[24:27]
	v_mfma_f32_16x16x32_bf16 v[12:15], v[150:153], v[218:221], v[12:15]
	v_mfma_f32_16x16x32_bf16 v[8:11], v[158:161], v[218:221], v[8:11]
	s_setprio 0
	s_setprio 1
	v_mfma_f32_16x16x32_bf16 v[52:55], v[162:165], v[186:189], v[52:55]
	v_mfma_f32_16x16x32_bf16 v[48:51], v[178:181], v[186:189], v[48:51]
	v_mfma_f32_16x16x32_bf16 v[36:39], v[162:165], v[194:197], v[36:39]
	v_mfma_f32_16x16x32_bf16 v[32:35], v[178:181], v[194:197], v[32:35]
	v_mfma_f32_16x16x32_bf16 v[20:23], v[162:165], v[206:209], v[20:23]
	v_mfma_f32_16x16x32_bf16 v[16:19], v[178:181], v[206:209], v[16:19]
	v_mfma_f32_16x16x32_bf16 v[0:3], v[162:165], v[214:217], v[0:3]
	v_mfma_f32_16x16x32_bf16 v[4:7], v[178:181], v[214:217], v[4:7]
	v_mfma_f32_16x16x32_bf16 v[52:55], v[174:177], v[190:193], v[52:55]
	v_mfma_f32_16x16x32_bf16 v[48:51], v[182:185], v[190:193], v[48:51]
	v_mfma_f32_16x16x32_bf16 v[36:39], v[174:177], v[202:205], v[36:39]
	v_mfma_f32_16x16x32_bf16 v[32:35], v[182:185], v[202:205], v[32:35]
	v_mfma_f32_16x16x32_bf16 v[20:23], v[174:177], v[210:213], v[20:23]
	v_mfma_f32_16x16x32_bf16 v[16:19], v[182:185], v[210:213], v[16:19]
	v_mfma_f32_16x16x32_bf16 v[0:3], v[174:177], v[218:221], v[0:3]
	v_mfma_f32_16x16x32_bf16 v[4:7], v[182:185], v[218:221], v[4:7]
	s_setprio 0
	s_barrier
	s_add_u32 s6, s6, 0x100
	s_addc_u32 s7, s7, 0
	s_add_u32 s58, s58, 0x100
	s_addc_u32 s59, s59, 0
	s_cmp_ge_i32 s60, s47
	s_mov_b32 s30, s60
	s_cbranch_scc1 .LBB0_713

; __device__ __forceinline__ u32x4 pk8(f32x4 a, f32x4 b) { u32x4 w; w.x = pk2(a[0], a[1]); w.y = pk2(a[2], a[3]); w.z = pk2(b[0], b[1]); w.w = pk2(b[2], b[3]); return w; }
; __device__ __forceinline__ void st16(bf16_t* p, u32x4 v) { __builtin_nontemporal_store(v, (u32x4*)p); }
;     __device__ __forceinline__ void operator()(const AccT& acc, const Unit& u, int wr, int wc, int fr_, int fq_) const {
;         int fr = fr_, fq = fq_; asm volatile("" : "+v"(fr), "+v"(fq));
;         const int pn = u.pn;
;         bf16_t* const KN = (bf16_t*)(ws + WS_RA); bf16_t* const VI = (bf16_t*)(ws + WS_VIMG); const float* const ssq_kv = (const float*)(ws + WS_SSQ) + T;
;         float ssv[2][4];
; #pragma unroll
;         for (int ai = 0; ai < 2; ++ai)
; #pragma unroll
;             for (int m = 0; m < 4; ++m) ssv[ai][m] = ssq_kv[(size_t)ROW_OF(ai, m)];
; #pragma unroll
;         for (int ai = 0; ai < 2; ++ai)
; #pragma unroll
;             for (int m = 0; m < 4; ++m) {
;                 const size_t row = (size_t)ROW_OF(ai, m);
;                 const float sc = __builtin_amdgcn_rsqf(ssv[ai][m] * (1.0f / KVLORA) + EPS);
;                 const int b = (int)(row >> 11), s = (int)(row & 2047);
;                 const f32x4 a0 = acc[ai][0][m][0] * sc, a1 = acc[ai][0][m][1] * sc, b0 = acc[ai][1][m][0] * sc, b1 = acc[ai][1][m][1] * sc;
;                 if (pn < 4) {
;                     const int ks = 2 * wc + (fq >> 1), h = fq & 1;
;                     bf16_t* p = KN + ((size_t)((b * 8 + 2 * pn) * 64 + (s >> 5))) * 4096 + (ks * 2 + h) * 256 + (s & 31) * 8;
;                     st16(p, pk8(a0, a1)); st16(p + (size_t)64 * 4096, pk8(b0, b1));
.LBB0_715:
	s_mov_b32 s99, 1
	v_lshl_add_u64 v[166:167], s[0:1], 0, v[138:139]
	v_lshl_add_u64 v[166:167], v[166:167], 0, 64
	v_lshl_add_u64 v[166:167], v[166:167], 0, 64
	s_add_i32 m0, s40, 0xc000
	s_mov_b32 s101, 1
	global_load_lds_dwordx4 v[166:167], off
	v_lshl_add_u64 v[166:167], s[0:1], 0, v[140:141]
	v_lshl_add_u64 v[166:167], v[166:167], 0, 64
	v_lshl_add_u64 v[166:167], v[166:167], 0, 64
	s_add_i32 m0, s40, 0xe000
	s_nop 0
	global_load_lds_dwordx4 v[166:167], off
	s_lshl_b32 s6, s35, 8
	v_mov_b32_e32 v167, v201
	v_mov_b32_e32 v173, v232
	s_add_i32 s6, s6, s48
	s_cmp_gt_i32 s34, 3
	v_add_u32_e32 v162, s6, v167
	v_ashrrev_i32_e32 v163, 31, v162
	v_lshl_add_u64 v[146:147], v[162:163], 2, s[24:25]
	v_add_u32_e32 v160, 16, v162
	v_mov_b32_e32 v166, v245
	v_ashrrev_i32_e32 v161, 31, v160
	v_add_u32_e32 v158, 32, v162
	v_add_u32_e32 v156, 48, v162
	v_add_u32_e32 v154, 0x80, v162
	v_add_u32_e32 v152, 0x90, v162
	v_add_u32_e32 v150, 0xa0, v162
	v_add_u32_e32 v146, 0xb0, v162
	v_lshl_add_u64 v[148:149], v[160:161], 2, s[24:25]
	v_ashrrev_i32_e32 v159, 31, v158
	v_ashrrev_i32_e32 v157, 31, v156
	v_ashrrev_i32_e32 v155, 31, v154
	v_ashrrev_i32_e32 v153, 31, v152
	v_ashrrev_i32_e32 v151, 31, v150
	v_ashrrev_i32_e32 v147, 31, v146
	v_lshl_add_u64 v[164:165], v[158:159], 2, s[24:25]
	v_lshl_add_u64 v[174:175], v[156:157], 2, s[24:25]
	v_lshl_add_u64 v[176:177], v[154:155], 2, s[24:25]
	v_lshl_add_u64 v[178:179], v[152:153], 2, s[24:25]
	v_lshl_add_u64 v[180:181], v[150:151], 2, s[24:25]
	v_lshl_add_u64 v[182:183], v[146:147], 2, s[24:25]
	v_mov_b32_e32 v161, v246
	v_mov_b32_e32 v159, v247
	v_mov_b32_e32 v157, v248
	v_mov_b32_e32 v155, v249
	v_mov_b32_e32 v153, v250
	v_mov_b32_e32 v151, v251
	v_mov_b32_e32 v147, v252
	v_lshlrev_b32_e32 v136, 6, v167
	v_lshlrev_b32_e32 v148, 3, v173
	v_and_b32_e32 v136, 0x1c0, v136
	s_cselect_b64 s[30:31], -1, 0
	s_lshl_b32 s58, s34, 9
	v_ashrrev_i32_e32 v149, 31, v148
	v_lshl_add_u64 v[174:175], s[26:27], 0, v[136:137]
	s_mov_b64 s[6:7], -1
	v_and_b32_e32 v163, 0x7ff, v162
	s_addk_i32 s58, 0xf800
	s_and_b64 vcc, exec, s[30:31]
	v_lshl_add_u64 v[148:149], v[148:149], 1, v[174:175]
	v_lshl_add_u32 v253, s57, 8, v201
	v_add_lshl_u32 v253, v253, s48, 2
	global_load_dword v245, v253, s[24:25]
	global_load_dword v246, v253, s[24:25] offset:64
	global_load_dword v247, v253, s[24:25] offset:128
	global_load_dword v248, v253, s[24:25] offset:192
	global_load_dword v249, v253, s[24:25] offset:512
	global_load_dword v250, v253, s[24:25] offset:576
	global_load_dword v251, v253, s[24:25] offset:640
	global_load_dword v252, v253, s[24:25] offset:704
	s_waitcnt vmcnt(8)
	v_fmamk_f32 v166, v166, 0x3b800000, v172
	v_rsq_f32_e32 v166, v166
	s_nop 0
	v_pk_mul_f32 v[122:123], v[122:123], v[166:167] op_sel_hi:[1,0]
	v_pk_mul_f32 v[120:121], v[120:121], v[166:167] op_sel_hi:[1,0]
	v_pk_mul_f32 v[126:127], v[126:127], v[166:167] op_sel_hi:[1,0]
	v_pk_mul_f32 v[124:125], v[124:125], v[166:167] op_sel_hi:[1,0]
	v_cvt_pk_bf16_f32 v120, v120, v121
	v_cvt_pk_bf16_f32 v121, v122, v123
	v_cvt_pk_bf16_f32 v122, v124, v125
	v_cvt_pk_bf16_f32 v123, v126, v127
	s_cbranch_vccz .LBB0_717
	v_and_b32_e32 v124, 0xfffff800, v162
	v_add_u32_e32 v124, s58, v124
	v_lshrrev_b32_e32 v125, 3, v163
	v_or_b32_e32 v124, v124, v125
	v_ashrrev_i32_e32 v125, 31, v124
	v_lshlrev_b64 v[124:125], 11, v[124:125]
	v_lshl_add_u64 v[164:165], v[148:149], 0, v[124:125]
	global_store_dwordx4 v[164:165], v[120:123], off nt
	s_mov_b64 s[6:7], 0

; #define PG8_STAGE(bufoff, gbase, voff) do { _Pragma("unroll") for (int _i = 0; _i < 2; ++_i) \
;         __builtin_amdgcn_global_load_lds((const unsigned*)((const char*)(gbase) + (voff)[_i]), (PG8_LAS unsigned*)(lds + (bufoff) + ldsw + _i * 8192), 16, 0, 0); } while (0)
; #define PG8_WAIT_V(n) asm volatile("s_waitcnt vmcnt(" #n ")" ::: "memory")
; #define PG8_BAR __builtin_amdgcn_s_barrier()
; template <class Epi, class Sched, bool ALIGN_EPI = false, bool SP2 = false>
; __device__ __forceinline__ void gemm_phase(PG8_LAS unsigned char* lds, const Gemm g, const Sched& S, const Epi& E) {
;     ...
;     if constexpr (SP2) {
;         PG8_STAGE(PG8_SB(0, 0), cB, voffB); PG8_STAGE(PG8_SB(0, 1), cB + hstep, voffB); PG8_STAGE(PG8_SA(0, 0), cA, voffA); PG8_STAGE(PG8_SA(0, 1), cA + hstep, voffA);
;         if (wr == 1) PG8_BAR;
;         PG8_WAIT_V(2); PG8_BAR;
;         PG8_STAGE(PG8_SB(1, 0), cB + kstep, voffB); PG8_STAGE(PG8_SA(1, 0), cA + kstep, voffA); PG8_STAGE(PG8_SB(1, 1), cB + hstep + kstep, voffB);
;         PG8_WAIT_V(6); PG8_BAR;
;     } else {
;     __device__ __forceinline__ void operator()(const AccT& acc, const Unit& u, int wr, int wc, int fr_, int fq_) const {
;     ...
;         const int c0 = u.pn * 128 + wc * 32 + 8 * fq;
;         const bf16_t* const U = (const bf16_t*)(ws + WS_RB); bf16_t* const A2 = (bf16_t*)(ws + WS_A2);
;         const f32x4 w0a = *(const f32x4*)(conv_w + c0), w0b = *(const f32x4*)(conv_w + c0 + 4);
;         const f32x4 w1a = *(const f32x4*)(conv_w + 1024 + c0), w1b = *(const f32x4*)(conv_w + 1024 + c0 + 4);
;         const f32x4 w2a = *(const f32x4*)(conv_w + 2048 + c0), w2b = *(const f32x4*)(conv_w + 2048 + c0 + 4);
.LBB0_760:
	s_mov_b64 s[14:15], 0x80
	s_add_i32 m0, s37, 0x18000
	v_lshl_add_u64 v[8:9], v[8:9], 0, s[14:15]
	s_waitcnt vmcnt(2)
	s_barrier
	global_load_lds_dwordx4 v[8:9], off
	v_lshl_add_u64 v[4:5], v[4:5], 0, s[14:15]
	s_add_i32 m0, s37, 0x1a000
	s_add_i32 s42, s37, 0x8000
	global_load_lds_dwordx4 v[4:5], off
	v_lshl_add_u64 v[4:5], v[6:7], 0, s[14:15]
	s_mov_b32 m0, s42
	s_add_i32 s43, s37, 0xa000
	global_load_lds_dwordx4 v[4:5], off
	v_lshl_add_u64 v[4:5], v[10:11], 0, s[14:15]
	s_mov_b32 m0, s43
	v_lshl_add_u64 v[2:3], v[2:3], 0, s[14:15]
	global_load_lds_dwordx4 v[4:5], off
	s_add_i32 m0, s37, 0x1c000
	v_lshl_add_u64 v[0:1], v[0:1], 0, s[14:15]
	global_load_lds_dwordx4 v[2:3], off
	s_add_i32 m0, s37, 0x1e000
	s_lshr_b32 s1, s1, 26
	global_load_lds_dwordx4 v[0:1], off
	s_add_i32 s1, s0, s1
	v_lshlrev_b32_e32 v1, 2, v201
	s_ashr_i32 s44, s1, 6
	v_lshl_or_b32 v0, v201, 6, v238
	s_lshl_b32 s1, s2, 13
	v_and_b32_e32 v1, 32, v1
	v_bitop3_b32 v2, v0, s1, v1 bitop3:0xde
	s_lshl_b32 s1, s3, 5
	s_lshl_b32 s45, s2, 6
	s_and_b32 s46, s1, 0x60
	s_cmp_gt_i32 s0, 63
	s_cselect_b64 s[16:17], -1, 0
	s_add_i32 s47, s44, -2
	s_cmpk_lt_u32 s18, 0x100
	s_cselect_b64 s[18:19], -1, 0
	s_add_u32 s20, s90, 0x9000000
	v_add_u32_e32 v0, v237, v235
	s_addc_u32 s21, s91, 0
	v_mul_lo_u32 v0, s0, v0
	s_add_u32 s22, s90, 0xd000000
	v_readlane_b32 s48, v254, 23
	v_lshlrev_b32_e32 v0, 1, v0
	s_addc_u32 s23, s91, 0
	v_readlane_b32 s62, v254, 37
	v_add3_u32 v0, v233, v0, v234
	v_mov_b32_e32 v1, v205
	v_readlane_b32 s63, v254, 38
	s_add_u32 s24, s62, 0x1000
	v_lshl_add_u64 v[210:211], s[4:5], 0, v[0:1]
	v_add_u32_e32 v0, v236, v235
	s_addc_u32 s25, s63, 0
	v_mul_lo_u32 v0, s0, v0
	s_waitcnt vmcnt(6)
	v_readlane_b32 s50, v254, 25
	v_readlane_b32 s51, v254, 26
	s_add_u32 s26, s62, 0x2000
	v_lshlrev_b32_e32 v0, 1, v0
	v_lshl_or_b32 v245, s46, 7, v239
	v_readlane_b32 s49, v254, 24
	s_addc_u32 s27, s63, 0
	v_add3_u32 v0, v233, v0, v234
	s_add_i32 s50, 0, 0x10000
	s_add_i32 s51, 0, 0x14000
	v_readlane_b32 s52, v254, 27
	v_readlane_b32 s53, v254, 28
	s_ashr_i32 s48, s83, 31
	s_ashr_i32 s49, s80, 31
	v_lshl_add_u64 v[212:213], s[4:5], 0, v[0:1]
	v_mov_b64_e32 v[214:215], 0x400
	v_mov_b64_e32 v[216:217], 0x3ff
	v_add_u32_e32 v246, s50, v245
	v_add_u32_e32 v247, s51, v245
	v_add_u32_e32 v248, 0, v2
	s_barrier
	v_readlane_b32 s54, v254, 29
	v_readlane_b32 s55, v254, 30
	v_readlane_b32 s56, v254, 31
	v_readlane_b32 s57, v254, 32
	v_readlane_b32 s58, v254, 33
	v_readlane_b32 s59, v254, 34
	v_readlane_b32 s60, v254, 35
	v_readlane_b32 s61, v254, 36
	s_mov_b32 s101, 0
	s_mov_b32 s99, 0
	s_branch .LBB0_763

; #define PG8_STAGE(bufoff, gbase, voff) do { _Pragma("unroll") for (int _i = 0; _i < 2; ++_i) \
;         __builtin_amdgcn_global_load_lds((const unsigned*)((const char*)(gbase) + (voff)[_i]), (PG8_LAS unsigned*)(lds + (bufoff) + ldsw + _i * 8192), 16, 0, 0); } while (0)
; #define PG8_LDA(dst, b, h) do { _Pragma("unroll") for (int m = 0; m < 4; ++m) _Pragma("unroll") for (int k = 0; k < 2; ++k) dst[m][k] = *(const PG8_LAS bf16x8*)(lds + PG8_SA(b, h) + aoff + m * 2048 + k * 1024); } while (0)
; #define PG8_LDB(dst, b, h) do { _Pragma("unroll") for (int n = 0; n < 2; ++n) _Pragma("unroll") for (int k = 0; k < 2; ++k) dst[n][k] = *(const PG8_LAS bf16x8*)(lds + PG8_SB(b, h) + boff + n * 2048 + k * 1024); } while (0)
; #define PG8_SCHED __builtin_amdgcn_sched_barrier(0)
; template <class Epi, class Sched, bool ALIGN_EPI = false, bool SP2 = false>
; __device__ __forceinline__ void gemm_phase(PG8_LAS unsigned char* lds, const Gemm g, const Sched& S, const Epi& E) {
;     ...
;             const bool last = (t == nt - 2);
;             const char* a1 = cA + (size_t)(t + 1) * kstep;
;             const char* a2 = last ? nA : cA + (size_t)(t + 2) * kstep; const char* b2 = last ? nB : cB + (size_t)(t + 2) * kstep;
;             const char* a3 = a2 + kstep; const char* b3 = b2 + kstep;
;             if (last && has_next) S.a_ready(nxt);
;             if constexpr (SP2) {
;             PG8_LDB(B0, 0, 0); PG8_LDB(B1, 0, 1); PG8_SCHED; PG8_LDA(At, 0, 0); PG8_STAGE(PG8_SA(1, 1), a1 + hstep, voffA);
.LBB0_773:
	s_andn2_b64 vcc, exec, s[16:17]
	s_cbranch_vccnz .LBB0_776
	s_add_u32 s10, s10, 0x80
	s_addc_u32 s11, s11, 0
	s_add_u32 s55, s30, 0x100
	s_addc_u32 s56, s31, 0
	s_mov_b32 s30, 0
	ds_read_b128 v[80:83], v246
	ds_read_b128 v[84:87], v246 offset:1024
	ds_read_b128 v[88:91], v246 offset:2048
	ds_read_b128 v[92:95], v246 offset:3072
	ds_read_b128 v[96:99], v247
	ds_read_b128 v[100:103], v247 offset:1024
	ds_read_b128 v[152:155], v247 offset:2048
	ds_read_b128 v[156:159], v247 offset:3072
	s_add_i32 s57, s30, 2
	s_add_u32 s58, s10, 0x80
	s_addc_u32 s31, s11, 0
	s_cmp_eq_u32 s47, s30
	s_cselect_b32 s30, s0, s58
	s_cselect_b32 s31, s1, s31
	s_cselect_b32 s59, s29, s56
	s_cselect_b32 s58, s28, s55
	v_lshl_add_u64 v[192:193], s[10:11], 0, v[210:211]
	s_add_i32 m0, s37, 0xc000
	ds_read_b128 v[160:163], v248
	ds_read_b128 v[164:167], v248 offset:1024
	ds_read_b128 v[168:171], v248 offset:2048
	ds_read_b128 v[172:175], v248 offset:3072
	ds_read_b128 v[176:179], v248 offset:4096
	ds_read_b128 v[180:183], v248 offset:5120
	ds_read_b128 v[184:187], v248 offset:6144
	ds_read_b128 v[188:191], v248 offset:7168
	s_cmp_lg_u32 s101, 0
	s_cbranch_scc1 .Ly1_skip_2
	global_load_lds_dwordx4 v[192:193], off
	v_lshl_add_u64 v[192:193], s[10:11], 0, v[212:213]
	s_add_i32 m0, s37, 0xe000
	s_nop 0
	global_load_lds_dwordx4 v[192:193], off

; #define PG8_STAGE(bufoff, gbase, voff) do { _Pragma("unroll") for (int _i = 0; _i < 2; ++_i) \
;         __builtin_amdgcn_global_load_lds((const unsigned*)((const char*)(gbase) + (voff)[_i]), (PG8_LAS unsigned*)(lds + (bufoff) + ldsw + _i * 8192), 16, 0, 0); } while (0)
; #define PG8_LDA(dst, b, h) do { _Pragma("unroll") for (int m = 0; m < 4; ++m) _Pragma("unroll") for (int k = 0; k < 2; ++k) dst[m][k] = *(const PG8_LAS bf16x8*)(lds + PG8_SA(b, h) + aoff + m * 2048 + k * 1024); } while (0)
; #define PG8_LDB(dst, b, h) do { _Pragma("unroll") for (int n = 0; n < 2; ++n) _Pragma("unroll") for (int k = 0; k < 2; ++k) dst[n][k] = *(const PG8_LAS bf16x8*)(lds + PG8_SB(b, h) + boff + n * 2048 + k * 1024); } while (0)
; #define PG8_MMA(ai, bj, At, Bt) do { __builtin_amdgcn_s_setprio(1); _Pragma("unroll") for (int m = 0; m < 4; ++m) _Pragma("unroll") for (int n = 0; n < 2; ++n) _Pragma("unroll") for (int k = 0; k < 2; ++k) \
;         acc[ai][bj][m][n] = __builtin_amdgcn_mfma_f32_16x16x32_bf16(Bt[n][k], At[m][k], acc[ai][bj][m][n], 0, 0, 0); __builtin_amdgcn_s_setprio(0); } while (0)
; #define PG8_WAIT_V(n) asm volatile("s_waitcnt vmcnt(" #n ")" ::: "memory")
; #define PG8_WAIT_L(n) asm volatile("s_waitcnt lgkmcnt(" #n ")" ::: "memory")
; #define PG8_BAR __builtin_amdgcn_s_barrier()
; #define PG8_SCHED __builtin_amdgcn_sched_barrier(0)
; template <class Epi, class Sched, bool ALIGN_EPI = false, bool SP2 = false>
; __device__ __forceinline__ void gemm_phase(PG8_LAS unsigned char* lds, const Gemm g, const Sched& S, const Epi& E) {
;     ...
;             PG8_WAIT_V(8); PG8_WAIT_L(0); PG8_BAR; PG8_MMA(0, 0, At, B0); PG8_MMA(0, 1, At, B1); PG8_BAR; PG8_SCHED;
;             PG8_LDA(At, 0, 1); PG8_STAGE(PG8_SB(0, 0), b2, voffB); PG8_STAGE(PG8_SB(0, 1), b2 + hstep, voffB); PG8_STAGE(PG8_SA(0, 0), a2, voffA);
;             PG8_WAIT_V(8); PG8_WAIT_L(0); PG8_BAR; PG8_MMA(1, 0, At, B0); PG8_MMA(1, 1, At, B1); PG8_BAR; PG8_SCHED;
;             PG8_LDB(B0, 1, 0); PG8_LDB(B1, 1, 1); PG8_SCHED; PG8_LDA(At, 1, 0); PG8_STAGE(PG8_SA(0, 1), a2 + hstep, voffA);
;             PG8_WAIT_V(8); PG8_WAIT_L(0); PG8_BAR; PG8_MMA(0, 0, At, B0); PG8_MMA(0, 1, At, B1); PG8_BAR; PG8_SCHED;
.Lwj_2_1:
	s_waitcnt lgkmcnt(0)
	s_barrier
	s_setprio 1
	s_waitcnt lgkmcnt(0)
	v_mfma_f32_16x16x32_bf16 v[56:59], v[80:83], v[160:163], 0
	v_mfma_f32_16x16x32_bf16 v[48:51], v[88:91], v[160:163], 0
	v_mfma_f32_16x16x32_bf16 v[40:43], v[80:83], v[168:171], 0
	v_mfma_f32_16x16x32_bf16 v[32:35], v[88:91], v[168:171], 0
	v_mfma_f32_16x16x32_bf16 v[24:27], v[80:83], v[176:179], 0
	v_mfma_f32_16x16x32_bf16 v[16:19], v[88:91], v[176:179], 0
	v_mfma_f32_16x16x32_bf16 v[8:11], v[80:83], v[184:187], 0
	v_mfma_f32_16x16x32_bf16 v[0:3], v[88:91], v[184:187], 0
	v_mfma_f32_16x16x32_bf16 v[56:59], v[84:87], v[164:167], v[56:59]
	v_mfma_f32_16x16x32_bf16 v[48:51], v[92:95], v[164:167], v[48:51]
	v_mfma_f32_16x16x32_bf16 v[40:43], v[84:87], v[172:175], v[40:43]
	v_mfma_f32_16x16x32_bf16 v[32:35], v[92:95], v[172:175], v[32:35]
	v_mfma_f32_16x16x32_bf16 v[24:27], v[84:87], v[180:183], v[24:27]
	v_mfma_f32_16x16x32_bf16 v[16:19], v[92:95], v[180:183], v[16:19]
	v_mfma_f32_16x16x32_bf16 v[8:11], v[84:87], v[188:191], v[8:11]
	v_mfma_f32_16x16x32_bf16 v[0:3], v[92:95], v[188:191], v[0:3]
	s_setprio 0
	s_setprio 1
	v_mfma_f32_16x16x32_bf16 v[60:63], v[96:99], v[160:163], 0
	v_mfma_f32_16x16x32_bf16 v[52:55], v[152:155], v[160:163], 0
	v_mfma_f32_16x16x32_bf16 v[44:47], v[96:99], v[168:171], 0
	v_mfma_f32_16x16x32_bf16 v[36:39], v[152:155], v[168:171], 0
	v_mfma_f32_16x16x32_bf16 v[28:31], v[96:99], v[176:179], 0
	v_mfma_f32_16x16x32_bf16 v[20:23], v[152:155], v[176:179], 0
	v_mfma_f32_16x16x32_bf16 v[12:15], v[96:99], v[184:187], 0
	v_mfma_f32_16x16x32_bf16 v[4:7], v[152:155], v[184:187], 0
	v_mfma_f32_16x16x32_bf16 v[60:63], v[100:103], v[164:167], v[60:63]
	v_mfma_f32_16x16x32_bf16 v[52:55], v[156:159], v[164:167], v[52:55]
	v_mfma_f32_16x16x32_bf16 v[44:47], v[100:103], v[172:175], v[44:47]
	v_mfma_f32_16x16x32_bf16 v[36:39], v[156:159], v[172:175], v[36:39]
	v_mfma_f32_16x16x32_bf16 v[28:31], v[100:103], v[180:183], v[28:31]
	v_mfma_f32_16x16x32_bf16 v[20:23], v[156:159], v[180:183], v[20:23]
	v_mfma_f32_16x16x32_bf16 v[12:15], v[100:103], v[188:191], v[12:15]
	v_mfma_f32_16x16x32_bf16 v[4:7], v[156:159], v[188:191], v[4:7]
	s_setprio 0
	s_barrier
	s_add_i32 s58, 0, 0x18000
	s_add_i32 s59, 0, 0x1c000
	v_add_u32_e32 v92, s58, v245
	v_add_u32_e32 v156, s59, v245
	ds_read_b128 v[80:83], v92
	ds_read_b128 v[84:87], v92 offset:1024
	ds_read_b128 v[88:91], v92 offset:2048
	ds_read_b128 v[92:95], v92 offset:3072
	ds_read_b128 v[96:99], v156
	ds_read_b128 v[100:103], v156 offset:1024
	ds_read_b128 v[152:155], v156 offset:2048
	ds_read_b128 v[156:159], v156 offset:3072
	s_add_u32 s30, s30, s4
	s_addc_u32 s31, s31, s5
	s_mov_b32 m0, s39
	v_lshl_add_u64 v[222:223], s[30:31], 0, v[202:203]
	ds_read_b128 v[160:163], v248 offset:32768
	ds_read_b128 v[164:167], v248 offset:33792
	ds_read_b128 v[168:171], v248 offset:34816
	ds_read_b128 v[172:175], v248 offset:35840
	ds_read_b128 v[176:179], v248 offset:36864
	ds_read_b128 v[180:183], v248 offset:37888
	ds_read_b128 v[184:187], v248 offset:38912
	ds_read_b128 v[188:191], v248 offset:39936
	global_load_lds_dwordx4 v[222:223], off
	v_lshl_add_u64 v[222:223], s[30:31], 0, v[206:207]
	s_mov_b32 m0, s40
	s_nop 0
	global_load_lds_dwordx4 v[222:223], off
	s_cmp_eq_u32 s99, 0
	s_cbranch_scc1 .Lw8_2_2
	s_waitcnt vmcnt(16)
	s_branch .Lwj_2_2

; #define PG8_STAGE(bufoff, gbase, voff) do { _Pragma("unroll") for (int _i = 0; _i < 2; ++_i) \
;         __builtin_amdgcn_global_load_lds((const unsigned*)((const char*)(gbase) + (voff)[_i]), (PG8_LAS unsigned*)(lds + (bufoff) + ldsw + _i * 8192), 16, 0, 0); } while (0)
; #define PG8_LDA(dst, b, h) do { _Pragma("unroll") for (int m = 0; m < 4; ++m) _Pragma("unroll") for (int k = 0; k < 2; ++k) dst[m][k] = *(const PG8_LAS bf16x8*)(lds + PG8_SA(b, h) + aoff + m * 2048 + k * 1024); } while (0)
; #define PG8_LDB(dst, b, h) do { _Pragma("unroll") for (int n = 0; n < 2; ++n) _Pragma("unroll") for (int k = 0; k < 2; ++k) dst[n][k] = *(const PG8_LAS bf16x8*)(lds + PG8_SB(b, h) + boff + n * 2048 + k * 1024); } while (0)
; #define PG8_MMA(ai, bj, At, Bt) do { __builtin_amdgcn_s_setprio(1); _Pragma("unroll") for (int m = 0; m < 4; ++m) _Pragma("unroll") for (int n = 0; n < 2; ++n) _Pragma("unroll") for (int k = 0; k < 2; ++k) \
;         acc[ai][bj][m][n] = __builtin_amdgcn_mfma_f32_16x16x32_bf16(Bt[n][k], At[m][k], acc[ai][bj][m][n], 0, 0, 0); __builtin_amdgcn_s_setprio(0); } while (0)
; #define PG8_WAIT_V(n) asm volatile("s_waitcnt vmcnt(" #n ")" ::: "memory")
; #define PG8_WAIT_L(n) asm volatile("s_waitcnt lgkmcnt(" #n ")" ::: "memory")
; #define PG8_BAR __builtin_amdgcn_s_barrier()
; #define PG8_SCHED __builtin_amdgcn_sched_barrier(0)
; template <class Epi, class Sched, bool ALIGN_EPI = false, bool SP2 = false>
; __device__ __forceinline__ void gemm_phase(PG8_LAS unsigned char* lds, const Gemm g, const Sched& S, const Epi& E) {
;     ...
;             PG8_WAIT_V(8); PG8_WAIT_L(0); PG8_BAR; PG8_MMA(1, 0, At, B0); PG8_MMA(1, 1, At, B1); PG8_BAR; PG8_SCHED;
;             PG8_LDB(B0, 1, 0); PG8_LDB(B1, 1, 1); PG8_SCHED; PG8_LDA(At, 1, 0); PG8_STAGE(PG8_SA(0, 1), a2 + hstep, voffA);
;             PG8_WAIT_V(8); PG8_WAIT_L(0); PG8_BAR; PG8_MMA(0, 0, At, B0); PG8_MMA(0, 1, At, B1); PG8_BAR; PG8_SCHED;
;             PG8_LDA(At, 1, 1); PG8_STAGE(PG8_SB(1, 0), b3, voffB); PG8_STAGE(PG8_SB(1, 1), b3 + hstep, voffB); PG8_STAGE(PG8_SA(1, 0), a3, voffA);
;             PG8_WAIT_V(8); PG8_WAIT_L(0); PG8_BAR; PG8_MMA(1, 0, At, B0); PG8_MMA(1, 1, At, B1); PG8_BAR; PG8_SCHED;
.Lwj_2_2:
	s_waitcnt lgkmcnt(0)
	s_barrier
	s_setprio 1
	s_waitcnt lgkmcnt(0)
	v_mfma_f32_16x16x32_bf16 v[144:147], v[80:83], v[160:163], v[144:147]
	v_mfma_f32_16x16x32_bf16 v[136:139], v[88:91], v[160:163], v[136:139]
	v_mfma_f32_16x16x32_bf16 v[128:131], v[80:83], v[168:171], v[128:131]
	v_mfma_f32_16x16x32_bf16 v[120:123], v[88:91], v[168:171], v[120:123]
	v_mfma_f32_16x16x32_bf16 v[112:115], v[80:83], v[176:179], v[112:115]
	v_mfma_f32_16x16x32_bf16 v[104:107], v[88:91], v[176:179], v[104:107]
	v_mfma_f32_16x16x32_bf16 v[72:75], v[80:83], v[184:187], v[72:75]
	v_mfma_f32_16x16x32_bf16 v[64:67], v[88:91], v[184:187], v[64:67]
	v_mfma_f32_16x16x32_bf16 v[144:147], v[84:87], v[164:167], v[144:147]
	v_mfma_f32_16x16x32_bf16 v[136:139], v[92:95], v[164:167], v[136:139]
	v_mfma_f32_16x16x32_bf16 v[128:131], v[84:87], v[172:175], v[128:131]
	v_mfma_f32_16x16x32_bf16 v[120:123], v[92:95], v[172:175], v[120:123]
	v_mfma_f32_16x16x32_bf16 v[112:115], v[84:87], v[180:183], v[112:115]
	v_mfma_f32_16x16x32_bf16 v[104:107], v[92:95], v[180:183], v[104:107]
	v_mfma_f32_16x16x32_bf16 v[72:75], v[84:87], v[188:191], v[72:75]
	v_mfma_f32_16x16x32_bf16 v[64:67], v[92:95], v[188:191], v[64:67]
	s_setprio 0
	s_setprio 1
	v_mfma_f32_16x16x32_bf16 v[148:151], v[96:99], v[160:163], v[148:151]
	v_mfma_f32_16x16x32_bf16 v[140:143], v[152:155], v[160:163], v[140:143]
	v_mfma_f32_16x16x32_bf16 v[132:135], v[96:99], v[168:171], v[132:135]
	v_mfma_f32_16x16x32_bf16 v[124:127], v[152:155], v[168:171], v[124:127]
	v_mfma_f32_16x16x32_bf16 v[116:119], v[96:99], v[176:179], v[116:119]
	v_mfma_f32_16x16x32_bf16 v[108:111], v[152:155], v[176:179], v[108:111]
	v_mfma_f32_16x16x32_bf16 v[76:79], v[96:99], v[184:187], v[76:79]
	v_mfma_f32_16x16x32_bf16 v[68:71], v[152:155], v[184:187], v[68:71]
	v_mfma_f32_16x16x32_bf16 v[148:151], v[100:103], v[164:167], v[148:151]
	v_mfma_f32_16x16x32_bf16 v[140:143], v[156:159], v[164:167], v[140:143]
	v_mfma_f32_16x16x32_bf16 v[132:135], v[100:103], v[172:175], v[132:135]
	v_mfma_f32_16x16x32_bf16 v[124:127], v[156:159], v[172:175], v[124:127]
	v_mfma_f32_16x16x32_bf16 v[116:119], v[100:103], v[180:183], v[116:119]
	v_mfma_f32_16x16x32_bf16 v[108:111], v[156:159], v[180:183], v[108:111]
	v_mfma_f32_16x16x32_bf16 v[76:79], v[100:103], v[188:191], v[76:79]
	v_mfma_f32_16x16x32_bf16 v[68:71], v[156:159], v[188:191], v[68:71]
	s_setprio 0
	s_barrier
	s_add_i32 s30, s58, s36
	v_lshl_add_u64 v[192:193], v[192:193], 0, s[14:15]
	s_mov_b32 m0, s30
	ds_read_b128 v[160:163], v248 offset:49152
	ds_read_b128 v[164:167], v248 offset:50176
	ds_read_b128 v[168:171], v248 offset:51200
	ds_read_b128 v[172:175], v248 offset:52224
	ds_read_b128 v[176:179], v248 offset:53248
	ds_read_b128 v[180:183], v248 offset:54272
	ds_read_b128 v[184:187], v248 offset:55296
	ds_read_b128 v[188:191], v248 offset:56320
	global_load_lds_dwordx4 v[192:193], off
	v_lshl_add_u64 v[192:193], v[194:195], 0, s[14:15]
	s_add_i32 m0, s30, 0x2000
	s_add_i32 s30, s59, s36
	global_load_lds_dwordx4 v[192:193], off
	v_lshl_add_u64 v[192:193], v[196:197], 0, s[14:15]
	s_mov_b32 m0, s30
	s_nop 0
	global_load_lds_dwordx4 v[192:193], off
	v_lshl_add_u64 v[192:193], v[198:199], 0, s[14:15]
	s_add_i32 m0, s30, 0x2000
	s_nop 0
	global_load_lds_dwordx4 v[192:193], off
	v_lshl_add_u64 v[192:193], v[218:219], 0, s[14:15]
	s_mov_b32 m0, s42
	s_nop 0
	global_load_lds_dwordx4 v[192:193], off
	v_lshl_add_u64 v[192:193], v[220:221], 0, s[14:15]
	s_mov_b32 m0, s43
	s_nop 0
	global_load_lds_dwordx4 v[192:193], off
	s_waitcnt vmcnt(8)
	s_waitcnt lgkmcnt(0)
	s_barrier
	s_setprio 1
	s_waitcnt lgkmcnt(0)
	v_mfma_f32_16x16x32_bf16 v[56:59], v[80:83], v[160:163], v[56:59]
	v_mfma_f32_16x16x32_bf16 v[48:51], v[88:91], v[160:163], v[48:51]
	v_mfma_f32_16x16x32_bf16 v[40:43], v[80:83], v[168:171], v[40:43]
	v_mfma_f32_16x16x32_bf16 v[32:35], v[88:91], v[168:171], v[32:35]
	v_mfma_f32_16x16x32_bf16 v[24:27], v[80:83], v[176:179], v[24:27]
	v_mfma_f32_16x16x32_bf16 v[16:19], v[88:91], v[176:179], v[16:19]
	v_mfma_f32_16x16x32_bf16 v[8:11], v[80:83], v[184:187], v[8:11]
	v_mfma_f32_16x16x32_bf16 v[0:3], v[88:91], v[184:187], v[0:3]
	v_mfma_f32_16x16x32_bf16 v[56:59], v[84:87], v[164:167], v[56:59]
	v_mfma_f32_16x16x32_bf16 v[48:51], v[92:95], v[164:167], v[48:51]
	v_mfma_f32_16x16x32_bf16 v[40:43], v[84:87], v[172:175], v[40:43]
	v_mfma_f32_16x16x32_bf16 v[32:35], v[92:95], v[172:175], v[32:35]
	v_mfma_f32_16x16x32_bf16 v[24:27], v[84:87], v[180:183], v[24:27]
	v_mfma_f32_16x16x32_bf16 v[16:19], v[92:95], v[180:183], v[16:19]
	v_mfma_f32_16x16x32_bf16 v[8:11], v[84:87], v[188:191], v[8:11]
	v_mfma_f32_16x16x32_bf16 v[0:3], v[92:95], v[188:191], v[0:3]
	s_setprio 0
	s_setprio 1
	v_mfma_f32_16x16x32_bf16 v[60:63], v[96:99], v[160:163], v[60:63]
	v_mfma_f32_16x16x32_bf16 v[52:55], v[152:155], v[160:163], v[52:55]
	v_mfma_f32_16x16x32_bf16 v[44:47], v[96:99], v[168:171], v[44:47]
	v_mfma_f32_16x16x32_bf16 v[36:39], v[152:155], v[168:171], v[36:39]
	v_mfma_f32_16x16x32_bf16 v[28:31], v[96:99], v[176:179], v[28:31]
	v_mfma_f32_16x16x32_bf16 v[20:23], v[152:155], v[176:179], v[20:23]
	v_mfma_f32_16x16x32_bf16 v[12:15], v[96:99], v[184:187], v[12:15]
	v_mfma_f32_16x16x32_bf16 v[4:7], v[152:155], v[184:187], v[4:7]
	v_mfma_f32_16x16x32_bf16 v[60:63], v[100:103], v[164:167], v[60:63]
	v_mfma_f32_16x16x32_bf16 v[52:55], v[156:159], v[164:167], v[52:55]
	v_mfma_f32_16x16x32_bf16 v[44:47], v[100:103], v[172:175], v[44:47]
	v_mfma_f32_16x16x32_bf16 v[36:39], v[156:159], v[172:175], v[36:39]
	v_mfma_f32_16x16x32_bf16 v[28:31], v[100:103], v[180:183], v[28:31]
	v_mfma_f32_16x16x32_bf16 v[20:23], v[156:159], v[180:183], v[20:23]
	v_mfma_f32_16x16x32_bf16 v[12:15], v[100:103], v[188:191], v[12:15]
	v_mfma_f32_16x16x32_bf16 v[4:7], v[156:159], v[188:191], v[4:7]
	s_setprio 0
	s_barrier
	s_add_u32 s10, s10, 0x100
	s_addc_u32 s11, s11, 0
	s_add_u32 s55, s55, 0x100
	s_addc_u32 s56, s56, 0
	s_cmp_ge_i32 s57, s44
	s_mov_b32 s30, s57
	s_cbranch_scc1 .LBB0_776

;     __device__ __forceinline__ void operator()(const AccT& acc, const Unit& u, int wr, int wc, int fr_, int fq_) const {
;         int fr = fr_, fq = fq_; asm volatile("" : "+v"(fr), "+v"(fq));
;         const int c0 = u.pn * 128 + wc * 32 + 8 * fq;
;         const bf16_t* const U = (const bf16_t*)(ws + WS_RB); bf16_t* const A2 = (bf16_t*)(ws + WS_A2);
;         const f32x4 w0a = *(const f32x4*)(conv_w + c0), w0b = *(const f32x4*)(conv_w + c0 + 4);
;         const f32x4 w1a = *(const f32x4*)(conv_w + 1024 + c0), w1b = *(const f32x4*)(conv_w + 1024 + c0 + 4);
;         const f32x4 w2a = *(const f32x4*)(conv_w + 2048 + c0), w2b = *(const f32x4*)(conv_w + 2048 + c0 + 4);
; #pragma unroll
;         for (int ai = 0; ai < 2; ++ai) {
;             u32x4 uu[4][3];
; #pragma unroll
;             for (int m = 0; m < 4; ++m) { const size_t row = (size_t)ROW_OF(ai, m); const int s = (int)(row & 2047); const u32x4 z4 = {0u, 0u, 0u, 0u};
;                 uu[m][2] = *(const u32x4*)(U + row * 1024 + c0);
;                 uu[m][1] = s >= 1 ? *(const u32x4*)(U + (row - 1) * 1024 + c0) : z4;
;                 uu[m][0] = s >= 2 ? *(const u32x4*)(U + (row - 2) * 1024 + c0) : z4; }
.LBB0_778:
	s_mov_b32 s99, 1
	v_lshl_add_u64 v[192:193], s[0:1], 0, v[210:211]
	v_lshl_add_u64 v[192:193], v[192:193], 0, 64
	v_lshl_add_u64 v[192:193], v[192:193], 0, 64
	s_add_i32 m0, s37, 0xc000
	s_mov_b32 s101, 1
	global_load_lds_dwordx4 v[192:193], off
	v_lshl_add_u64 v[192:193], s[0:1], 0, v[212:213]
	v_lshl_add_u64 v[192:193], v[192:193], 0, 64
	v_lshl_add_u64 v[192:193], v[192:193], 0, 64
	s_add_i32 m0, s37, 0xe000
	s_nop 0
	global_load_lds_dwordx4 v[192:193], off
	s_lshl_b32 s10, s64, 7
	v_mov_b32_e32 v152, v201
	v_mov_b32_e32 v80, v232
	s_or_b32 s10, s10, s46
	v_readlane_b32 s56, v254, 23
	v_lshl_add_u32 v220, v80, 3, s10
	s_lshl_b32 s10, s33, 8
	s_add_i32 s10, s10, s45
	v_add_u32_e32 v222, s10, v152
	v_ashrrev_i32_e32 v221, 31, v220
	v_ashrrev_i32_e32 v223, 31, v222
	v_lshlrev_b64 v[80:81], 2, v[220:221]
	v_readlane_b32 s70, v254, 37
	v_readlane_b32 s71, v254, 38
	v_lshlrev_b64 v[152:153], 11, v[222:223]
	v_lshl_add_u64 v[152:153], s[20:21], 0, v[152:153]
	v_lshl_add_u64 v[82:83], s[70:71], 0, v[80:81]
	global_load_dwordx4 v[88:91], v[82:83], off offset:16
	global_load_dwordx4 v[100:103], v[82:83], off
	v_lshl_add_u64 v[82:83], s[24:25], 0, v[80:81]
	v_lshl_add_u64 v[92:93], s[26:27], 0, v[80:81]
	v_lshl_add_u64 v[152:153], v[220:221], 1, v[152:153]
	global_load_dwordx4 v[84:87], v[82:83], off offset:16
	global_load_dwordx4 v[96:99], v[82:83], off
	s_nop 0
	global_load_dwordx4 v[80:83], v[92:93], off offset:16
	s_nop 0
	global_load_dwordx4 v[92:95], v[92:93], off
	v_and_b32_e32 v154, 0x7ff, v222
	global_load_dwordx4 v[188:191], v[152:153], off
	v_mov_b32_e32 v196, 0
	v_cmp_ne_u32_e32 vcc, 0, v154
	v_mov_b32_e32 v192, 0
	v_mov_b32_e32 v193, 0
	v_mov_b32_e32 v194, 0
	v_mov_b32_e32 v195, 0
	v_readlane_b32 s57, v254, 24
	v_readlane_b32 s58, v254, 25
	v_readlane_b32 s59, v254, 26
	v_readlane_b32 s60, v254, 27
	v_readlane_b32 s61, v254, 28
	v_readlane_b32 s62, v254, 29
	v_readlane_b32 s63, v254, 30
	v_readlane_b32 s64, v254, 31
	v_readlane_b32 s65, v254, 32
	v_readlane_b32 s66, v254, 33
	v_readlane_b32 s67, v254, 34
	v_readlane_b32 s68, v254, 35
	v_readlane_b32 s69, v254, 36
	s_and_saveexec_b64 s[10:11], vcc
	s_cbranch_execz .LBB0_780
	global_load_dwordx4 v[192:195], v[152:153], off offset:-2048

; #define PG8_STAGE(bufoff, gbase, voff) do { _Pragma("unroll") for (int _i = 0; _i < 2; ++_i) \
;         __builtin_amdgcn_global_load_lds((const unsigned*)((const char*)(gbase) + (voff)[_i]), (PG8_LAS unsigned*)(lds + (bufoff) + ldsw + _i * 8192), 16, 0, 0); } while (0)
; #define PG8_WAIT_V(n) asm volatile("s_waitcnt vmcnt(" #n ")" ::: "memory")
; #define PG8_BAR __builtin_amdgcn_s_barrier()
; template <class Epi, class Sched, bool ALIGN_EPI = false, bool SP2 = false>
; __device__ __forceinline__ void gemm_phase(PG8_LAS unsigned char* lds, const Gemm g, const Sched& S, const Epi& E) {
;     ...
;     if constexpr (SP2) {
;         PG8_STAGE(PG8_SB(0, 0), cB, voffB); PG8_STAGE(PG8_SB(0, 1), cB + hstep, voffB); PG8_STAGE(PG8_SA(0, 0), cA, voffA); PG8_STAGE(PG8_SA(0, 1), cA + hstep, voffA);
;         if (wr == 1) PG8_BAR;
;         PG8_WAIT_V(2); PG8_BAR;
;         PG8_STAGE(PG8_SB(1, 0), cB + kstep, voffB); PG8_STAGE(PG8_SA(1, 0), cA + kstep, voffA); PG8_STAGE(PG8_SB(1, 1), cB + hstep + kstep, voffB);
;         PG8_WAIT_V(6); PG8_BAR;
;     } else {
;     __device__ __forceinline__ void operator()(const AccT& acc, const Unit& u, int wr, int wc, int fr_, int fq_) const {
;     ...
;         const int c0 = u.pn * 128 + wc * 32 + 8 * fq;
;         const bf16_t* const U = (const bf16_t*)(ws + WS_RB); bf16_t* const A2 = (bf16_t*)(ws + WS_A2);
;         const f32x4 w0a = *(const f32x4*)(conv_w + c0), w0b = *(const f32x4*)(conv_w + c0 + 4);
;         const f32x4 w1a = *(const f32x4*)(conv_w + 1024 + c0), w1b = *(const f32x4*)(conv_w + 1024 + c0 + 4);
;         const f32x4 w2a = *(const f32x4*)(conv_w + 2048 + c0), w2b = *(const f32x4*)(conv_w + 2048 + c0 + 4);
.LBB0_825:
	s_mov_b64 s[16:17], 0x80
	s_add_i32 m0, s39, 0x18000
	v_lshl_add_u64 v[8:9], v[8:9], 0, s[16:17]
	s_waitcnt vmcnt(2)
	s_barrier
	global_load_lds_dwordx4 v[8:9], off
	v_lshl_add_u64 v[4:5], v[4:5], 0, s[16:17]
	s_add_i32 m0, s39, 0x1a000
	s_add_i32 s44, s39, 0x8000
	global_load_lds_dwordx4 v[4:5], off
	v_lshl_add_u64 v[4:5], v[6:7], 0, s[16:17]
	s_mov_b32 m0, s44
	s_add_i32 s45, s39, 0xa000
	global_load_lds_dwordx4 v[4:5], off
	v_lshl_add_u64 v[4:5], v[10:11], 0, s[16:17]
	s_mov_b32 m0, s45
	v_lshl_add_u64 v[2:3], v[2:3], 0, s[16:17]
	global_load_lds_dwordx4 v[4:5], off
	s_add_i32 m0, s39, 0x1c000
	v_lshl_add_u64 v[0:1], v[0:1], 0, s[16:17]
	global_load_lds_dwordx4 v[2:3], off
	s_add_i32 m0, s39, 0x1e000
	s_lshr_b32 s1, s1, 26
	global_load_lds_dwordx4 v[0:1], off
	s_add_i32 s1, s0, s1
	v_lshlrev_b32_e32 v1, 2, v201
	s_ashr_i32 s46, s1, 6
	v_lshl_or_b32 v0, v201, 6, v238
	s_lshl_b32 s1, s4, 13
	v_and_b32_e32 v1, 32, v1
	v_bitop3_b32 v2, v0, s1, v1 bitop3:0xde
	s_lshl_b32 s1, s5, 5
	s_lshl_b32 s47, s4, 6
	s_and_b32 s48, s1, 0x60
	s_cmp_gt_i32 s0, 63
	s_cselect_b64 s[18:19], -1, 0
	s_add_i32 s49, s46, -2
	s_cmpk_lt_u32 s20, 0x100
	s_cselect_b64 s[20:21], -1, 0
	s_add_u32 s22, s90, 0x9000000
	v_add_u32_e32 v0, v237, v235
	s_addc_u32 s23, s91, 0
	v_mul_lo_u32 v0, s0, v0
	s_add_u32 s24, s90, 0xd000000
	v_readlane_b32 s64, v254, 23
	v_lshlrev_b32_e32 v0, 1, v0
	s_addc_u32 s25, s91, 0
	v_readlane_b32 s78, v254, 37
	v_add3_u32 v0, v233, v0, v234
	v_mov_b32_e32 v1, v205
	v_readlane_b32 s79, v254, 38
	s_add_u32 s26, s78, 0x1000
	v_lshl_add_u64 v[210:211], s[6:7], 0, v[0:1]
	v_add_u32_e32 v0, v236, v235
	s_addc_u32 s27, s79, 0
	v_mul_lo_u32 v0, s0, v0
	s_waitcnt vmcnt(6)
	s_add_u32 s28, s78, 0x2000
	v_lshlrev_b32_e32 v0, 1, v0
	v_lshl_or_b32 v245, s48, 7, v239
	s_addc_u32 s29, s79, 0
	v_add3_u32 v0, v233, v0, v234
	s_add_i32 s52, 0, 0x10000
	s_add_i32 s53, 0, 0x14000
	s_ashr_i32 s50, s83, 31
	s_ashr_i32 s51, s80, 31
	v_lshl_add_u64 v[212:213], s[6:7], 0, v[0:1]
	v_mov_b64_e32 v[214:215], 0x400
	v_mov_b64_e32 v[216:217], 0x3ff
	v_add_u32_e32 v246, s52, v245
	v_add_u32_e32 v247, s53, v245
	v_add_u32_e32 v248, 0, v2
	s_barrier
	v_readlane_b32 s65, v254, 24
	v_readlane_b32 s66, v254, 25
	v_readlane_b32 s67, v254, 26
	v_readlane_b32 s68, v254, 27
	v_readlane_b32 s69, v254, 28
	v_readlane_b32 s70, v254, 29
	v_readlane_b32 s71, v254, 30
	v_readlane_b32 s72, v254, 31
	v_readlane_b32 s73, v254, 32
	v_readlane_b32 s74, v254, 33
	v_readlane_b32 s75, v254, 34
	v_readlane_b32 s76, v254, 35
	v_readlane_b32 s77, v254, 36
	s_mov_b32 s101, 0
	s_mov_b32 s99, 0
	s_branch .LBB0_828

; #define PG8_STAGE(bufoff, gbase, voff) do { _Pragma("unroll") for (int _i = 0; _i < 2; ++_i) \
;         __builtin_amdgcn_global_load_lds((const unsigned*)((const char*)(gbase) + (voff)[_i]), (PG8_LAS unsigned*)(lds + (bufoff) + ldsw + _i * 8192), 16, 0, 0); } while (0)
; #define PG8_LDA(dst, b, h) do { _Pragma("unroll") for (int m = 0; m < 4; ++m) _Pragma("unroll") for (int k = 0; k < 2; ++k) dst[m][k] = *(const PG8_LAS bf16x8*)(lds + PG8_SA(b, h) + aoff + m * 2048 + k * 1024); } while (0)
; #define PG8_LDB(dst, b, h) do { _Pragma("unroll") for (int n = 0; n < 2; ++n) _Pragma("unroll") for (int k = 0; k < 2; ++k) dst[n][k] = *(const PG8_LAS bf16x8*)(lds + PG8_SB(b, h) + boff + n * 2048 + k * 1024); } while (0)
; #define PG8_SCHED __builtin_amdgcn_sched_barrier(0)
; template <class Epi, class Sched, bool ALIGN_EPI = false, bool SP2 = false>
; __device__ __forceinline__ void gemm_phase(PG8_LAS unsigned char* lds, const Gemm g, const Sched& S, const Epi& E) {
;     ...
;             const bool last = (t == nt - 2);
;             const char* a1 = cA + (size_t)(t + 1) * kstep;
;             const char* a2 = last ? nA : cA + (size_t)(t + 2) * kstep; const char* b2 = last ? nB : cB + (size_t)(t + 2) * kstep;
;             const char* a3 = a2 + kstep; const char* b3 = b2 + kstep;
;             if (last && has_next) S.a_ready(nxt);
;             if constexpr (SP2) {
;             PG8_LDB(B0, 0, 0); PG8_LDB(B1, 0, 1); PG8_SCHED; PG8_LDA(At, 0, 0); PG8_STAGE(PG8_SA(1, 1), a1 + hstep, voffA);
.LBB0_838:
	s_andn2_b64 vcc, exec, s[18:19]
	s_cbranch_vccnz .LBB0_841
	s_add_u32 s10, s10, 0x80
	s_addc_u32 s11, s11, 0
	s_add_u32 s57, s34, 0x100
	s_addc_u32 s58, s35, 0
	s_mov_b32 s34, 0
	ds_read_b128 v[80:83], v246
	ds_read_b128 v[84:87], v246 offset:1024
	ds_read_b128 v[88:91], v246 offset:2048
	ds_read_b128 v[92:95], v246 offset:3072
	ds_read_b128 v[96:99], v247
	ds_read_b128 v[100:103], v247 offset:1024
	ds_read_b128 v[152:155], v247 offset:2048
	ds_read_b128 v[156:159], v247 offset:3072
	s_add_i32 s59, s34, 2
	s_add_u32 s60, s10, 0x80
	s_addc_u32 s35, s11, 0
	s_cmp_eq_u32 s49, s34
	s_cselect_b32 s34, s0, s60
	s_cselect_b32 s35, s1, s35
	s_cselect_b32 s61, s31, s58
	s_cselect_b32 s60, s30, s57
	v_lshl_add_u64 v[192:193], s[10:11], 0, v[210:211]
	s_add_i32 m0, s39, 0xc000
	ds_read_b128 v[160:163], v248
	ds_read_b128 v[164:167], v248 offset:1024
	ds_read_b128 v[168:171], v248 offset:2048
	ds_read_b128 v[172:175], v248 offset:3072
	ds_read_b128 v[176:179], v248 offset:4096
	ds_read_b128 v[180:183], v248 offset:5120
	ds_read_b128 v[184:187], v248 offset:6144
	ds_read_b128 v[188:191], v248 offset:7168
	s_cmp_lg_u32 s101, 0
	s_cbranch_scc1 .Ly1_skip_3
	global_load_lds_dwordx4 v[192:193], off
	v_lshl_add_u64 v[192:193], s[10:11], 0, v[212:213]
	s_add_i32 m0, s39, 0xe000
	s_nop 0
	global_load_lds_dwordx4 v[192:193], off

; #define PG8_STAGE(bufoff, gbase, voff) do { _Pragma("unroll") for (int _i = 0; _i < 2; ++_i) \
;         __builtin_amdgcn_global_load_lds((const unsigned*)((const char*)(gbase) + (voff)[_i]), (PG8_LAS unsigned*)(lds + (bufoff) + ldsw + _i * 8192), 16, 0, 0); } while (0)
; #define PG8_LDA(dst, b, h) do { _Pragma("unroll") for (int m = 0; m < 4; ++m) _Pragma("unroll") for (int k = 0; k < 2; ++k) dst[m][k] = *(const PG8_LAS bf16x8*)(lds + PG8_SA(b, h) + aoff + m * 2048 + k * 1024); } while (0)
; #define PG8_LDB(dst, b, h) do { _Pragma("unroll") for (int n = 0; n < 2; ++n) _Pragma("unroll") for (int k = 0; k < 2; ++k) dst[n][k] = *(const PG8_LAS bf16x8*)(lds + PG8_SB(b, h) + boff + n * 2048 + k * 1024); } while (0)
; #define PG8_MMA(ai, bj, At, Bt) do { __builtin_amdgcn_s_setprio(1); _Pragma("unroll") for (int m = 0; m < 4; ++m) _Pragma("unroll") for (int n = 0; n < 2; ++n) _Pragma("unroll") for (int k = 0; k < 2; ++k) \
;         acc[ai][bj][m][n] = __builtin_amdgcn_mfma_f32_16x16x32_bf16(Bt[n][k], At[m][k], acc[ai][bj][m][n], 0, 0, 0); __builtin_amdgcn_s_setprio(0); } while (0)
; #define PG8_WAIT_V(n) asm volatile("s_waitcnt vmcnt(" #n ")" ::: "memory")
; #define PG8_WAIT_L(n) asm volatile("s_waitcnt lgkmcnt(" #n ")" ::: "memory")
; #define PG8_BAR __builtin_amdgcn_s_barrier()
; #define PG8_SCHED __builtin_amdgcn_sched_barrier(0)
; template <class Epi, class Sched, bool ALIGN_EPI = false, bool SP2 = false>
; __device__ __forceinline__ void gemm_phase(PG8_LAS unsigned char* lds, const Gemm g, const Sched& S, const Epi& E) {
;     ...
;             PG8_WAIT_V(8); PG8_WAIT_L(0); PG8_BAR; PG8_MMA(0, 0, At, B0); PG8_MMA(0, 1, At, B1); PG8_BAR; PG8_SCHED;
;             PG8_LDA(At, 0, 1); PG8_STAGE(PG8_SB(0, 0), b2, voffB); PG8_STAGE(PG8_SB(0, 1), b2 + hstep, voffB); PG8_STAGE(PG8_SA(0, 0), a2, voffA);
;             PG8_WAIT_V(8); PG8_WAIT_L(0); PG8_BAR; PG8_MMA(1, 0, At, B0); PG8_MMA(1, 1, At, B1); PG8_BAR; PG8_SCHED;
;             PG8_LDB(B0, 1, 0); PG8_LDB(B1, 1, 1); PG8_SCHED; PG8_LDA(At, 1, 0); PG8_STAGE(PG8_SA(0, 1), a2 + hstep, voffA);
;             PG8_WAIT_V(8); PG8_WAIT_L(0); PG8_BAR; PG8_MMA(0, 0, At, B0); PG8_MMA(0, 1, At, B1); PG8_BAR; PG8_SCHED;
.Lwj_3_1:
	s_waitcnt lgkmcnt(0)
	s_barrier
	s_setprio 1
	s_waitcnt lgkmcnt(0)
	v_mfma_f32_16x16x32_bf16 v[56:59], v[80:83], v[160:163], 0
	v_mfma_f32_16x16x32_bf16 v[48:51], v[88:91], v[160:163], 0
	v_mfma_f32_16x16x32_bf16 v[40:43], v[80:83], v[168:171], 0
	v_mfma_f32_16x16x32_bf16 v[32:35], v[88:91], v[168:171], 0
	v_mfma_f32_16x16x32_bf16 v[24:27], v[80:83], v[176:179], 0
	v_mfma_f32_16x16x32_bf16 v[16:19], v[88:91], v[176:179], 0
	v_mfma_f32_16x16x32_bf16 v[8:11], v[80:83], v[184:187], 0
	v_mfma_f32_16x16x32_bf16 v[0:3], v[88:91], v[184:187], 0
	v_mfma_f32_16x16x32_bf16 v[56:59], v[84:87], v[164:167], v[56:59]
	v_mfma_f32_16x16x32_bf16 v[48:51], v[92:95], v[164:167], v[48:51]
	v_mfma_f32_16x16x32_bf16 v[40:43], v[84:87], v[172:175], v[40:43]
	v_mfma_f32_16x16x32_bf16 v[32:35], v[92:95], v[172:175], v[32:35]
	v_mfma_f32_16x16x32_bf16 v[24:27], v[84:87], v[180:183], v[24:27]
	v_mfma_f32_16x16x32_bf16 v[16:19], v[92:95], v[180:183], v[16:19]
	v_mfma_f32_16x16x32_bf16 v[8:11], v[84:87], v[188:191], v[8:11]
	v_mfma_f32_16x16x32_bf16 v[0:3], v[92:95], v[188:191], v[0:3]
	s_setprio 0
	s_setprio 1
	v_mfma_f32_16x16x32_bf16 v[60:63], v[96:99], v[160:163], 0
	v_mfma_f32_16x16x32_bf16 v[52:55], v[152:155], v[160:163], 0
	v_mfma_f32_16x16x32_bf16 v[44:47], v[96:99], v[168:171], 0
	v_mfma_f32_16x16x32_bf16 v[36:39], v[152:155], v[168:171], 0
	v_mfma_f32_16x16x32_bf16 v[28:31], v[96:99], v[176:179], 0
	v_mfma_f32_16x16x32_bf16 v[20:23], v[152:155], v[176:179], 0
	v_mfma_f32_16x16x32_bf16 v[12:15], v[96:99], v[184:187], 0
	v_mfma_f32_16x16x32_bf16 v[4:7], v[152:155], v[184:187], 0
	v_mfma_f32_16x16x32_bf16 v[60:63], v[100:103], v[164:167], v[60:63]
	v_mfma_f32_16x16x32_bf16 v[52:55], v[156:159], v[164:167], v[52:55]
	v_mfma_f32_16x16x32_bf16 v[44:47], v[100:103], v[172:175], v[44:47]
	v_mfma_f32_16x16x32_bf16 v[36:39], v[156:159], v[172:175], v[36:39]
	v_mfma_f32_16x16x32_bf16 v[28:31], v[100:103], v[180:183], v[28:31]
	v_mfma_f32_16x16x32_bf16 v[20:23], v[156:159], v[180:183], v[20:23]
	v_mfma_f32_16x16x32_bf16 v[12:15], v[100:103], v[188:191], v[12:15]
	v_mfma_f32_16x16x32_bf16 v[4:7], v[156:159], v[188:191], v[4:7]
	s_setprio 0
	s_barrier
	s_add_i32 s60, 0, 0x18000
	s_add_i32 s61, 0, 0x1c000
	v_add_u32_e32 v92, s60, v245
	v_add_u32_e32 v156, s61, v245
	ds_read_b128 v[80:83], v92
	ds_read_b128 v[84:87], v92 offset:1024
	ds_read_b128 v[88:91], v92 offset:2048
	ds_read_b128 v[92:95], v92 offset:3072
	ds_read_b128 v[96:99], v156
	ds_read_b128 v[100:103], v156 offset:1024
	ds_read_b128 v[152:155], v156 offset:2048
	ds_read_b128 v[156:159], v156 offset:3072
	s_add_u32 s34, s34, s6
	s_addc_u32 s35, s35, s7
	s_mov_b32 m0, s41
	v_lshl_add_u64 v[222:223], s[34:35], 0, v[202:203]
	ds_read_b128 v[160:163], v248 offset:32768
	ds_read_b128 v[164:167], v248 offset:33792
	ds_read_b128 v[168:171], v248 offset:34816
	ds_read_b128 v[172:175], v248 offset:35840
	ds_read_b128 v[176:179], v248 offset:36864
	ds_read_b128 v[180:183], v248 offset:37888
	ds_read_b128 v[184:187], v248 offset:38912
	ds_read_b128 v[188:191], v248 offset:39936
	global_load_lds_dwordx4 v[222:223], off
	v_lshl_add_u64 v[222:223], s[34:35], 0, v[206:207]
	s_mov_b32 m0, s42
	s_nop 0
	global_load_lds_dwordx4 v[222:223], off
	s_cmp_eq_u32 s99, 0
	s_cbranch_scc1 .Lw8_3_2
	s_waitcnt vmcnt(16)
	s_branch .Lwj_3_2

; #define PG8_STAGE(bufoff, gbase, voff) do { _Pragma("unroll") for (int _i = 0; _i < 2; ++_i) \
;         __builtin_amdgcn_global_load_lds((const unsigned*)((const char*)(gbase) + (voff)[_i]), (PG8_LAS unsigned*)(lds + (bufoff) + ldsw + _i * 8192), 16, 0, 0); } while (0)
; #define PG8_LDA(dst, b, h) do { _Pragma("unroll") for (int m = 0; m < 4; ++m) _Pragma("unroll") for (int k = 0; k < 2; ++k) dst[m][k] = *(const PG8_LAS bf16x8*)(lds + PG8_SA(b, h) + aoff + m * 2048 + k * 1024); } while (0)
; #define PG8_LDB(dst, b, h) do { _Pragma("unroll") for (int n = 0; n < 2; ++n) _Pragma("unroll") for (int k = 0; k < 2; ++k) dst[n][k] = *(const PG8_LAS bf16x8*)(lds + PG8_SB(b, h) + boff + n * 2048 + k * 1024); } while (0)
; #define PG8_MMA(ai, bj, At, Bt) do { __builtin_amdgcn_s_setprio(1); _Pragma("unroll") for (int m = 0; m < 4; ++m) _Pragma("unroll") for (int n = 0; n < 2; ++n) _Pragma("unroll") for (int k = 0; k < 2; ++k) \
;         acc[ai][bj][m][n] = __builtin_amdgcn_mfma_f32_16x16x32_bf16(Bt[n][k], At[m][k], acc[ai][bj][m][n], 0, 0, 0); __builtin_amdgcn_s_setprio(0); } while (0)
; #define PG8_WAIT_V(n) asm volatile("s_waitcnt vmcnt(" #n ")" ::: "memory")
; #define PG8_WAIT_L(n) asm volatile("s_waitcnt lgkmcnt(" #n ")" ::: "memory")
; #define PG8_BAR __builtin_amdgcn_s_barrier()
; #define PG8_SCHED __builtin_amdgcn_sched_barrier(0)
; template <class Epi, class Sched, bool ALIGN_EPI = false, bool SP2 = false>
; __device__ __forceinline__ void gemm_phase(PG8_LAS unsigned char* lds, const Gemm g, const Sched& S, const Epi& E) {
;     ...
;             PG8_WAIT_V(8); PG8_WAIT_L(0); PG8_BAR; PG8_MMA(1, 0, At, B0); PG8_MMA(1, 1, At, B1); PG8_BAR; PG8_SCHED;
;             PG8_LDB(B0, 1, 0); PG8_LDB(B1, 1, 1); PG8_SCHED; PG8_LDA(At, 1, 0); PG8_STAGE(PG8_SA(0, 1), a2 + hstep, voffA);
;             PG8_WAIT_V(8); PG8_WAIT_L(0); PG8_BAR; PG8_MMA(0, 0, At, B0); PG8_MMA(0, 1, At, B1); PG8_BAR; PG8_SCHED;
;             PG8_LDA(At, 1, 1); PG8_STAGE(PG8_SB(1, 0), b3, voffB); PG8_STAGE(PG8_SB(1, 1), b3 + hstep, voffB); PG8_STAGE(PG8_SA(1, 0), a3, voffA);
;             PG8_WAIT_V(8); PG8_WAIT_L(0); PG8_BAR; PG8_MMA(1, 0, At, B0); PG8_MMA(1, 1, At, B1); PG8_BAR; PG8_SCHED;
.Lwj_3_2:
	s_waitcnt lgkmcnt(0)
	s_barrier
	s_setprio 1
	s_waitcnt lgkmcnt(0)
	v_mfma_f32_16x16x32_bf16 v[144:147], v[80:83], v[160:163], v[144:147]
	v_mfma_f32_16x16x32_bf16 v[136:139], v[88:91], v[160:163], v[136:139]
	v_mfma_f32_16x16x32_bf16 v[128:131], v[80:83], v[168:171], v[128:131]
	v_mfma_f32_16x16x32_bf16 v[120:123], v[88:91], v[168:171], v[120:123]
	v_mfma_f32_16x16x32_bf16 v[112:115], v[80:83], v[176:179], v[112:115]
	v_mfma_f32_16x16x32_bf16 v[104:107], v[88:91], v[176:179], v[104:107]
	v_mfma_f32_16x16x32_bf16 v[72:75], v[80:83], v[184:187], v[72:75]
	v_mfma_f32_16x16x32_bf16 v[64:67], v[88:91], v[184:187], v[64:67]
	v_mfma_f32_16x16x32_bf16 v[144:147], v[84:87], v[164:167], v[144:147]
	v_mfma_f32_16x16x32_bf16 v[136:139], v[92:95], v[164:167], v[136:139]
	v_mfma_f32_16x16x32_bf16 v[128:131], v[84:87], v[172:175], v[128:131]
	v_mfma_f32_16x16x32_bf16 v[120:123], v[92:95], v[172:175], v[120:123]
	v_mfma_f32_16x16x32_bf16 v[112:115], v[84:87], v[180:183], v[112:115]
	v_mfma_f32_16x16x32_bf16 v[104:107], v[92:95], v[180:183], v[104:107]
	v_mfma_f32_16x16x32_bf16 v[72:75], v[84:87], v[188:191], v[72:75]
	v_mfma_f32_16x16x32_bf16 v[64:67], v[92:95], v[188:191], v[64:67]
	s_setprio 0
	s_setprio 1
	v_mfma_f32_16x16x32_bf16 v[148:151], v[96:99], v[160:163], v[148:151]
	v_mfma_f32_16x16x32_bf16 v[140:143], v[152:155], v[160:163], v[140:143]
	v_mfma_f32_16x16x32_bf16 v[132:135], v[96:99], v[168:171], v[132:135]
	v_mfma_f32_16x16x32_bf16 v[124:127], v[152:155], v[168:171], v[124:127]
	v_mfma_f32_16x16x32_bf16 v[116:119], v[96:99], v[176:179], v[116:119]
	v_mfma_f32_16x16x32_bf16 v[108:111], v[152:155], v[176:179], v[108:111]
	v_mfma_f32_16x16x32_bf16 v[76:79], v[96:99], v[184:187], v[76:79]
	v_mfma_f32_16x16x32_bf16 v[68:71], v[152:155], v[184:187], v[68:71]
	v_mfma_f32_16x16x32_bf16 v[148:151], v[100:103], v[164:167], v[148:151]
	v_mfma_f32_16x16x32_bf16 v[140:143], v[156:159], v[164:167], v[140:143]
	v_mfma_f32_16x16x32_bf16 v[132:135], v[100:103], v[172:175], v[132:135]
	v_mfma_f32_16x16x32_bf16 v[124:127], v[156:159], v[172:175], v[124:127]
	v_mfma_f32_16x16x32_bf16 v[116:119], v[100:103], v[180:183], v[116:119]
	v_mfma_f32_16x16x32_bf16 v[108:111], v[156:159], v[180:183], v[108:111]
	v_mfma_f32_16x16x32_bf16 v[76:79], v[100:103], v[188:191], v[76:79]
	v_mfma_f32_16x16x32_bf16 v[68:71], v[156:159], v[188:191], v[68:71]
	s_setprio 0
	s_barrier
	s_add_i32 s34, s60, s38
	v_lshl_add_u64 v[192:193], v[192:193], 0, s[16:17]
	s_mov_b32 m0, s34
	ds_read_b128 v[160:163], v248 offset:49152
	ds_read_b128 v[164:167], v248 offset:50176
	ds_read_b128 v[168:171], v248 offset:51200
	ds_read_b128 v[172:175], v248 offset:52224
	ds_read_b128 v[176:179], v248 offset:53248
	ds_read_b128 v[180:183], v248 offset:54272
	ds_read_b128 v[184:187], v248 offset:55296
	ds_read_b128 v[188:191], v248 offset:56320
	global_load_lds_dwordx4 v[192:193], off
	v_lshl_add_u64 v[192:193], v[194:195], 0, s[16:17]
	s_add_i32 m0, s34, 0x2000
	s_add_i32 s34, s61, s38
	global_load_lds_dwordx4 v[192:193], off
	v_lshl_add_u64 v[192:193], v[196:197], 0, s[16:17]
	s_mov_b32 m0, s34
	s_nop 0
	global_load_lds_dwordx4 v[192:193], off
	v_lshl_add_u64 v[192:193], v[198:199], 0, s[16:17]
	s_add_i32 m0, s34, 0x2000
	s_nop 0
	global_load_lds_dwordx4 v[192:193], off
	v_lshl_add_u64 v[192:193], v[218:219], 0, s[16:17]
	s_mov_b32 m0, s44
	s_nop 0
	global_load_lds_dwordx4 v[192:193], off
	v_lshl_add_u64 v[192:193], v[220:221], 0, s[16:17]
	s_mov_b32 m0, s45
	s_nop 0
	global_load_lds_dwordx4 v[192:193], off
	s_waitcnt vmcnt(8)
	s_waitcnt lgkmcnt(0)
	s_barrier
	s_setprio 1
	s_waitcnt lgkmcnt(0)
	v_mfma_f32_16x16x32_bf16 v[56:59], v[80:83], v[160:163], v[56:59]
	v_mfma_f32_16x16x32_bf16 v[48:51], v[88:91], v[160:163], v[48:51]
	v_mfma_f32_16x16x32_bf16 v[40:43], v[80:83], v[168:171], v[40:43]
	v_mfma_f32_16x16x32_bf16 v[32:35], v[88:91], v[168:171], v[32:35]
	v_mfma_f32_16x16x32_bf16 v[24:27], v[80:83], v[176:179], v[24:27]
	v_mfma_f32_16x16x32_bf16 v[16:19], v[88:91], v[176:179], v[16:19]
	v_mfma_f32_16x16x32_bf16 v[8:11], v[80:83], v[184:187], v[8:11]
	v_mfma_f32_16x16x32_bf16 v[0:3], v[88:91], v[184:187], v[0:3]
	v_mfma_f32_16x16x32_bf16 v[56:59], v[84:87], v[164:167], v[56:59]
	v_mfma_f32_16x16x32_bf16 v[48:51], v[92:95], v[164:167], v[48:51]
	v_mfma_f32_16x16x32_bf16 v[40:43], v[84:87], v[172:175], v[40:43]
	v_mfma_f32_16x16x32_bf16 v[32:35], v[92:95], v[172:175], v[32:35]
	v_mfma_f32_16x16x32_bf16 v[24:27], v[84:87], v[180:183], v[24:27]
	v_mfma_f32_16x16x32_bf16 v[16:19], v[92:95], v[180:183], v[16:19]
	v_mfma_f32_16x16x32_bf16 v[8:11], v[84:87], v[188:191], v[8:11]
	v_mfma_f32_16x16x32_bf16 v[0:3], v[92:95], v[188:191], v[0:3]
	s_setprio 0
	s_setprio 1
	v_mfma_f32_16x16x32_bf16 v[60:63], v[96:99], v[160:163], v[60:63]
	v_mfma_f32_16x16x32_bf16 v[52:55], v[152:155], v[160:163], v[52:55]
	v_mfma_f32_16x16x32_bf16 v[44:47], v[96:99], v[168:171], v[44:47]
	v_mfma_f32_16x16x32_bf16 v[36:39], v[152:155], v[168:171], v[36:39]
	v_mfma_f32_16x16x32_bf16 v[28:31], v[96:99], v[176:179], v[28:31]
	v_mfma_f32_16x16x32_bf16 v[20:23], v[152:155], v[176:179], v[20:23]
	v_mfma_f32_16x16x32_bf16 v[12:15], v[96:99], v[184:187], v[12:15]
	v_mfma_f32_16x16x32_bf16 v[4:7], v[152:155], v[184:187], v[4:7]
	v_mfma_f32_16x16x32_bf16 v[60:63], v[100:103], v[164:167], v[60:63]
	v_mfma_f32_16x16x32_bf16 v[52:55], v[156:159], v[164:167], v[52:55]
	v_mfma_f32_16x16x32_bf16 v[44:47], v[100:103], v[172:175], v[44:47]
	v_mfma_f32_16x16x32_bf16 v[36:39], v[156:159], v[172:175], v[36:39]
	v_mfma_f32_16x16x32_bf16 v[28:31], v[100:103], v[180:183], v[28:31]
	v_mfma_f32_16x16x32_bf16 v[20:23], v[156:159], v[180:183], v[20:23]
	v_mfma_f32_16x16x32_bf16 v[12:15], v[100:103], v[188:191], v[12:15]
	v_mfma_f32_16x16x32_bf16 v[4:7], v[156:159], v[188:191], v[4:7]
	s_setprio 0
	s_barrier
	s_add_u32 s10, s10, 0x100
	s_addc_u32 s11, s11, 0
	s_add_u32 s57, s57, 0x100
	s_addc_u32 s58, s58, 0
	s_cmp_ge_i32 s59, s46
	s_mov_b32 s34, s59
	s_cbranch_scc1 .LBB0_841

;     __device__ __forceinline__ void operator()(const AccT& acc, const Unit& u, int wr, int wc, int fr_, int fq_) const {
;         int fr = fr_, fq = fq_; asm volatile("" : "+v"(fr), "+v"(fq));
;         const int c0 = u.pn * 128 + wc * 32 + 8 * fq;
;         const bf16_t* const U = (const bf16_t*)(ws + WS_RB); bf16_t* const A2 = (bf16_t*)(ws + WS_A2);
;         const f32x4 w0a = *(const f32x4*)(conv_w + c0), w0b = *(const f32x4*)(conv_w + c0 + 4);
;         const f32x4 w1a = *(const f32x4*)(conv_w + 1024 + c0), w1b = *(const f32x4*)(conv_w + 1024 + c0 + 4);
;         const f32x4 w2a = *(const f32x4*)(conv_w + 2048 + c0), w2b = *(const f32x4*)(conv_w + 2048 + c0 + 4);
; #pragma unroll
;         for (int ai = 0; ai < 2; ++ai) {
;             u32x4 uu[4][3];
; #pragma unroll
;             for (int m = 0; m < 4; ++m) { const size_t row = (size_t)ROW_OF(ai, m); const int s = (int)(row & 2047); const u32x4 z4 = {0u, 0u, 0u, 0u};
;                 uu[m][2] = *(const u32x4*)(U + row * 1024 + c0);
;                 uu[m][1] = s >= 1 ? *(const u32x4*)(U + (row - 1) * 1024 + c0) : z4;
;                 uu[m][0] = s >= 2 ? *(const u32x4*)(U + (row - 2) * 1024 + c0) : z4; }
.LBB0_843:
	s_mov_b32 s99, 1
	v_lshl_add_u64 v[192:193], s[0:1], 0, v[210:211]
	v_lshl_add_u64 v[192:193], v[192:193], 0, 64
	v_lshl_add_u64 v[192:193], v[192:193], 0, 64
	s_add_i32 m0, s39, 0xc000
	s_mov_b32 s101, 1
	global_load_lds_dwordx4 v[192:193], off
	v_lshl_add_u64 v[192:193], s[0:1], 0, v[212:213]
	v_lshl_add_u64 v[192:193], v[192:193], 0, 64
	v_lshl_add_u64 v[192:193], v[192:193], 0, 64
	s_add_i32 m0, s39, 0xe000
	s_nop 0
	global_load_lds_dwordx4 v[192:193], off
	s_lshl_b32 s10, s56, 7
	v_mov_b32_e32 v152, v201
	v_mov_b32_e32 v80, v232
	s_or_b32 s10, s10, s48
	v_readlane_b32 s56, v254, 23
	v_lshl_add_u32 v220, v80, 3, s10
	s_lshl_b32 s10, s33, 8
	s_add_i32 s10, s10, s47
	v_add_u32_e32 v222, s10, v152
	v_ashrrev_i32_e32 v221, 31, v220
	v_ashrrev_i32_e32 v223, 31, v222
	v_lshlrev_b64 v[80:81], 2, v[220:221]
	v_readlane_b32 s70, v254, 37
	v_readlane_b32 s71, v254, 38
	v_lshlrev_b64 v[152:153], 11, v[222:223]
	v_lshl_add_u64 v[152:153], s[22:23], 0, v[152:153]
	v_lshl_add_u64 v[82:83], s[70:71], 0, v[80:81]
	global_load_dwordx4 v[88:91], v[82:83], off offset:16
	global_load_dwordx4 v[100:103], v[82:83], off
	v_lshl_add_u64 v[82:83], s[26:27], 0, v[80:81]
	v_lshl_add_u64 v[92:93], s[28:29], 0, v[80:81]
	v_lshl_add_u64 v[152:153], v[220:221], 1, v[152:153]
	global_load_dwordx4 v[84:87], v[82:83], off offset:16
	global_load_dwordx4 v[96:99], v[82:83], off
	s_nop 0
	global_load_dwordx4 v[80:83], v[92:93], off offset:16
	s_nop 0
	global_load_dwordx4 v[92:95], v[92:93], off
	v_and_b32_e32 v154, 0x7ff, v222
	global_load_dwordx4 v[188:191], v[152:153], off
	v_mov_b32_e32 v196, 0
	v_cmp_ne_u32_e32 vcc, 0, v154
	v_mov_b32_e32 v192, 0
	v_mov_b32_e32 v193, 0
	v_mov_b32_e32 v194, 0
	v_mov_b32_e32 v195, 0
	v_readlane_b32 s57, v254, 24
	v_readlane_b32 s58, v254, 25
	v_readlane_b32 s59, v254, 26
	v_readlane_b32 s60, v254, 27
	v_readlane_b32 s61, v254, 28
	v_readlane_b32 s62, v254, 29
	v_readlane_b32 s63, v254, 30
	v_readlane_b32 s64, v254, 31
	v_readlane_b32 s65, v254, 32
	v_readlane_b32 s66, v254, 33
	v_readlane_b32 s67, v254, 34
	v_readlane_b32 s68, v254, 35
	v_readlane_b32 s69, v254, 36
	s_and_saveexec_b64 s[10:11], vcc
	s_cbranch_execz .LBB0_845
	global_load_dwordx4 v[192:195], v[152:153], off offset:-2048

; #define PG8_STAGE(bufoff, gbase, voff) do { _Pragma("unroll") for (int _i = 0; _i < 2; ++_i) \
;         __builtin_amdgcn_global_load_lds((const unsigned*)((const char*)(gbase) + (voff)[_i]), (PG8_LAS unsigned*)(lds + (bufoff) + ldsw + _i * 8192), 16, 0, 0); } while (0)
; #define PG8_WAIT_V(n) asm volatile("s_waitcnt vmcnt(" #n ")" ::: "memory")
; #define PG8_BAR __builtin_amdgcn_s_barrier()
; template <class Epi, class Sched, bool ALIGN_EPI = false, bool SP2 = false>
; __device__ __forceinline__ void gemm_phase(PG8_LAS unsigned char* lds, const Gemm g, const Sched& S, const Epi& E) {
;     ...
;     if constexpr (SP2) {
;         PG8_STAGE(PG8_SB(0, 0), cB, voffB); PG8_STAGE(PG8_SB(0, 1), cB + hstep, voffB); PG8_STAGE(PG8_SA(0, 0), cA, voffA); PG8_STAGE(PG8_SA(0, 1), cA + hstep, voffA);
;         if (wr == 1) PG8_BAR;
;         PG8_WAIT_V(2); PG8_BAR;
;         PG8_STAGE(PG8_SB(1, 0), cB + kstep, voffB); PG8_STAGE(PG8_SA(1, 0), cA + kstep, voffA); PG8_STAGE(PG8_SB(1, 1), cB + hstep + kstep, voffB);
;         PG8_WAIT_V(6); PG8_BAR;
;     } else {
;     __device__ __forceinline__ void operator()(const AccT& acc, const Unit& u, int wr, int wc, int fr_, int fq_) const {
;     ...
;         bf16_t* const KN = (bf16_t*)(ws + WS_RA); bf16_t* const VI = (bf16_t*)(ws + WS_VIMG); const float* const ssq_kv = (const float*)(ws + WS_SSQ) + T;
;         float ssv[2][4];
; #pragma unroll
;         for (int ai = 0; ai < 2; ++ai)
; #pragma unroll
;             for (int m = 0; m < 4; ++m) ssv[ai][m] = ssq_kv[(size_t)ROW_OF(ai, m)];
.LBB0_888:
	s_mov_b64 s[14:15], 0x80
	s_add_i32 m0, s38, 0x18000
	v_lshl_add_u64 v[8:9], v[8:9], 0, s[14:15]
	s_waitcnt vmcnt(2)
	s_barrier
	global_load_lds_dwordx4 v[8:9], off
	v_lshl_add_u64 v[4:5], v[4:5], 0, s[14:15]
	s_add_i32 m0, s38, 0x1a000
	s_add_i32 s43, s38, 0x8000
	global_load_lds_dwordx4 v[4:5], off
	v_lshl_add_u64 v[4:5], v[6:7], 0, s[14:15]
	s_mov_b32 m0, s43
	s_add_i32 s44, s38, 0xa000
	global_load_lds_dwordx4 v[4:5], off
	v_lshl_add_u64 v[4:5], v[10:11], 0, s[14:15]
	s_mov_b32 m0, s44
	v_lshl_add_u64 v[2:3], v[2:3], 0, s[14:15]
	global_load_lds_dwordx4 v[4:5], off
	s_add_i32 m0, s38, 0x1c000
	v_lshl_add_u64 v[0:1], v[0:1], 0, s[14:15]
	global_load_lds_dwordx4 v[2:3], off
	s_add_i32 m0, s38, 0x1e000
	s_lshr_b32 s1, s1, 26
	global_load_lds_dwordx4 v[0:1], off
	s_add_i32 s1, s0, s1
	s_and_b32 s2, s2, 3
	s_ashr_i32 s45, s1, 6
	s_lshl_b32 s46, s3, 6
	s_lshl_b32 s1, s3, 13
	s_cmp_gt_i32 s0, 63
	s_cselect_b64 s[16:17], -1, 0
	s_add_i32 s47, s45, -2
	v_lshlrev_b32_e32 v1, 2, v201
	s_cmpk_lt_u32 s18, 0x100
	v_lshl_or_b32 v0, v201, 6, v238
	v_and_b32_e32 v1, 32, v1
	s_cselect_b64 s[18:19], -1, 0
	s_add_u32 s20, s90, 0x5000000
	v_bitop3_b32 v0, v0, s1, v1 bitop3:0xde
	s_addc_u32 s21, s91, 0
	v_add_u32_e32 v1, v237, v235
	s_add_u32 s22, s90, 0x20000
	v_mul_lo_u32 v1, s0, v1
	s_addc_u32 s23, s91, 0
	s_lshl_b32 s1, s2, 9
	v_lshlrev_b32_e32 v1, 1, v1
	s_add_u32 s1, s90, s1
	v_add3_u32 v136, v233, v1, v234
	v_add_u32_e32 v1, v236, v235
	s_addc_u32 s3, s91, 0
	v_mul_lo_u32 v1, s0, v1
	s_waitcnt vmcnt(6)
	s_add_u32 s24, s1, 0x1b000000
	v_lshlrev_b32_e32 v1, 1, v1
	v_lshl_or_b32 v168, s2, 12, v239
	s_addc_u32 s25, s3, 0
	v_lshl_add_u64 v[138:139], s[6:7], 0, v[136:137]
	v_add3_u32 v136, v233, v1, v234
	s_add_i32 s51, 0, 0x10000
	s_add_i32 s52, 0, 0x14000
	s_lshl_b32 s48, s2, 2
	s_ashr_i32 s49, s83, 31
	s_ashr_i32 s50, s80, 31
	v_lshl_add_u64 v[140:141], s[6:7], 0, v[136:137]
	v_mov_b64_e32 v[142:143], 0x400
	v_mov_b64_e32 v[144:145], 0x3ff
	v_add_u32_e32 v169, s51, v168
	v_add_u32_e32 v170, s52, v168
	v_add_u32_e32 v171, 0, v0
	v_mov_b32_e32 v172, 0x358637bd
	s_mov_b32 s53, 0x80000
	s_barrier
	v_lshl_add_u32 v253, s31, 8, v201
	v_add_lshl_u32 v253, v253, s46, 2
	global_load_dword v245, v253, s[22:23]
	global_load_dword v246, v253, s[22:23] offset:64
	global_load_dword v247, v253, s[22:23] offset:128
	global_load_dword v248, v253, s[22:23] offset:192
	global_load_dword v249, v253, s[22:23] offset:512
	global_load_dword v250, v253, s[22:23] offset:576
	global_load_dword v251, v253, s[22:23] offset:640
	global_load_dword v252, v253, s[22:23] offset:704
	s_mov_b32 s101, 0
	s_mov_b32 s99, 0
	s_branch .LBB0_891

; #define PG8_STAGE(bufoff, gbase, voff) do { _Pragma("unroll") for (int _i = 0; _i < 2; ++_i) \
;         __builtin_amdgcn_global_load_lds((const unsigned*)((const char*)(gbase) + (voff)[_i]), (PG8_LAS unsigned*)(lds + (bufoff) + ldsw + _i * 8192), 16, 0, 0); } while (0)
; #define PG8_LDA(dst, b, h) do { _Pragma("unroll") for (int m = 0; m < 4; ++m) _Pragma("unroll") for (int k = 0; k < 2; ++k) dst[m][k] = *(const PG8_LAS bf16x8*)(lds + PG8_SA(b, h) + aoff + m * 2048 + k * 1024); } while (0)
; #define PG8_LDB(dst, b, h) do { _Pragma("unroll") for (int n = 0; n < 2; ++n) _Pragma("unroll") for (int k = 0; k < 2; ++k) dst[n][k] = *(const PG8_LAS bf16x8*)(lds + PG8_SB(b, h) + boff + n * 2048 + k * 1024); } while (0)
; #define PG8_SCHED __builtin_amdgcn_sched_barrier(0)
; template <class Epi, class Sched, bool ALIGN_EPI = false, bool SP2 = false>
; __device__ __forceinline__ void gemm_phase(PG8_LAS unsigned char* lds, const Gemm g, const Sched& S, const Epi& E) {
;     ...
;             const bool last = (t == nt - 2);
;             const char* a1 = cA + (size_t)(t + 1) * kstep;
;             const char* a2 = last ? nA : cA + (size_t)(t + 2) * kstep; const char* b2 = last ? nB : cB + (size_t)(t + 2) * kstep;
;             const char* a3 = a2 + kstep; const char* b3 = b2 + kstep;
;             if (last && has_next) S.a_ready(nxt);
;             if constexpr (SP2) {
;             PG8_LDB(B0, 0, 0); PG8_LDB(B1, 0, 1); PG8_SCHED; PG8_LDA(At, 0, 0); PG8_STAGE(PG8_SA(1, 1), a1 + hstep, voffA);
.LBB0_901:
	s_andn2_b64 vcc, exec, s[16:17]
	s_cbranch_vccnz .LBB0_904
	s_add_u32 s4, s4, 0x80
	s_addc_u32 s5, s5, 0
	s_add_u32 s56, s28, 0x100
	s_addc_u32 s57, s29, 0
	s_mov_b32 s28, 0
	ds_read_b128 v[146:149], v169
	ds_read_b128 v[150:153], v169 offset:1024
	ds_read_b128 v[154:157], v169 offset:2048
	ds_read_b128 v[158:161], v169 offset:3072
	ds_read_b128 v[162:165], v170
	ds_read_b128 v[174:177], v170 offset:1024
	ds_read_b128 v[178:181], v170 offset:2048
	ds_read_b128 v[182:185], v170 offset:3072
	s_add_i32 s58, s28, 2
	s_add_u32 s59, s4, 0x80
	s_addc_u32 s29, s5, 0
	s_cmp_eq_u32 s47, s28
	s_cselect_b32 s28, s0, s59
	s_cselect_b32 s29, s1, s29
	s_cselect_b32 s61, s27, s57
	s_cselect_b32 s60, s26, s56
	v_lshl_add_u64 v[166:167], s[4:5], 0, v[138:139]
	s_add_i32 m0, s38, 0xc000
	ds_read_b128 v[186:189], v171
	ds_read_b128 v[190:193], v171 offset:1024
	ds_read_b128 v[194:197], v171 offset:2048
	ds_read_b128 v[202:205], v171 offset:3072
	ds_read_b128 v[206:209], v171 offset:4096
	ds_read_b128 v[210:213], v171 offset:5120
	ds_read_b128 v[214:217], v171 offset:6144
	ds_read_b128 v[218:221], v171 offset:7168
	s_cmp_lg_u32 s101, 0
	s_cbranch_scc1 .Ly1_skip_4
	global_load_lds_dwordx4 v[166:167], off
	v_lshl_add_u64 v[166:167], s[4:5], 0, v[140:141]
	s_add_i32 m0, s38, 0xe000
	s_nop 0
	global_load_lds_dwordx4 v[166:167], off

; #define PG8_STAGE(bufoff, gbase, voff) do { _Pragma("unroll") for (int _i = 0; _i < 2; ++_i) \
;         __builtin_amdgcn_global_load_lds((const unsigned*)((const char*)(gbase) + (voff)[_i]), (PG8_LAS unsigned*)(lds + (bufoff) + ldsw + _i * 8192), 16, 0, 0); } while (0)
; #define PG8_LDA(dst, b, h) do { _Pragma("unroll") for (int m = 0; m < 4; ++m) _Pragma("unroll") for (int k = 0; k < 2; ++k) dst[m][k] = *(const PG8_LAS bf16x8*)(lds + PG8_SA(b, h) + aoff + m * 2048 + k * 1024); } while (0)
; #define PG8_LDB(dst, b, h) do { _Pragma("unroll") for (int n = 0; n < 2; ++n) _Pragma("unroll") for (int k = 0; k < 2; ++k) dst[n][k] = *(const PG8_LAS bf16x8*)(lds + PG8_SB(b, h) + boff + n * 2048 + k * 1024); } while (0)
; #define PG8_MMA(ai, bj, At, Bt) do { __builtin_amdgcn_s_setprio(1); _Pragma("unroll") for (int m = 0; m < 4; ++m) _Pragma("unroll") for (int n = 0; n < 2; ++n) _Pragma("unroll") for (int k = 0; k < 2; ++k) \
;         acc[ai][bj][m][n] = __builtin_amdgcn_mfma_f32_16x16x32_bf16(Bt[n][k], At[m][k], acc[ai][bj][m][n], 0, 0, 0); __builtin_amdgcn_s_setprio(0); } while (0)
; #define PG8_WAIT_V(n) asm volatile("s_waitcnt vmcnt(" #n ")" ::: "memory")
; #define PG8_WAIT_L(n) asm volatile("s_waitcnt lgkmcnt(" #n ")" ::: "memory")
; #define PG8_BAR __builtin_amdgcn_s_barrier()
; #define PG8_SCHED __builtin_amdgcn_sched_barrier(0)
; template <class Epi, class Sched, bool ALIGN_EPI = false, bool SP2 = false>
; __device__ __forceinline__ void gemm_phase(PG8_LAS unsigned char* lds, const Gemm g, const Sched& S, const Epi& E) {
;     ...
;             PG8_WAIT_V(8); PG8_WAIT_L(0); PG8_BAR; PG8_MMA(0, 0, At, B0); PG8_MMA(0, 1, At, B1); PG8_BAR; PG8_SCHED;
;             PG8_LDA(At, 0, 1); PG8_STAGE(PG8_SB(0, 0), b2, voffB); PG8_STAGE(PG8_SB(0, 1), b2 + hstep, voffB); PG8_STAGE(PG8_SA(0, 0), a2, voffA);
;             PG8_WAIT_V(8); PG8_WAIT_L(0); PG8_BAR; PG8_MMA(1, 0, At, B0); PG8_MMA(1, 1, At, B1); PG8_BAR; PG8_SCHED;
;             PG8_LDB(B0, 1, 0); PG8_LDB(B1, 1, 1); PG8_SCHED; PG8_LDA(At, 1, 0); PG8_STAGE(PG8_SA(0, 1), a2 + hstep, voffA);
;             PG8_WAIT_V(8); PG8_WAIT_L(0); PG8_BAR; PG8_MMA(0, 0, At, B0); PG8_MMA(0, 1, At, B1); PG8_BAR; PG8_SCHED;
.Lwj_4_1:
	s_waitcnt lgkmcnt(0)
	s_barrier
	s_setprio 1
	s_waitcnt lgkmcnt(0)
	v_mfma_f32_16x16x32_bf16 v[60:63], v[146:149], v[186:189], 0
	v_mfma_f32_16x16x32_bf16 v[56:59], v[154:157], v[186:189], 0
	v_mfma_f32_16x16x32_bf16 v[44:47], v[146:149], v[194:197], 0
	v_mfma_f32_16x16x32_bf16 v[40:43], v[154:157], v[194:197], 0
	v_mfma_f32_16x16x32_bf16 v[28:31], v[146:149], v[206:209], 0
	v_mfma_f32_16x16x32_bf16 v[24:27], v[154:157], v[206:209], 0
	v_mfma_f32_16x16x32_bf16 v[12:15], v[146:149], v[214:217], 0
	v_mfma_f32_16x16x32_bf16 v[8:11], v[154:157], v[214:217], 0
	v_mfma_f32_16x16x32_bf16 v[60:63], v[150:153], v[190:193], v[60:63]
	v_mfma_f32_16x16x32_bf16 v[56:59], v[158:161], v[190:193], v[56:59]
	v_mfma_f32_16x16x32_bf16 v[44:47], v[150:153], v[202:205], v[44:47]
	v_mfma_f32_16x16x32_bf16 v[40:43], v[158:161], v[202:205], v[40:43]
	v_mfma_f32_16x16x32_bf16 v[28:31], v[150:153], v[210:213], v[28:31]
	v_mfma_f32_16x16x32_bf16 v[24:27], v[158:161], v[210:213], v[24:27]
	v_mfma_f32_16x16x32_bf16 v[12:15], v[150:153], v[218:221], v[12:15]
	v_mfma_f32_16x16x32_bf16 v[8:11], v[158:161], v[218:221], v[8:11]
	s_setprio 0
	s_setprio 1
	v_mfma_f32_16x16x32_bf16 v[52:55], v[162:165], v[186:189], 0
	v_mfma_f32_16x16x32_bf16 v[48:51], v[178:181], v[186:189], 0
	v_mfma_f32_16x16x32_bf16 v[36:39], v[162:165], v[194:197], 0
	v_mfma_f32_16x16x32_bf16 v[32:35], v[178:181], v[194:197], 0
	v_mfma_f32_16x16x32_bf16 v[20:23], v[162:165], v[206:209], 0
	v_mfma_f32_16x16x32_bf16 v[16:19], v[178:181], v[206:209], 0
	v_mfma_f32_16x16x32_bf16 v[0:3], v[162:165], v[214:217], 0
	v_mfma_f32_16x16x32_bf16 v[4:7], v[178:181], v[214:217], 0
	v_mfma_f32_16x16x32_bf16 v[52:55], v[174:177], v[190:193], v[52:55]
	v_mfma_f32_16x16x32_bf16 v[48:51], v[182:185], v[190:193], v[48:51]
	v_mfma_f32_16x16x32_bf16 v[36:39], v[174:177], v[202:205], v[36:39]
	v_mfma_f32_16x16x32_bf16 v[32:35], v[182:185], v[202:205], v[32:35]
	v_mfma_f32_16x16x32_bf16 v[20:23], v[174:177], v[210:213], v[20:23]
	v_mfma_f32_16x16x32_bf16 v[16:19], v[182:185], v[210:213], v[16:19]
	v_mfma_f32_16x16x32_bf16 v[0:3], v[174:177], v[218:221], v[0:3]
	v_mfma_f32_16x16x32_bf16 v[4:7], v[182:185], v[218:221], v[4:7]
	s_setprio 0
	s_barrier
	s_add_i32 s59, 0, 0x18000
	v_add_u32_e32 v136, s59, v168
	s_add_i32 s60, 0, 0x1c000
	ds_read_b128 v[146:149], v136
	ds_read_b128 v[150:153], v136 offset:1024
	ds_read_b128 v[154:157], v136 offset:2048
	ds_read_b128 v[158:161], v136 offset:3072
	v_add_u32_e32 v136, s60, v168
	ds_read_b128 v[162:165], v136
	ds_read_b128 v[174:177], v136 offset:1024
	ds_read_b128 v[178:181], v136 offset:2048
	ds_read_b128 v[182:185], v136 offset:3072
	s_add_u32 s28, s28, s6
	s_addc_u32 s29, s29, s7
	s_mov_b32 m0, s40
	v_lshl_add_u64 v[230:231], s[28:29], 0, v[128:129]
	ds_read_b128 v[186:189], v171 offset:32768
	ds_read_b128 v[190:193], v171 offset:33792
	ds_read_b128 v[194:197], v171 offset:34816
	ds_read_b128 v[202:205], v171 offset:35840
	ds_read_b128 v[206:209], v171 offset:36864
	ds_read_b128 v[210:213], v171 offset:37888
	ds_read_b128 v[214:217], v171 offset:38912
	ds_read_b128 v[218:221], v171 offset:39936
	global_load_lds_dwordx4 v[230:231], off
	v_lshl_add_u64 v[230:231], s[28:29], 0, v[132:133]
	s_mov_b32 m0, s41
	s_nop 0
	global_load_lds_dwordx4 v[230:231], off
	s_cmp_eq_u32 s99, 0
	s_cbranch_scc1 .Lw8_4_2
	s_waitcnt vmcnt(16)
	s_branch .Lwj_4_2

; #define PG8_STAGE(bufoff, gbase, voff) do { _Pragma("unroll") for (int _i = 0; _i < 2; ++_i) \
;         __builtin_amdgcn_global_load_lds((const unsigned*)((const char*)(gbase) + (voff)[_i]), (PG8_LAS unsigned*)(lds + (bufoff) + ldsw + _i * 8192), 16, 0, 0); } while (0)
; #define PG8_LDA(dst, b, h) do { _Pragma("unroll") for (int m = 0; m < 4; ++m) _Pragma("unroll") for (int k = 0; k < 2; ++k) dst[m][k] = *(const PG8_LAS bf16x8*)(lds + PG8_SA(b, h) + aoff + m * 2048 + k * 1024); } while (0)
; #define PG8_LDB(dst, b, h) do { _Pragma("unroll") for (int n = 0; n < 2; ++n) _Pragma("unroll") for (int k = 0; k < 2; ++k) dst[n][k] = *(const PG8_LAS bf16x8*)(lds + PG8_SB(b, h) + boff + n * 2048 + k * 1024); } while (0)
; #define PG8_MMA(ai, bj, At, Bt) do { __builtin_amdgcn_s_setprio(1); _Pragma("unroll") for (int m = 0; m < 4; ++m) _Pragma("unroll") for (int n = 0; n < 2; ++n) _Pragma("unroll") for (int k = 0; k < 2; ++k) \
;         acc[ai][bj][m][n] = __builtin_amdgcn_mfma_f32_16x16x32_bf16(Bt[n][k], At[m][k], acc[ai][bj][m][n], 0, 0, 0); __builtin_amdgcn_s_setprio(0); } while (0)
; #define PG8_WAIT_V(n) asm volatile("s_waitcnt vmcnt(" #n ")" ::: "memory")
; #define PG8_WAIT_L(n) asm volatile("s_waitcnt lgkmcnt(" #n ")" ::: "memory")
; #define PG8_BAR __builtin_amdgcn_s_barrier()
; #define PG8_SCHED __builtin_amdgcn_sched_barrier(0)
; template <class Epi, class Sched, bool ALIGN_EPI = false, bool SP2 = false>
; __device__ __forceinline__ void gemm_phase(PG8_LAS unsigned char* lds, const Gemm g, const Sched& S, const Epi& E) {
;     ...
;             PG8_WAIT_V(8); PG8_WAIT_L(0); PG8_BAR; PG8_MMA(1, 0, At, B0); PG8_MMA(1, 1, At, B1); PG8_BAR; PG8_SCHED;
;             PG8_LDB(B0, 1, 0); PG8_LDB(B1, 1, 1); PG8_SCHED; PG8_LDA(At, 1, 0); PG8_STAGE(PG8_SA(0, 1), a2 + hstep, voffA);
;             PG8_WAIT_V(8); PG8_WAIT_L(0); PG8_BAR; PG8_MMA(0, 0, At, B0); PG8_MMA(0, 1, At, B1); PG8_BAR; PG8_SCHED;
;             PG8_LDA(At, 1, 1); PG8_STAGE(PG8_SB(1, 0), b3, voffB); PG8_STAGE(PG8_SB(1, 1), b3 + hstep, voffB); PG8_STAGE(PG8_SA(1, 0), a3, voffA);
;             PG8_WAIT_V(8); PG8_WAIT_L(0); PG8_BAR; PG8_MMA(1, 0, At, B0); PG8_MMA(1, 1, At, B1); PG8_BAR; PG8_SCHED;
.Lwj_4_2:
	s_waitcnt lgkmcnt(0)
	s_barrier
	s_setprio 1
	s_waitcnt lgkmcnt(0)
	v_mfma_f32_16x16x32_bf16 v[120:123], v[146:149], v[186:189], v[120:123]
	v_mfma_f32_16x16x32_bf16 v[124:127], v[154:157], v[186:189], v[124:127]
	v_mfma_f32_16x16x32_bf16 v[108:111], v[146:149], v[194:197], v[108:111]
	v_mfma_f32_16x16x32_bf16 v[104:107], v[154:157], v[194:197], v[104:107]
	v_mfma_f32_16x16x32_bf16 v[92:95], v[146:149], v[206:209], v[92:95]
	v_mfma_f32_16x16x32_bf16 v[88:91], v[154:157], v[206:209], v[88:91]
	v_mfma_f32_16x16x32_bf16 v[76:79], v[146:149], v[214:217], v[76:79]
	v_mfma_f32_16x16x32_bf16 v[72:75], v[154:157], v[214:217], v[72:75]
	v_mfma_f32_16x16x32_bf16 v[120:123], v[150:153], v[190:193], v[120:123]
	v_mfma_f32_16x16x32_bf16 v[124:127], v[158:161], v[190:193], v[124:127]
	v_mfma_f32_16x16x32_bf16 v[108:111], v[150:153], v[202:205], v[108:111]
	v_mfma_f32_16x16x32_bf16 v[104:107], v[158:161], v[202:205], v[104:107]
	v_mfma_f32_16x16x32_bf16 v[92:95], v[150:153], v[210:213], v[92:95]
	v_mfma_f32_16x16x32_bf16 v[88:91], v[158:161], v[210:213], v[88:91]
	v_mfma_f32_16x16x32_bf16 v[76:79], v[150:153], v[218:221], v[76:79]
	v_mfma_f32_16x16x32_bf16 v[72:75], v[158:161], v[218:221], v[72:75]
	s_setprio 0
	s_setprio 1
	v_mfma_f32_16x16x32_bf16 v[116:119], v[162:165], v[186:189], v[116:119]
	v_mfma_f32_16x16x32_bf16 v[112:115], v[178:181], v[186:189], v[112:115]
	v_mfma_f32_16x16x32_bf16 v[100:103], v[162:165], v[194:197], v[100:103]
	v_mfma_f32_16x16x32_bf16 v[96:99], v[178:181], v[194:197], v[96:99]
	v_mfma_f32_16x16x32_bf16 v[84:87], v[162:165], v[206:209], v[84:87]
	v_mfma_f32_16x16x32_bf16 v[80:83], v[178:181], v[206:209], v[80:83]
	v_mfma_f32_16x16x32_bf16 v[68:71], v[162:165], v[214:217], v[68:71]
	v_mfma_f32_16x16x32_bf16 v[64:67], v[178:181], v[214:217], v[64:67]
	v_mfma_f32_16x16x32_bf16 v[116:119], v[174:177], v[190:193], v[116:119]
	v_mfma_f32_16x16x32_bf16 v[112:115], v[182:185], v[190:193], v[112:115]
	v_mfma_f32_16x16x32_bf16 v[100:103], v[174:177], v[202:205], v[100:103]
	v_mfma_f32_16x16x32_bf16 v[96:99], v[182:185], v[202:205], v[96:99]
	v_mfma_f32_16x16x32_bf16 v[84:87], v[174:177], v[210:213], v[84:87]
	v_mfma_f32_16x16x32_bf16 v[80:83], v[182:185], v[210:213], v[80:83]
	v_mfma_f32_16x16x32_bf16 v[68:71], v[174:177], v[218:221], v[68:71]
	v_mfma_f32_16x16x32_bf16 v[64:67], v[182:185], v[218:221], v[64:67]
	s_setprio 0
	s_barrier
	s_add_i32 s28, s59, s37
	v_lshl_add_u64 v[166:167], v[166:167], 0, s[14:15]
	s_mov_b32 m0, s28
	ds_read_b128 v[186:189], v171 offset:49152
	ds_read_b128 v[190:193], v171 offset:50176
	ds_read_b128 v[194:197], v171 offset:51200
	ds_read_b128 v[202:205], v171 offset:52224
	ds_read_b128 v[206:209], v171 offset:53248
	ds_read_b128 v[210:213], v171 offset:54272
	ds_read_b128 v[214:217], v171 offset:55296
	ds_read_b128 v[218:221], v171 offset:56320
	global_load_lds_dwordx4 v[166:167], off
	v_lshl_add_u64 v[166:167], v[198:199], 0, s[14:15]
	s_add_i32 m0, s28, 0x2000
	s_add_i32 s28, s60, s37
	global_load_lds_dwordx4 v[166:167], off
	v_lshl_add_u64 v[166:167], v[222:223], 0, s[14:15]
	s_mov_b32 m0, s28
	s_nop 0
	global_load_lds_dwordx4 v[166:167], off
	v_lshl_add_u64 v[166:167], v[224:225], 0, s[14:15]
	s_add_i32 m0, s28, 0x2000
	s_nop 0
	global_load_lds_dwordx4 v[166:167], off
	v_lshl_add_u64 v[166:167], v[226:227], 0, s[14:15]
	s_mov_b32 m0, s43
	s_nop 0
	global_load_lds_dwordx4 v[166:167], off
	v_lshl_add_u64 v[166:167], v[228:229], 0, s[14:15]
	s_mov_b32 m0, s44
	s_nop 0
	global_load_lds_dwordx4 v[166:167], off
	s_waitcnt vmcnt(8)
	s_waitcnt lgkmcnt(0)
	s_barrier
	s_setprio 1
	s_waitcnt lgkmcnt(0)
	v_mfma_f32_16x16x32_bf16 v[60:63], v[146:149], v[186:189], v[60:63]
	v_mfma_f32_16x16x32_bf16 v[56:59], v[154:157], v[186:189], v[56:59]
	v_mfma_f32_16x16x32_bf16 v[44:47], v[146:149], v[194:197], v[44:47]
	v_mfma_f32_16x16x32_bf16 v[40:43], v[154:157], v[194:197], v[40:43]
	v_mfma_f32_16x16x32_bf16 v[28:31], v[146:149], v[206:209], v[28:31]
	v_mfma_f32_16x16x32_bf16 v[24:27], v[154:157], v[206:209], v[24:27]
	v_mfma_f32_16x16x32_bf16 v[12:15], v[146:149], v[214:217], v[12:15]
	v_mfma_f32_16x16x32_bf16 v[8:11], v[154:157], v[214:217], v[8:11]
	v_mfma_f32_16x16x32_bf16 v[60:63], v[150:153], v[190:193], v[60:63]
	v_mfma_f32_16x16x32_bf16 v[56:59], v[158:161], v[190:193], v[56:59]
	v_mfma_f32_16x16x32_bf16 v[44:47], v[150:153], v[202:205], v[44:47]
	v_mfma_f32_16x16x32_bf16 v[40:43], v[158:161], v[202:205], v[40:43]
	v_mfma_f32_16x16x32_bf16 v[28:31], v[150:153], v[210:213], v[28:31]
	v_mfma_f32_16x16x32_bf16 v[24:27], v[158:161], v[210:213], v[24:27]
	v_mfma_f32_16x16x32_bf16 v[12:15], v[150:153], v[218:221], v[12:15]
	v_mfma_f32_16x16x32_bf16 v[8:11], v[158:161], v[218:221], v[8:11]
	s_setprio 0
	s_setprio 1
	v_mfma_f32_16x16x32_bf16 v[52:55], v[162:165], v[186:189], v[52:55]
	v_mfma_f32_16x16x32_bf16 v[48:51], v[178:181], v[186:189], v[48:51]
	v_mfma_f32_16x16x32_bf16 v[36:39], v[162:165], v[194:197], v[36:39]
	v_mfma_f32_16x16x32_bf16 v[32:35], v[178:181], v[194:197], v[32:35]
	v_mfma_f32_16x16x32_bf16 v[20:23], v[162:165], v[206:209], v[20:23]
	v_mfma_f32_16x16x32_bf16 v[16:19], v[178:181], v[206:209], v[16:19]
	v_mfma_f32_16x16x32_bf16 v[0:3], v[162:165], v[214:217], v[0:3]
	v_mfma_f32_16x16x32_bf16 v[4:7], v[178:181], v[214:217], v[4:7]
	v_mfma_f32_16x16x32_bf16 v[52:55], v[174:177], v[190:193], v[52:55]
	v_mfma_f32_16x16x32_bf16 v[48:51], v[182:185], v[190:193], v[48:51]
	v_mfma_f32_16x16x32_bf16 v[36:39], v[174:177], v[202:205], v[36:39]
	v_mfma_f32_16x16x32_bf16 v[32:35], v[182:185], v[202:205], v[32:35]
	v_mfma_f32_16x16x32_bf16 v[20:23], v[174:177], v[210:213], v[20:23]
	v_mfma_f32_16x16x32_bf16 v[16:19], v[182:185], v[210:213], v[16:19]
	v_mfma_f32_16x16x32_bf16 v[0:3], v[174:177], v[218:221], v[0:3]
	v_mfma_f32_16x16x32_bf16 v[4:7], v[182:185], v[218:221], v[4:7]
	s_setprio 0
	s_barrier
	s_add_u32 s4, s4, 0x100
	s_addc_u32 s5, s5, 0
	s_add_u32 s56, s56, 0x100
	s_addc_u32 s57, s57, 0
	s_cmp_ge_i32 s58, s45
	s_mov_b32 s28, s58
	s_cbranch_scc1 .LBB0_904

; __device__ __forceinline__ u32x4 pk8(f32x4 a, f32x4 b) { u32x4 w; w.x = pk2(a[0], a[1]); w.y = pk2(a[2], a[3]); w.z = pk2(b[0], b[1]); w.w = pk2(b[2], b[3]); return w; }
; __device__ __forceinline__ void st16(bf16_t* p, u32x4 v) { __builtin_nontemporal_store(v, (u32x4*)p); }
;     __device__ __forceinline__ void operator()(const AccT& acc, const Unit& u, int wr, int wc, int fr_, int fq_) const {
;         int fr = fr_, fq = fq_; asm volatile("" : "+v"(fr), "+v"(fq));
;         const int pn = u.pn;
;         bf16_t* const KN = (bf16_t*)(ws + WS_RA); bf16_t* const VI = (bf16_t*)(ws + WS_VIMG); const float* const ssq_kv = (const float*)(ws + WS_SSQ) + T;
;         float ssv[2][4];
; #pragma unroll
;         for (int ai = 0; ai < 2; ++ai)
; #pragma unroll
;             for (int m = 0; m < 4; ++m) ssv[ai][m] = ssq_kv[(size_t)ROW_OF(ai, m)];
; #pragma unroll
;         for (int ai = 0; ai < 2; ++ai)
; #pragma unroll
;             for (int m = 0; m < 4; ++m) {
;                 const size_t row = (size_t)ROW_OF(ai, m);
;                 const float sc = __builtin_amdgcn_rsqf(ssv[ai][m] * (1.0f / KVLORA) + EPS);
;                 const int b = (int)(row >> 11), s = (int)(row & 2047);
;                 const f32x4 a0 = acc[ai][0][m][0] * sc, a1 = acc[ai][0][m][1] * sc, b0 = acc[ai][1][m][0] * sc, b1 = acc[ai][1][m][1] * sc;
;                 if (pn < 4) {
;                     const int ks = 2 * wc + (fq >> 1), h = fq & 1;
;                     bf16_t* p = KN + ((size_t)((b * 8 + 2 * pn) * 64 + (s >> 5))) * 4096 + (ks * 2 + h) * 256 + (s & 31) * 8;
;                     st16(p, pk8(a0, a1)); st16(p + (size_t)64 * 4096, pk8(b0, b1));
.LBB0_906:
	s_mov_b32 s99, 1
	v_lshl_add_u64 v[166:167], s[0:1], 0, v[138:139]
	v_lshl_add_u64 v[166:167], v[166:167], 0, 64
	v_lshl_add_u64 v[166:167], v[166:167], 0, 64
	s_add_i32 m0, s38, 0xc000
	s_mov_b32 s101, 1
	global_load_lds_dwordx4 v[166:167], off
	v_lshl_add_u64 v[166:167], s[0:1], 0, v[140:141]
	v_lshl_add_u64 v[166:167], v[166:167], 0, 64
	v_lshl_add_u64 v[166:167], v[166:167], 0, 64
	s_add_i32 m0, s38, 0xe000
	s_nop 0
	global_load_lds_dwordx4 v[166:167], off
	s_lshl_b32 s4, s31, 8
	v_mov_b32_e32 v167, v201
	v_mov_b32_e32 v173, v232
	s_add_i32 s4, s4, s46
	s_cmp_gt_i32 s30, 3
	v_add_u32_e32 v162, s4, v167
	v_ashrrev_i32_e32 v163, 31, v162
	v_lshl_add_u64 v[146:147], v[162:163], 2, s[22:23]
	v_add_u32_e32 v160, 16, v162
	v_mov_b32_e32 v166, v245
	v_ashrrev_i32_e32 v161, 31, v160
	v_add_u32_e32 v158, 32, v162
	v_add_u32_e32 v156, 48, v162
	v_add_u32_e32 v154, 0x80, v162
	v_add_u32_e32 v152, 0x90, v162
	v_add_u32_e32 v150, 0xa0, v162
	v_add_u32_e32 v146, 0xb0, v162
	v_lshl_add_u64 v[148:149], v[160:161], 2, s[22:23]
	v_ashrrev_i32_e32 v159, 31, v158
	v_ashrrev_i32_e32 v157, 31, v156
	v_ashrrev_i32_e32 v155, 31, v154
	v_ashrrev_i32_e32 v153, 31, v152
	v_ashrrev_i32_e32 v151, 31, v150
	v_ashrrev_i32_e32 v147, 31, v146
	v_lshl_add_u64 v[164:165], v[158:159], 2, s[22:23]
	v_lshl_add_u64 v[174:175], v[156:157], 2, s[22:23]
	v_lshl_add_u64 v[176:177], v[154:155], 2, s[22:23]
	v_lshl_add_u64 v[178:179], v[152:153], 2, s[22:23]
	v_lshl_add_u64 v[180:181], v[150:151], 2, s[22:23]
	v_lshl_add_u64 v[182:183], v[146:147], 2, s[22:23]
	v_mov_b32_e32 v161, v246
	v_mov_b32_e32 v159, v247
	v_mov_b32_e32 v157, v248
	v_mov_b32_e32 v155, v249
	v_mov_b32_e32 v153, v250
	v_mov_b32_e32 v151, v251
	v_mov_b32_e32 v147, v252
	v_lshlrev_b32_e32 v136, 6, v167
	v_lshlrev_b32_e32 v148, 3, v173
	v_and_b32_e32 v136, 0x1c0, v136
	s_cselect_b64 s[28:29], -1, 0
	s_lshl_b32 s56, s30, 9
	v_ashrrev_i32_e32 v149, 31, v148
	v_lshl_add_u64 v[174:175], s[24:25], 0, v[136:137]
	s_mov_b64 s[4:5], -1
	v_and_b32_e32 v163, 0x7ff, v162
	s_addk_i32 s56, 0xf800
	s_and_b64 vcc, exec, s[28:29]
	v_lshl_add_u64 v[148:149], v[148:149], 1, v[174:175]
	v_lshl_add_u32 v253, s55, 8, v201
	v_add_lshl_u32 v253, v253, s46, 2
	global_load_dword v245, v253, s[22:23]
	global_load_dword v246, v253, s[22:23] offset:64
	global_load_dword v247, v253, s[22:23] offset:128
	global_load_dword v248, v253, s[22:23] offset:192
	global_load_dword v249, v253, s[22:23] offset:512
	global_load_dword v250, v253, s[22:23] offset:576
	global_load_dword v251, v253, s[22:23] offset:640
	global_load_dword v252, v253, s[22:23] offset:704
	s_waitcnt vmcnt(8)
	v_fmamk_f32 v166, v166, 0x3b800000, v172
	v_rsq_f32_e32 v166, v166
	s_nop 0
	v_pk_mul_f32 v[122:123], v[122:123], v[166:167] op_sel_hi:[1,0]
	v_pk_mul_f32 v[120:121], v[120:121], v[166:167] op_sel_hi:[1,0]
	v_pk_mul_f32 v[126:127], v[126:127], v[166:167] op_sel_hi:[1,0]
	v_pk_mul_f32 v[124:125], v[124:125], v[166:167] op_sel_hi:[1,0]
	v_cvt_pk_bf16_f32 v120, v120, v121
	v_cvt_pk_bf16_f32 v121, v122, v123
	v_cvt_pk_bf16_f32 v122, v124, v125
	v_cvt_pk_bf16_f32 v123, v126, v127
	s_cbranch_vccz .LBB0_908
	v_and_b32_e32 v124, 0xfffff800, v162
	v_add_u32_e32 v124, s56, v124
	v_lshrrev_b32_e32 v125, 3, v163
	v_or_b32_e32 v124, v124, v125
	v_ashrrev_i32_e32 v125, 31, v124
	v_lshlrev_b64 v[124:125], 11, v[124:125]
	v_lshl_add_u64 v[164:165], v[148:149], 0, v[124:125]
	global_store_dwordx4 v[164:165], v[120:123], off nt
	s_mov_b64 s[4:5], 0

; #define PG8_STAGE(bufoff, gbase, voff) do { _Pragma("unroll") for (int _i = 0; _i < 2; ++_i) \
;         __builtin_amdgcn_global_load_lds((const unsigned*)((const char*)(gbase) + (voff)[_i]), (PG8_LAS unsigned*)(lds + (bufoff) + ldsw + _i * 8192), 16, 0, 0); } while (0)
; #define PG8_WAIT_V(n) asm volatile("s_waitcnt vmcnt(" #n ")" ::: "memory")
; #define PG8_BAR __builtin_amdgcn_s_barrier()
; template <class Epi, class Sched, bool ALIGN_EPI = false, bool SP2 = false>
; __device__ __forceinline__ void gemm_phase(PG8_LAS unsigned char* lds, const Gemm g, const Sched& S, const Epi& E) {
;     ...
;     if constexpr (SP2) {
;         PG8_STAGE(PG8_SB(0, 0), cB, voffB); PG8_STAGE(PG8_SB(0, 1), cB + hstep, voffB); PG8_STAGE(PG8_SA(0, 0), cA, voffA); PG8_STAGE(PG8_SA(0, 1), cA + hstep, voffA);
;         if (wr == 1) PG8_BAR;
;         PG8_WAIT_V(2); PG8_BAR;
;         PG8_STAGE(PG8_SB(1, 0), cB + kstep, voffB); PG8_STAGE(PG8_SA(1, 0), cA + kstep, voffA); PG8_STAGE(PG8_SB(1, 1), cB + hstep + kstep, voffB);
;         PG8_WAIT_V(6); PG8_BAR;
;     } else {
;     __device__ __forceinline__ void operator()(const AccT& acc, const Unit& u, int wr, int wc, int fr_, int fq_) const {
;     ...
;         bf16_t* const QI = (bf16_t*)(ws + WS_QIMG); const float* const ssq_q = (const float*)(ws + WS_SSQ); const float* const rope = (const float*)(ws + WS_ROPE);
;         float ssv[2][4];
; #pragma unroll
;         for (int ai = 0; ai < 2; ++ai)
; #pragma unroll
;             for (int m = 0; m < 4; ++m) ssv[ai][m] = ssq_q[(size_t)ROW_OF(ai, m)];
.LBB0_999:
	s_mov_b64 s[18:19], 0x80
	s_add_i32 m0, s37, 0x18000
	v_lshl_add_u64 v[8:9], v[8:9], 0, s[18:19]
	s_waitcnt vmcnt(2)
	s_barrier
	global_load_lds_dwordx4 v[8:9], off
	v_lshl_add_u64 v[4:5], v[4:5], 0, s[18:19]
	s_add_i32 m0, s37, 0x1a000
	s_add_i32 s42, s37, 0x8000
	global_load_lds_dwordx4 v[4:5], off
	v_lshl_add_u64 v[4:5], v[6:7], 0, s[18:19]
	s_mov_b32 m0, s42
	s_add_i32 s43, s37, 0xa000
	global_load_lds_dwordx4 v[4:5], off
	v_lshl_add_u64 v[4:5], v[10:11], 0, s[18:19]
	s_mov_b32 m0, s43
	v_lshl_add_u64 v[2:3], v[2:3], 0, s[18:19]
	global_load_lds_dwordx4 v[4:5], off
	s_add_i32 m0, s37, 0x1c000
	v_lshl_add_u64 v[0:1], v[0:1], 0, s[18:19]
	global_load_lds_dwordx4 v[2:3], off
	s_add_i32 m0, s37, 0x1e000
	s_lshr_b32 s1, s1, 26
	global_load_lds_dwordx4 v[0:1], off
	s_add_i32 s1, s0, s1
	v_lshlrev_b32_e32 v1, 2, v201
	s_ashr_i32 s44, s1, 6
	v_lshl_or_b32 v0, v201, 6, v238
	s_lshl_b32 s1, s3, 13
	v_and_b32_e32 v1, 32, v1
	v_bitop3_b32 v0, v0, s1, v1 bitop3:0xde
	v_add_u32_e32 v1, v237, v235
	s_and_b32 s2, s2, 3
	s_lshl_b32 s45, s3, 6
	v_mul_lo_u32 v1, s0, v1
	s_cmp_gt_i32 s0, 63
	v_lshlrev_b32_e32 v1, 1, v1
	s_cselect_b64 s[20:21], -1, 0
	s_add_i32 s46, s44, -2
	v_add3_u32 v168, v233, v1, v234
	v_add_u32_e32 v1, v236, v235
	s_cmpk_lt_u32 s11, 0x100
	v_mul_lo_u32 v1, s0, v1
	s_waitcnt vmcnt(6)
	s_cselect_b64 s[22:23], -1, 0
	s_add_u32 s24, s90, 0x100000
	v_lshlrev_b32_e32 v1, 1, v1
	v_lshl_or_b32 v194, s2, 12, v239
	s_addc_u32 s25, s91, 0
	s_lshl_b32 s1, s2, 6
	v_lshl_add_u64 v[170:171], s[12:13], 0, v[168:169]
	v_add3_u32 v168, v233, v1, v234
	s_add_i32 s52, 0, 0x10000
	s_add_i32 s53, 0, 0x14000
	s_or_b32 s47, s1, 0xfffffc00
	s_lshl_b32 s48, s2, 2
	s_ashr_i32 s49, s83, 31
	s_ashr_i32 s50, s80, 31
	v_lshl_add_u64 v[172:173], s[12:13], 0, v[168:169]
	v_mov_b64_e32 v[174:175], 0x300
	v_mov_b64_e32 v[176:177], 0x2ff
	s_movk_i32 s51, 0x61
	v_add_u32_e32 v195, s52, v194
	v_add_u32_e32 v196, s53, v194
	v_add_u32_e32 v197, 0, v0
	v_mov_b32_e32 v198, 0x358637bd
	s_movk_i32 s54, 0x3000
	s_barrier
	v_lshl_add_u32 v253, s10, 8, v201
	v_add_lshl_u32 v253, v253, s45, 2
	global_load_dword v245, v253, s[90:91]
	global_load_dword v246, v253, s[90:91] offset:64
	global_load_dword v247, v253, s[90:91] offset:128
	global_load_dword v248, v253, s[90:91] offset:192
	global_load_dword v249, v253, s[90:91] offset:512
	global_load_dword v250, v253, s[90:91] offset:576
	global_load_dword v251, v253, s[90:91] offset:640
	global_load_dword v252, v253, s[90:91] offset:704
	s_mov_b32 s101, 0
	s_mov_b32 s99, 0
	s_branch .LBB0_1002

; #define PG8_STAGE(bufoff, gbase, voff) do { _Pragma("unroll") for (int _i = 0; _i < 2; ++_i) \
;         __builtin_amdgcn_global_load_lds((const unsigned*)((const char*)(gbase) + (voff)[_i]), (PG8_LAS unsigned*)(lds + (bufoff) + ldsw + _i * 8192), 16, 0, 0); } while (0)
; #define PG8_LDA(dst, b, h) do { _Pragma("unroll") for (int m = 0; m < 4; ++m) _Pragma("unroll") for (int k = 0; k < 2; ++k) dst[m][k] = *(const PG8_LAS bf16x8*)(lds + PG8_SA(b, h) + aoff + m * 2048 + k * 1024); } while (0)
; #define PG8_LDB(dst, b, h) do { _Pragma("unroll") for (int n = 0; n < 2; ++n) _Pragma("unroll") for (int k = 0; k < 2; ++k) dst[n][k] = *(const PG8_LAS bf16x8*)(lds + PG8_SB(b, h) + boff + n * 2048 + k * 1024); } while (0)
; #define PG8_SCHED __builtin_amdgcn_sched_barrier(0)
; template <class Epi, class Sched, bool ALIGN_EPI = false, bool SP2 = false>
; __device__ __forceinline__ void gemm_phase(PG8_LAS unsigned char* lds, const Gemm g, const Sched& S, const Epi& E) {
;     ...
;             const bool last = (t == nt - 2);
;             const char* a1 = cA + (size_t)(t + 1) * kstep;
;             const char* a2 = last ? nA : cA + (size_t)(t + 2) * kstep; const char* b2 = last ? nB : cB + (size_t)(t + 2) * kstep;
;             const char* a3 = a2 + kstep; const char* b3 = b2 + kstep;
;             if (last && has_next) S.a_ready(nxt);
;             if constexpr (SP2) {
;             PG8_LDB(B0, 0, 0); PG8_LDB(B1, 0, 1); PG8_SCHED; PG8_LDA(At, 0, 0); PG8_STAGE(PG8_SA(1, 1), a1 + hstep, voffA);
.LBB0_1008:
	s_waitcnt vmcnt(0)
	s_andn2_b64 vcc, exec, s[20:21]
	s_cbranch_vccnz .LBB0_1011
	s_add_u32 s4, s4, 0x80
	s_addc_u32 s5, s5, 0
	s_add_u32 s11, s6, 0x100
	s_addc_u32 s29, s7, 0
	s_mov_b32 s6, 0
	ds_read_b128 v[128:131], v195
	ds_read_b128 v[132:135], v195 offset:1024
	ds_read_b128 v[136:139], v195 offset:2048
	ds_read_b128 v[140:143], v195 offset:3072
	ds_read_b128 v[144:147], v196
	ds_read_b128 v[148:151], v196 offset:1024
	ds_read_b128 v[152:155], v196 offset:2048
	ds_read_b128 v[156:159], v196 offset:3072
	s_add_i32 s56, s6, 2
	s_add_u32 s57, s4, 0x80
	s_addc_u32 s7, s5, 0
	s_cmp_eq_u32 s46, s6
	s_cselect_b32 s6, s0, s57
	s_cselect_b32 s7, s1, s7
	s_cselect_b32 s59, s27, s29
	s_cselect_b32 s58, s26, s11
	v_lshl_add_u64 v[218:219], s[4:5], 0, v[170:171]
	s_add_i32 m0, s37, 0xc000
	ds_read_b128 v[178:181], v197
	ds_read_b128 v[182:185], v197 offset:1024
	ds_read_b128 v[186:189], v197 offset:2048
	ds_read_b128 v[190:193], v197 offset:3072
	ds_read_b128 v[202:205], v197 offset:4096
	ds_read_b128 v[206:209], v197 offset:5120
	ds_read_b128 v[210:213], v197 offset:6144
	ds_read_b128 v[214:217], v197 offset:7168
	s_cmp_lg_u32 s101, 0
	s_cbranch_scc1 .Ly1_skip_5
	global_load_lds_dwordx4 v[218:219], off
	v_lshl_add_u64 v[218:219], s[4:5], 0, v[172:173]
	s_add_i32 m0, s37, 0xe000
	s_nop 0
	global_load_lds_dwordx4 v[218:219], off

; #define PG8_STAGE(bufoff, gbase, voff) do { _Pragma("unroll") for (int _i = 0; _i < 2; ++_i) \
;         __builtin_amdgcn_global_load_lds((const unsigned*)((const char*)(gbase) + (voff)[_i]), (PG8_LAS unsigned*)(lds + (bufoff) + ldsw + _i * 8192), 16, 0, 0); } while (0)
; #define PG8_LDA(dst, b, h) do { _Pragma("unroll") for (int m = 0; m < 4; ++m) _Pragma("unroll") for (int k = 0; k < 2; ++k) dst[m][k] = *(const PG8_LAS bf16x8*)(lds + PG8_SA(b, h) + aoff + m * 2048 + k * 1024); } while (0)
; #define PG8_LDB(dst, b, h) do { _Pragma("unroll") for (int n = 0; n < 2; ++n) _Pragma("unroll") for (int k = 0; k < 2; ++k) dst[n][k] = *(const PG8_LAS bf16x8*)(lds + PG8_SB(b, h) + boff + n * 2048 + k * 1024); } while (0)
; #define PG8_MMA(ai, bj, At, Bt) do { __builtin_amdgcn_s_setprio(1); _Pragma("unroll") for (int m = 0; m < 4; ++m) _Pragma("unroll") for (int n = 0; n < 2; ++n) _Pragma("unroll") for (int k = 0; k < 2; ++k) \
;         acc[ai][bj][m][n] = __builtin_amdgcn_mfma_f32_16x16x32_bf16(Bt[n][k], At[m][k], acc[ai][bj][m][n], 0, 0, 0); __builtin_amdgcn_s_setprio(0); } while (0)
; #define PG8_WAIT_V(n) asm volatile("s_waitcnt vmcnt(" #n ")" ::: "memory")
; #define PG8_WAIT_L(n) asm volatile("s_waitcnt lgkmcnt(" #n ")" ::: "memory")
; #define PG8_BAR __builtin_amdgcn_s_barrier()
; #define PG8_SCHED __builtin_amdgcn_sched_barrier(0)
; template <class Epi, class Sched, bool ALIGN_EPI = false, bool SP2 = false>
; __device__ __forceinline__ void gemm_phase(PG8_LAS unsigned char* lds, const Gemm g, const Sched& S, const Epi& E) {
;     ...
;             PG8_WAIT_V(8); PG8_WAIT_L(0); PG8_BAR; PG8_MMA(0, 0, At, B0); PG8_MMA(0, 1, At, B1); PG8_BAR; PG8_SCHED;
;             PG8_LDA(At, 0, 1); PG8_STAGE(PG8_SB(0, 0), b2, voffB); PG8_STAGE(PG8_SB(0, 1), b2 + hstep, voffB); PG8_STAGE(PG8_SA(0, 0), a2, voffA);
;             PG8_WAIT_V(8); PG8_WAIT_L(0); PG8_BAR; PG8_MMA(1, 0, At, B0); PG8_MMA(1, 1, At, B1); PG8_BAR; PG8_SCHED;
;             PG8_LDB(B0, 1, 0); PG8_LDB(B1, 1, 1); PG8_SCHED; PG8_LDA(At, 1, 0); PG8_STAGE(PG8_SA(0, 1), a2 + hstep, voffA);
;             PG8_WAIT_V(8); PG8_WAIT_L(0); PG8_BAR; PG8_MMA(0, 0, At, B0); PG8_MMA(0, 1, At, B1); PG8_BAR; PG8_SCHED;
.Lwj_5_1:
	s_waitcnt lgkmcnt(0)
	s_barrier
	s_setprio 1
	s_waitcnt lgkmcnt(0)
	v_mfma_f32_16x16x32_bf16 v[60:63], v[128:131], v[178:181], 0
	v_mfma_f32_16x16x32_bf16 v[56:59], v[136:139], v[178:181], 0
	v_mfma_f32_16x16x32_bf16 v[44:47], v[128:131], v[186:189], 0
	v_mfma_f32_16x16x32_bf16 v[40:43], v[136:139], v[186:189], 0
	v_mfma_f32_16x16x32_bf16 v[28:31], v[128:131], v[202:205], 0
	v_mfma_f32_16x16x32_bf16 v[24:27], v[136:139], v[202:205], 0
	v_mfma_f32_16x16x32_bf16 v[12:15], v[128:131], v[210:213], 0
	v_mfma_f32_16x16x32_bf16 v[8:11], v[136:139], v[210:213], 0
	v_mfma_f32_16x16x32_bf16 v[60:63], v[132:135], v[182:185], v[60:63]
	v_mfma_f32_16x16x32_bf16 v[56:59], v[140:143], v[182:185], v[56:59]
	v_mfma_f32_16x16x32_bf16 v[44:47], v[132:135], v[190:193], v[44:47]
	v_mfma_f32_16x16x32_bf16 v[40:43], v[140:143], v[190:193], v[40:43]
	v_mfma_f32_16x16x32_bf16 v[28:31], v[132:135], v[206:209], v[28:31]
	v_mfma_f32_16x16x32_bf16 v[24:27], v[140:143], v[206:209], v[24:27]
	v_mfma_f32_16x16x32_bf16 v[12:15], v[132:135], v[214:217], v[12:15]
	v_mfma_f32_16x16x32_bf16 v[8:11], v[140:143], v[214:217], v[8:11]
	s_setprio 0
	s_setprio 1
	v_mfma_f32_16x16x32_bf16 v[52:55], v[144:147], v[178:181], 0
	v_mfma_f32_16x16x32_bf16 v[48:51], v[152:155], v[178:181], 0
	v_mfma_f32_16x16x32_bf16 v[36:39], v[144:147], v[186:189], 0
	v_mfma_f32_16x16x32_bf16 v[32:35], v[152:155], v[186:189], 0
	v_mfma_f32_16x16x32_bf16 v[20:23], v[144:147], v[202:205], 0
	v_mfma_f32_16x16x32_bf16 v[16:19], v[152:155], v[202:205], 0
	v_mfma_f32_16x16x32_bf16 v[4:7], v[144:147], v[210:213], 0
	v_mfma_f32_16x16x32_bf16 v[0:3], v[152:155], v[210:213], 0
	v_mfma_f32_16x16x32_bf16 v[52:55], v[148:151], v[182:185], v[52:55]
	v_mfma_f32_16x16x32_bf16 v[48:51], v[156:159], v[182:185], v[48:51]
	v_mfma_f32_16x16x32_bf16 v[36:39], v[148:151], v[190:193], v[36:39]
	v_mfma_f32_16x16x32_bf16 v[32:35], v[156:159], v[190:193], v[32:35]
	v_mfma_f32_16x16x32_bf16 v[20:23], v[148:151], v[206:209], v[20:23]
	v_mfma_f32_16x16x32_bf16 v[16:19], v[156:159], v[206:209], v[16:19]
	v_mfma_f32_16x16x32_bf16 v[4:7], v[148:151], v[214:217], v[4:7]
	v_mfma_f32_16x16x32_bf16 v[0:3], v[156:159], v[214:217], v[0:3]
	s_setprio 0
	s_barrier
	s_add_i32 s57, 0, 0x18000
	s_add_i32 s58, 0, 0x1c000
	v_add_u32_e32 v140, s57, v194
	v_add_u32_e32 v156, s58, v194
	ds_read_b128 v[128:131], v140
	ds_read_b128 v[132:135], v140 offset:1024
	ds_read_b128 v[136:139], v140 offset:2048
	ds_read_b128 v[140:143], v140 offset:3072
	ds_read_b128 v[144:147], v156
	ds_read_b128 v[148:151], v156 offset:1024
	ds_read_b128 v[152:155], v156 offset:2048
	ds_read_b128 v[156:159], v156 offset:3072
	s_add_u32 s6, s6, s12
	s_addc_u32 s7, s7, s13
	s_mov_b32 m0, s39
	v_lshl_add_u64 v[230:231], s[6:7], 0, v[160:161]
	ds_read_b128 v[178:181], v197 offset:32768
	ds_read_b128 v[182:185], v197 offset:33792
	ds_read_b128 v[186:189], v197 offset:34816
	ds_read_b128 v[190:193], v197 offset:35840
	ds_read_b128 v[202:205], v197 offset:36864
	ds_read_b128 v[206:209], v197 offset:37888
	ds_read_b128 v[210:213], v197 offset:38912
	ds_read_b128 v[214:217], v197 offset:39936
	global_load_lds_dwordx4 v[230:231], off
	v_lshl_add_u64 v[230:231], s[6:7], 0, v[164:165]
	s_mov_b32 m0, s40
	s_nop 0
	global_load_lds_dwordx4 v[230:231], off
	s_cmp_eq_u32 s99, 0
	s_cbranch_scc1 .Lw8_5_2
	s_waitcnt vmcnt(16)
	s_branch .Lwj_5_2

; #define PG8_STAGE(bufoff, gbase, voff) do { _Pragma("unroll") for (int _i = 0; _i < 2; ++_i) \
;         __builtin_amdgcn_global_load_lds((const unsigned*)((const char*)(gbase) + (voff)[_i]), (PG8_LAS unsigned*)(lds + (bufoff) + ldsw + _i * 8192), 16, 0, 0); } while (0)
; #define PG8_LDA(dst, b, h) do { _Pragma("unroll") for (int m = 0; m < 4; ++m) _Pragma("unroll") for (int k = 0; k < 2; ++k) dst[m][k] = *(const PG8_LAS bf16x8*)(lds + PG8_SA(b, h) + aoff + m * 2048 + k * 1024); } while (0)
; #define PG8_LDB(dst, b, h) do { _Pragma("unroll") for (int n = 0; n < 2; ++n) _Pragma("unroll") for (int k = 0; k < 2; ++k) dst[n][k] = *(const PG8_LAS bf16x8*)(lds + PG8_SB(b, h) + boff + n * 2048 + k * 1024); } while (0)
; #define PG8_MMA(ai, bj, At, Bt) do { __builtin_amdgcn_s_setprio(1); _Pragma("unroll") for (int m = 0; m < 4; ++m) _Pragma("unroll") for (int n = 0; n < 2; ++n) _Pragma("unroll") for (int k = 0; k < 2; ++k) \
;         acc[ai][bj][m][n] = __builtin_amdgcn_mfma_f32_16x16x32_bf16(Bt[n][k], At[m][k], acc[ai][bj][m][n], 0, 0, 0); __builtin_amdgcn_s_setprio(0); } while (0)
; #define PG8_WAIT_V(n) asm volatile("s_waitcnt vmcnt(" #n ")" ::: "memory")
; #define PG8_WAIT_L(n) asm volatile("s_waitcnt lgkmcnt(" #n ")" ::: "memory")
; #define PG8_BAR __builtin_amdgcn_s_barrier()
; #define PG8_SCHED __builtin_amdgcn_sched_barrier(0)
; template <class Epi, class Sched, bool ALIGN_EPI = false, bool SP2 = false>
; __device__ __forceinline__ void gemm_phase(PG8_LAS unsigned char* lds, const Gemm g, const Sched& S, const Epi& E) {
;     ...
;             PG8_WAIT_V(8); PG8_WAIT_L(0); PG8_BAR; PG8_MMA(1, 0, At, B0); PG8_MMA(1, 1, At, B1); PG8_BAR; PG8_SCHED;
;             PG8_LDB(B0, 1, 0); PG8_LDB(B1, 1, 1); PG8_SCHED; PG8_LDA(At, 1, 0); PG8_STAGE(PG8_SA(0, 1), a2 + hstep, voffA);
;             PG8_WAIT_V(8); PG8_WAIT_L(0); PG8_BAR; PG8_MMA(0, 0, At, B0); PG8_MMA(0, 1, At, B1); PG8_BAR; PG8_SCHED;
;             PG8_LDA(At, 1, 1); PG8_STAGE(PG8_SB(1, 0), b3, voffB); PG8_STAGE(PG8_SB(1, 1), b3 + hstep, voffB); PG8_STAGE(PG8_SA(1, 0), a3, voffA);
;             PG8_WAIT_V(8); PG8_WAIT_L(0); PG8_BAR; PG8_MMA(1, 0, At, B0); PG8_MMA(1, 1, At, B1); PG8_BAR; PG8_SCHED;
.Lwj_5_2:
	s_waitcnt lgkmcnt(0)
	s_barrier
	s_setprio 1
	s_waitcnt lgkmcnt(0)
	v_mfma_f32_16x16x32_bf16 v[124:127], v[128:131], v[178:181], v[124:127]
	v_mfma_f32_16x16x32_bf16 v[120:123], v[136:139], v[178:181], v[120:123]
	v_mfma_f32_16x16x32_bf16 v[108:111], v[128:131], v[186:189], v[108:111]
	v_mfma_f32_16x16x32_bf16 v[104:107], v[136:139], v[186:189], v[104:107]
	v_mfma_f32_16x16x32_bf16 v[92:95], v[128:131], v[202:205], v[92:95]
	v_mfma_f32_16x16x32_bf16 v[88:91], v[136:139], v[202:205], v[88:91]
	v_mfma_f32_16x16x32_bf16 v[76:79], v[128:131], v[210:213], v[76:79]
	v_mfma_f32_16x16x32_bf16 v[72:75], v[136:139], v[210:213], v[72:75]
	v_mfma_f32_16x16x32_bf16 v[124:127], v[132:135], v[182:185], v[124:127]
	v_mfma_f32_16x16x32_bf16 v[120:123], v[140:143], v[182:185], v[120:123]
	v_mfma_f32_16x16x32_bf16 v[108:111], v[132:135], v[190:193], v[108:111]
	v_mfma_f32_16x16x32_bf16 v[104:107], v[140:143], v[190:193], v[104:107]
	v_mfma_f32_16x16x32_bf16 v[92:95], v[132:135], v[206:209], v[92:95]
	v_mfma_f32_16x16x32_bf16 v[88:91], v[140:143], v[206:209], v[88:91]
	v_mfma_f32_16x16x32_bf16 v[76:79], v[132:135], v[214:217], v[76:79]
	v_mfma_f32_16x16x32_bf16 v[72:75], v[140:143], v[214:217], v[72:75]
	s_setprio 0
	s_setprio 1
	v_mfma_f32_16x16x32_bf16 v[116:119], v[144:147], v[178:181], v[116:119]
	v_mfma_f32_16x16x32_bf16 v[112:115], v[152:155], v[178:181], v[112:115]
	v_mfma_f32_16x16x32_bf16 v[100:103], v[144:147], v[186:189], v[100:103]
	v_mfma_f32_16x16x32_bf16 v[96:99], v[152:155], v[186:189], v[96:99]
	v_mfma_f32_16x16x32_bf16 v[84:87], v[144:147], v[202:205], v[84:87]
	v_mfma_f32_16x16x32_bf16 v[80:83], v[152:155], v[202:205], v[80:83]
	v_mfma_f32_16x16x32_bf16 v[68:71], v[144:147], v[210:213], v[68:71]
	v_mfma_f32_16x16x32_bf16 v[64:67], v[152:155], v[210:213], v[64:67]
	v_mfma_f32_16x16x32_bf16 v[116:119], v[148:151], v[182:185], v[116:119]
	v_mfma_f32_16x16x32_bf16 v[112:115], v[156:159], v[182:185], v[112:115]
	v_mfma_f32_16x16x32_bf16 v[100:103], v[148:151], v[190:193], v[100:103]
	v_mfma_f32_16x16x32_bf16 v[96:99], v[156:159], v[190:193], v[96:99]
	v_mfma_f32_16x16x32_bf16 v[84:87], v[148:151], v[206:209], v[84:87]
	v_mfma_f32_16x16x32_bf16 v[80:83], v[156:159], v[206:209], v[80:83]
	v_mfma_f32_16x16x32_bf16 v[68:71], v[148:151], v[214:217], v[68:71]
	v_mfma_f32_16x16x32_bf16 v[64:67], v[156:159], v[214:217], v[64:67]
	s_setprio 0
	s_barrier
	s_add_i32 s6, s57, s36
	v_lshl_add_u64 v[218:219], v[218:219], 0, s[18:19]
	s_mov_b32 m0, s6
	ds_read_b128 v[178:181], v197 offset:49152
	ds_read_b128 v[182:185], v197 offset:50176
	ds_read_b128 v[186:189], v197 offset:51200
	ds_read_b128 v[190:193], v197 offset:52224
	ds_read_b128 v[202:205], v197 offset:53248
	ds_read_b128 v[206:209], v197 offset:54272
	ds_read_b128 v[210:213], v197 offset:55296
	ds_read_b128 v[214:217], v197 offset:56320
	global_load_lds_dwordx4 v[218:219], off
	v_lshl_add_u64 v[218:219], v[220:221], 0, s[18:19]
	s_add_i32 m0, s6, 0x2000
	s_add_i32 s6, s58, s36
	global_load_lds_dwordx4 v[218:219], off
	v_lshl_add_u64 v[218:219], v[222:223], 0, s[18:19]
	s_mov_b32 m0, s6
	s_nop 0
	global_load_lds_dwordx4 v[218:219], off
	v_lshl_add_u64 v[218:219], v[224:225], 0, s[18:19]
	s_add_i32 m0, s6, 0x2000
	s_nop 0
	global_load_lds_dwordx4 v[218:219], off
	v_lshl_add_u64 v[218:219], v[226:227], 0, s[18:19]
	s_mov_b32 m0, s42
	s_nop 0
	global_load_lds_dwordx4 v[218:219], off
	v_lshl_add_u64 v[218:219], v[228:229], 0, s[18:19]
	s_mov_b32 m0, s43
	s_nop 0
	global_load_lds_dwordx4 v[218:219], off
	s_waitcnt vmcnt(8)
	s_waitcnt lgkmcnt(0)
	s_barrier
	s_setprio 1
	s_waitcnt lgkmcnt(0)
	v_mfma_f32_16x16x32_bf16 v[60:63], v[128:131], v[178:181], v[60:63]
	v_mfma_f32_16x16x32_bf16 v[56:59], v[136:139], v[178:181], v[56:59]
	v_mfma_f32_16x16x32_bf16 v[44:47], v[128:131], v[186:189], v[44:47]
	v_mfma_f32_16x16x32_bf16 v[40:43], v[136:139], v[186:189], v[40:43]
	v_mfma_f32_16x16x32_bf16 v[28:31], v[128:131], v[202:205], v[28:31]
	v_mfma_f32_16x16x32_bf16 v[24:27], v[136:139], v[202:205], v[24:27]
	v_mfma_f32_16x16x32_bf16 v[12:15], v[128:131], v[210:213], v[12:15]
	v_mfma_f32_16x16x32_bf16 v[8:11], v[136:139], v[210:213], v[8:11]
	v_mfma_f32_16x16x32_bf16 v[60:63], v[132:135], v[182:185], v[60:63]
	v_mfma_f32_16x16x32_bf16 v[56:59], v[140:143], v[182:185], v[56:59]
	v_mfma_f32_16x16x32_bf16 v[44:47], v[132:135], v[190:193], v[44:47]
	v_mfma_f32_16x16x32_bf16 v[40:43], v[140:143], v[190:193], v[40:43]
	v_mfma_f32_16x16x32_bf16 v[28:31], v[132:135], v[206:209], v[28:31]
	v_mfma_f32_16x16x32_bf16 v[24:27], v[140:143], v[206:209], v[24:27]
	v_mfma_f32_16x16x32_bf16 v[12:15], v[132:135], v[214:217], v[12:15]
	v_mfma_f32_16x16x32_bf16 v[8:11], v[140:143], v[214:217], v[8:11]
	s_setprio 0
	s_setprio 1
	v_mfma_f32_16x16x32_bf16 v[52:55], v[144:147], v[178:181], v[52:55]
	v_mfma_f32_16x16x32_bf16 v[48:51], v[152:155], v[178:181], v[48:51]
	v_mfma_f32_16x16x32_bf16 v[36:39], v[144:147], v[186:189], v[36:39]
	v_mfma_f32_16x16x32_bf16 v[32:35], v[152:155], v[186:189], v[32:35]
	v_mfma_f32_16x16x32_bf16 v[20:23], v[144:147], v[202:205], v[20:23]
	v_mfma_f32_16x16x32_bf16 v[16:19], v[152:155], v[202:205], v[16:19]
	v_mfma_f32_16x16x32_bf16 v[4:7], v[144:147], v[210:213], v[4:7]
	v_mfma_f32_16x16x32_bf16 v[0:3], v[152:155], v[210:213], v[0:3]
	v_mfma_f32_16x16x32_bf16 v[52:55], v[148:151], v[182:185], v[52:55]
	v_mfma_f32_16x16x32_bf16 v[48:51], v[156:159], v[182:185], v[48:51]
	v_mfma_f32_16x16x32_bf16 v[36:39], v[148:151], v[190:193], v[36:39]
	v_mfma_f32_16x16x32_bf16 v[32:35], v[156:159], v[190:193], v[32:35]
	v_mfma_f32_16x16x32_bf16 v[20:23], v[148:151], v[206:209], v[20:23]
	v_mfma_f32_16x16x32_bf16 v[16:19], v[156:159], v[206:209], v[16:19]
	v_mfma_f32_16x16x32_bf16 v[4:7], v[148:151], v[214:217], v[4:7]
	v_mfma_f32_16x16x32_bf16 v[0:3], v[156:159], v[214:217], v[0:3]
	s_setprio 0
	s_barrier
	s_add_u32 s4, s4, 0x100
	s_addc_u32 s5, s5, 0
	s_add_u32 s11, s11, 0x100
	s_addc_u32 s29, s29, 0
	s_cmp_ge_i32 s56, s44
	s_mov_b32 s6, s56
	s_cbranch_scc1 .LBB0_1011

; #define PG8_STAGE(bufoff, gbase, voff) do { _Pragma("unroll") for (int _i = 0; _i < 2; ++_i) \
;         __builtin_amdgcn_global_load_lds((const unsigned*)((const char*)(gbase) + (voff)[_i]), (PG8_LAS unsigned*)(lds + (bufoff) + ldsw + _i * 8192), 16, 0, 0); } while (0)
; #define PG8_LDA(dst, b, h) do { _Pragma("unroll") for (int m = 0; m < 4; ++m) _Pragma("unroll") for (int k = 0; k < 2; ++k) dst[m][k] = *(const PG8_LAS bf16x8*)(lds + PG8_SA(b, h) + aoff + m * 2048 + k * 1024); } while (0)
; #define PG8_LDB(dst, b, h) do { _Pragma("unroll") for (int n = 0; n < 2; ++n) _Pragma("unroll") for (int k = 0; k < 2; ++k) dst[n][k] = *(const PG8_LAS bf16x8*)(lds + PG8_SB(b, h) + boff + n * 2048 + k * 1024); } while (0)
; #define PG8_SCHED __builtin_amdgcn_sched_barrier(0)
; template <class Epi, class Sched, bool ALIGN_EPI = false, bool SP2 = false>
; __device__ __forceinline__ void gemm_phase(PG8_LAS unsigned char* lds, const Gemm g, const Sched& S, const Epi& E) {
;     ...
;             const char* a1 = cA + (size_t)(t + 1) * kstep;
;             const char* a2 = last ? nA : cA + (size_t)(t + 2) * kstep; const char* b2 = last ? nB : cB + (size_t)(t + 2) * kstep;
;             const char* a3 = a2 + kstep; const char* b3 = b2 + kstep;
;             if (last && has_next) S.a_ready(nxt);
;             if constexpr (SP2) {
;             PG8_LDB(B0, 0, 0); PG8_LDB(B1, 0, 1); PG8_SCHED; PG8_LDA(At, 0, 0); PG8_STAGE(PG8_SA(1, 1), a1 + hstep, voffA);
;     __device__ __forceinline__ void operator()(const AccT& acc, const Unit& u, int wr, int wc, int fr_, int fq_) const {
;     ...
;         float ssv[2][4];
; #pragma unroll
;         for (int ai = 0; ai < 2; ++ai)
; #pragma unroll
;             for (int m = 0; m < 4; ++m) ssv[ai][m] = ssq_q[(size_t)ROW_OF(ai, m)];
; #pragma unroll
;         for (int aim = 0; aim < 4; ++aim) { const int ai = aim >> 1;
;             f32x4 cs[4][4];
;             if (pn >= 4) {
; #pragma unroll
;                 for (int m = 2 * (aim & 1); m < 2 * (aim & 1) + 2; ++m) { const f32x4* cp = (const f32x4*)(rope + (size_t)ROW_OF(ai, m) * 64 + 16 * fq);
; #pragma unroll
;                     for (int j = 0; j < 4; ++j) cs[m][j] = cp[j]; }
.Lq_skip:
	s_mov_b32 s99, 1
	v_lshl_add_u64 v[218:219], s[0:1], 0, v[170:171]
	v_lshl_add_u64 v[218:219], v[218:219], 0, 64
	v_lshl_add_u64 v[218:219], v[218:219], 0, 64
	s_add_i32 m0, s37, 0xc000
	s_mov_b32 s101, 1
	global_load_lds_dwordx4 v[218:219], off
	v_lshl_add_u64 v[218:219], s[0:1], 0, v[172:173]
	v_lshl_add_u64 v[218:219], v[218:219], 0, 64
	v_lshl_add_u64 v[218:219], v[218:219], 0, 64
	s_add_i32 m0, s37, 0xe000
	s_nop 0
	global_load_lds_dwordx4 v[218:219], off
	s_lshl_b32 s4, s10, 8
	v_mov_b32_e32 v184, v232
	v_mov_b32_e32 v185, v201
	s_add_i32 s4, s4, s45
	s_cmp_gt_i32 s28, 3
	v_add_u32_e32 v188, s4, v185
	v_ashrrev_i32_e32 v189, 31, v188
	v_lshl_add_u64 v[128:129], v[188:189], 2, s[90:91]
	v_mov_b32_e32 v179, v245
	v_mov_b32_e32 v192, v246
	v_mov_b32_e32 v206, v247
	v_mov_b32_e32 v205, v248
	v_mov_b32_e32 v204, v249
	v_mov_b32_e32 v203, v250
	v_mov_b32_e32 v202, v251
	v_mov_b32_e32 v199, v252
	v_lshlrev_b32_e32 v128, 4, v184
	v_add_u32_e32 v190, 16, v188
	v_ashrrev_i32_e32 v129, 31, v128
	v_ashrrev_i32_e32 v191, 31, v190
	s_cselect_b64 s[10:11], -1, 0
	s_cmp_lt_i32 s28, 4
	v_lshl_add_u64 v[186:187], v[128:129], 2, s[24:25]
	s_cbranch_scc1 .LBB0_1015
	v_lshlrev_b64 v[128:129], 8, v[188:189]
	v_lshl_add_u64 v[128:129], v[186:187], 0, v[128:129]
	global_load_dwordx4 v[144:147], v[128:129], off offset:48
	global_load_dwordx4 v[148:151], v[128:129], off offset:32
	global_load_dwordx4 v[152:155], v[128:129], off offset:16
	global_load_dwordx4 v[156:159], v[128:129], off
	v_lshlrev_b64 v[128:129], 8, v[190:191]
	v_lshl_add_u64 v[140:141], v[186:187], 0, v[128:129]
	global_load_dwordx4 v[128:131], v[140:141], off offset:48
	global_load_dwordx4 v[132:135], v[140:141], off offset:32
	global_load_dwordx4 v[136:139], v[140:141], off offset:16
	s_nop 0
	global_load_dwordx4 v[140:143], v[140:141], off

; #define PG8_STAGE(bufoff, gbase, voff) do { _Pragma("unroll") for (int _i = 0; _i < 2; ++_i) \
;         __builtin_amdgcn_global_load_lds((const unsigned*)((const char*)(gbase) + (voff)[_i]), (PG8_LAS unsigned*)(lds + (bufoff) + ldsw + _i * 8192), 16, 0, 0); } while (0)
; #define PG8_WAIT_V(n) asm volatile("s_waitcnt vmcnt(" #n ")" ::: "memory")
; #define PG8_BAR __builtin_amdgcn_s_barrier()
; template <class Epi, class Sched, bool ALIGN_EPI = false, bool SP2 = false>
; __device__ __forceinline__ void gemm_phase(PG8_LAS unsigned char* lds, const Gemm g, const Sched& S, const Epi& E) {
;     const int tid = threadIdx.x, wid = __builtin_amdgcn_readfirstlane(tid >> 6), lane = tid & 63, wr = wid >> 2, wc = wid & 3, fr = lane & 15, fq = lane >> 4;
;     int Kv_ = g.K; asm volatile("" : "+s"(Kv_)); const int K = Kv_, nt = K / BK;
;     unsigned voffA[2], voffB[2];
; #pragma unroll
;     for (int i = 0; i < 2; ++i) { int R, C; stage_rc(tid * 16 + i * 8192, R, C); const int Rb = Epi::PERM ? ((R & ~31) + perm32(R & 31)) : R;
;         voffA[i] = (unsigned)(R * K + C) * 2u; voffB[i] = (unsigned)(Rb * K + C) * 2u; }
;     const size_t kstep = (size_t)(BK * 2);
;     const size_t hstep = (size_t)HALF * K * 2;
;     const size_t tstep = 2 * hstep;
;     const unsigned ldsw = (unsigned)wid * 1024u;
;     const int aoff = lds_byte(wr * 64 + fr, fq * 8), boff = lds_byte(wc * 32 + fr, fq * 8);
;     ...
;         PG8_STAGE(PG8_SB(1, 0), cB + kstep, voffB); PG8_STAGE(PG8_SA(1, 0), cA + kstep, voffA); PG8_STAGE(PG8_SB(1, 1), cB + hstep + kstep, voffB);
;         PG8_WAIT_V(6); PG8_BAR;
.LBB0_1382:
	s_mov_b64 s[12:13], 0x80
	s_add_i32 m0, s30, 0x18000
	v_lshl_add_u64 v[8:9], v[8:9], 0, s[12:13]
	s_waitcnt vmcnt(2)
	s_barrier
	global_load_lds_dwordx4 v[8:9], off
	v_lshl_add_u64 v[4:5], v[4:5], 0, s[12:13]
	s_add_i32 m0, s30, 0x1a000
	s_add_i32 s36, s30, 0x8000
	global_load_lds_dwordx4 v[4:5], off
	v_lshl_add_u64 v[4:5], v[6:7], 0, s[12:13]
	s_mov_b32 m0, s36
	s_add_i32 s37, s30, 0xa000
	global_load_lds_dwordx4 v[4:5], off
	v_lshl_add_u64 v[4:5], v[10:11], 0, s[12:13]
	s_mov_b32 m0, s37
	v_lshl_add_u64 v[2:3], v[2:3], 0, s[12:13]
	global_load_lds_dwordx4 v[4:5], off
	s_add_i32 m0, s30, 0x1c000
	v_lshl_add_u64 v[0:1], v[0:1], 0, s[12:13]
	global_load_lds_dwordx4 v[2:3], off
	s_add_i32 m0, s30, 0x1e000
	v_bfe_u32 v145, v200, 4, 2
	global_load_lds_dwordx4 v[0:1], off
	s_lshr_b32 s1, s1, 26
	v_and_b32_e32 v144, 15, v200
	s_add_i32 s1, s0, s1
	v_lshlrev_b32_e32 v0, 4, v145
	v_lshlrev_b32_e32 v2, 2, v200
	s_ashr_i32 s38, s1, 6
	v_lshl_or_b32 v1, v144, 6, v0
	s_lshl_b32 s1, s3, 13
	v_and_b32_e32 v2, 32, v2
	v_bitop3_b32 v3, v1, s1, v2 bitop3:0xde
	s_lshl_b32 s1, s14, 5
	s_sext_i32_i8 s49, s2
	s_and_b32 s1, s1, 0x60
	v_lshlrev_b32_e32 v1, 6, v200
	s_movk_i32 s2, 0x3c0
	s_lshl_b32 s39, s3, 6
	v_and_or_b32 v0, v1, s2, v0
	s_lshl_b32 s2, s1, 7
	v_bitop3_b32 v146, s2, v0, v2 bitop3:0xf6
	s_cmp_gt_i32 s0, 63
	v_add_u32_e32 v0, v15, v14
	s_cselect_b64 s[14:15], -1, 0
	s_add_i32 s40, s38, -2
	v_mul_lo_u32 v0, s0, v0
	s_cmpk_lt_u32 s16, 0x100
	v_lshlrev_b32_e32 v0, 1, v0
	s_cselect_b64 s[16:17], -1, 0
	s_lshl_b32 s1, s1, 1
	v_add3_u32 v0, v12, v0, v13
	v_mov_b32_e32 v1, v131
	s_add_u32 s1, s90, s1
	v_lshl_add_u64 v[136:137], s[6:7], 0, v[0:1]
	v_add_u32_e32 v0, v16, v14
	s_addc_u32 s2, s91, 0
	v_mul_lo_u32 v0, s0, v0
	s_waitcnt vmcnt(6)
	s_add_u32 s41, s1, 0x9000000
	v_lshlrev_b32_e32 v0, 1, v0
	s_addc_u32 s42, s2, 0
	v_add3_u32 v0, v12, v0, v13
	s_add_i32 s44, 0, 0x10000
	s_add_i32 s45, 0, 0x14000
	s_ashr_i32 s43, s83, 31
	v_lshl_add_u64 v[138:139], s[6:7], 0, v[0:1]
	v_mov_b64_e32 v[140:141], 0x200
	v_mov_b64_e32 v[142:143], 0x1ff
	v_add_u32_e32 v147, s44, v146
	v_add_u32_e32 v148, s45, v146
	v_add_u32_e32 v149, 0, v3
	s_barrier
	s_mov_b32 s101, 0
	s_mov_b32 s99, 0
	s_branch .LBB0_1385

; #define PG8_STAGE(bufoff, gbase, voff) do { _Pragma("unroll") for (int _i = 0; _i < 2; ++_i) \
;         __builtin_amdgcn_global_load_lds((const unsigned*)((const char*)(gbase) + (voff)[_i]), (PG8_LAS unsigned*)(lds + (bufoff) + ldsw + _i * 8192), 16, 0, 0); } while (0)
; #define PG8_LDA(dst, b, h) do { _Pragma("unroll") for (int m = 0; m < 4; ++m) _Pragma("unroll") for (int k = 0; k < 2; ++k) dst[m][k] = *(const PG8_LAS bf16x8*)(lds + PG8_SA(b, h) + aoff + m * 2048 + k * 1024); } while (0)
; #define PG8_LDB(dst, b, h) do { _Pragma("unroll") for (int n = 0; n < 2; ++n) _Pragma("unroll") for (int k = 0; k < 2; ++k) dst[n][k] = *(const PG8_LAS bf16x8*)(lds + PG8_SB(b, h) + boff + n * 2048 + k * 1024); } while (0)
; #define PG8_SCHED __builtin_amdgcn_sched_barrier(0)
; template <class Epi, class Sched, bool ALIGN_EPI = false, bool SP2 = false>
; __device__ __forceinline__ void gemm_phase(PG8_LAS unsigned char* lds, const Gemm g, const Sched& S, const Epi& E) {
;     ...
;         for (int t = 0; t < nt; t += 2) {
;             if constexpr (Epi::HAS_MID) { if (t == Epi::MID_T) E.mid(acc, cur, wr, wc, fr, fq); }
;             const bool last = (t == nt - 2);
;             const char* a1 = cA + (size_t)(t + 1) * kstep;
;             const char* a2 = last ? nA : cA + (size_t)(t + 2) * kstep; const char* b2 = last ? nB : cB + (size_t)(t + 2) * kstep;
;             const char* a3 = a2 + kstep; const char* b3 = b2 + kstep;
;             if (last && has_next) S.a_ready(nxt);
;             if constexpr (SP2) {
;             PG8_LDB(B0, 0, 0); PG8_LDB(B1, 0, 1); PG8_SCHED; PG8_LDA(At, 0, 0); PG8_STAGE(PG8_SA(1, 1), a1 + hstep, voffA);
.LBB0_1395:
	s_andn2_b64 vcc, exec, s[14:15]
	s_cbranch_vccnz .LBB0_1398
	s_add_u32 s20, s20, 0x80
	s_addc_u32 s21, s21, 0
	s_add_u32 s50, s22, 0x100
	s_addc_u32 s51, s23, 0
	s_mov_b32 s22, 0
	ds_read_b128 v[150:153], v147
	ds_read_b128 v[154:157], v147 offset:1024
	ds_read_b128 v[158:161], v147 offset:2048
	ds_read_b128 v[162:165], v147 offset:3072
	ds_read_b128 v[166:169], v148
	ds_read_b128 v[170:173], v148 offset:1024
	ds_read_b128 v[174:177], v148 offset:2048
	ds_read_b128 v[178:181], v148 offset:3072
	s_add_i32 s52, s22, 2
	s_add_u32 s53, s20, 0x80
	s_addc_u32 s23, s21, 0
	s_cmp_eq_u32 s40, s22
	s_cselect_b32 s22, s0, s53
	s_cselect_b32 s23, s1, s23
	s_cselect_b32 s55, s19, s51
	s_cselect_b32 s54, s18, s50
	v_lshl_add_u64 v[198:199], s[20:21], 0, v[136:137]
	s_add_i32 m0, s30, 0xc000
	ds_read_b128 v[182:185], v149
	ds_read_b128 v[186:189], v149 offset:1024
	ds_read_b128 v[190:193], v149 offset:2048
	ds_read_b128 v[194:197], v149 offset:3072
	ds_read_b128 v[202:205], v149 offset:4096
	ds_read_b128 v[206:209], v149 offset:5120
	ds_read_b128 v[210:213], v149 offset:6144
	ds_read_b128 v[214:217], v149 offset:7168
	s_cmp_lg_u32 s101, 0
	s_cbranch_scc1 .Ly1_skip_6
	global_load_lds_dwordx4 v[198:199], off
	v_lshl_add_u64 v[198:199], s[20:21], 0, v[138:139]
	s_add_i32 m0, s30, 0xe000
	s_nop 0
	global_load_lds_dwordx4 v[198:199], off

; #define PG8_STAGE(bufoff, gbase, voff) do { _Pragma("unroll") for (int _i = 0; _i < 2; ++_i) \
;         __builtin_amdgcn_global_load_lds((const unsigned*)((const char*)(gbase) + (voff)[_i]), (PG8_LAS unsigned*)(lds + (bufoff) + ldsw + _i * 8192), 16, 0, 0); } while (0)
; #define PG8_LDA(dst, b, h) do { _Pragma("unroll") for (int m = 0; m < 4; ++m) _Pragma("unroll") for (int k = 0; k < 2; ++k) dst[m][k] = *(const PG8_LAS bf16x8*)(lds + PG8_SA(b, h) + aoff + m * 2048 + k * 1024); } while (0)
; #define PG8_LDB(dst, b, h) do { _Pragma("unroll") for (int n = 0; n < 2; ++n) _Pragma("unroll") for (int k = 0; k < 2; ++k) dst[n][k] = *(const PG8_LAS bf16x8*)(lds + PG8_SB(b, h) + boff + n * 2048 + k * 1024); } while (0)
; #define PG8_MMA(ai, bj, At, Bt) do { __builtin_amdgcn_s_setprio(1); _Pragma("unroll") for (int m = 0; m < 4; ++m) _Pragma("unroll") for (int n = 0; n < 2; ++n) _Pragma("unroll") for (int k = 0; k < 2; ++k) \
;         acc[ai][bj][m][n] = __builtin_amdgcn_mfma_f32_16x16x32_bf16(Bt[n][k], At[m][k], acc[ai][bj][m][n], 0, 0, 0); __builtin_amdgcn_s_setprio(0); } while (0)
; #define PG8_WAIT_V(n) asm volatile("s_waitcnt vmcnt(" #n ")" ::: "memory")
; #define PG8_WAIT_L(n) asm volatile("s_waitcnt lgkmcnt(" #n ")" ::: "memory")
; #define PG8_BAR __builtin_amdgcn_s_barrier()
; #define PG8_SCHED __builtin_amdgcn_sched_barrier(0)
; template <class Epi, class Sched, bool ALIGN_EPI = false, bool SP2 = false>
; __device__ __forceinline__ void gemm_phase(PG8_LAS unsigned char* lds, const Gemm g, const Sched& S, const Epi& E) {
;     ...
;             PG8_WAIT_V(8); PG8_WAIT_L(0); PG8_BAR; PG8_MMA(0, 0, At, B0); PG8_MMA(0, 1, At, B1); PG8_BAR; PG8_SCHED;
;             PG8_LDA(At, 0, 1); PG8_STAGE(PG8_SB(0, 0), b2, voffB); PG8_STAGE(PG8_SB(0, 1), b2 + hstep, voffB); PG8_STAGE(PG8_SA(0, 0), a2, voffA);
;             PG8_WAIT_V(8); PG8_WAIT_L(0); PG8_BAR; PG8_MMA(1, 0, At, B0); PG8_MMA(1, 1, At, B1); PG8_BAR; PG8_SCHED;
;             PG8_LDB(B0, 1, 0); PG8_LDB(B1, 1, 1); PG8_SCHED; PG8_LDA(At, 1, 0); PG8_STAGE(PG8_SA(0, 1), a2 + hstep, voffA);
.Lwj_6_1:
	s_waitcnt lgkmcnt(0)
	s_barrier
	s_setprio 1
	s_waitcnt lgkmcnt(0)
	v_mfma_f32_16x16x32_bf16 v[60:63], v[150:153], v[182:185], 0
	v_mfma_f32_16x16x32_bf16 v[56:59], v[158:161], v[182:185], 0
	v_mfma_f32_16x16x32_bf16 v[44:47], v[150:153], v[190:193], 0
	v_mfma_f32_16x16x32_bf16 v[40:43], v[158:161], v[190:193], 0
	v_mfma_f32_16x16x32_bf16 v[28:31], v[150:153], v[202:205], 0
	v_mfma_f32_16x16x32_bf16 v[24:27], v[158:161], v[202:205], 0
	v_mfma_f32_16x16x32_bf16 v[12:15], v[150:153], v[210:213], 0
	v_mfma_f32_16x16x32_bf16 v[8:11], v[158:161], v[210:213], 0
	v_mfma_f32_16x16x32_bf16 v[60:63], v[154:157], v[186:189], v[60:63]
	v_mfma_f32_16x16x32_bf16 v[56:59], v[162:165], v[186:189], v[56:59]
	v_mfma_f32_16x16x32_bf16 v[44:47], v[154:157], v[194:197], v[44:47]
	v_mfma_f32_16x16x32_bf16 v[40:43], v[162:165], v[194:197], v[40:43]
	v_mfma_f32_16x16x32_bf16 v[28:31], v[154:157], v[206:209], v[28:31]
	v_mfma_f32_16x16x32_bf16 v[24:27], v[162:165], v[206:209], v[24:27]
	v_mfma_f32_16x16x32_bf16 v[12:15], v[154:157], v[214:217], v[12:15]
	v_mfma_f32_16x16x32_bf16 v[8:11], v[162:165], v[214:217], v[8:11]
	s_setprio 0
	s_setprio 1
	v_mfma_f32_16x16x32_bf16 v[52:55], v[166:169], v[182:185], 0
	v_mfma_f32_16x16x32_bf16 v[48:51], v[174:177], v[182:185], 0
	v_mfma_f32_16x16x32_bf16 v[36:39], v[166:169], v[190:193], 0
	v_mfma_f32_16x16x32_bf16 v[32:35], v[174:177], v[190:193], 0
	v_mfma_f32_16x16x32_bf16 v[20:23], v[166:169], v[202:205], 0
	v_mfma_f32_16x16x32_bf16 v[16:19], v[174:177], v[202:205], 0
	v_mfma_f32_16x16x32_bf16 v[4:7], v[166:169], v[210:213], 0
	v_mfma_f32_16x16x32_bf16 v[0:3], v[174:177], v[210:213], 0
	v_mfma_f32_16x16x32_bf16 v[52:55], v[170:173], v[186:189], v[52:55]
	v_mfma_f32_16x16x32_bf16 v[48:51], v[178:181], v[186:189], v[48:51]
	v_mfma_f32_16x16x32_bf16 v[36:39], v[170:173], v[194:197], v[36:39]
	v_mfma_f32_16x16x32_bf16 v[32:35], v[178:181], v[194:197], v[32:35]
	v_mfma_f32_16x16x32_bf16 v[20:23], v[170:173], v[206:209], v[20:23]
	v_mfma_f32_16x16x32_bf16 v[16:19], v[178:181], v[206:209], v[16:19]
	v_mfma_f32_16x16x32_bf16 v[4:7], v[170:173], v[214:217], v[4:7]
	v_mfma_f32_16x16x32_bf16 v[0:3], v[178:181], v[214:217], v[0:3]
	s_setprio 0
	s_barrier
	s_add_i32 s53, 0, 0x18000
	s_add_i32 s54, 0, 0x1c000
	v_add_u32_e32 v162, s53, v146
	v_add_u32_e32 v178, s54, v146
	ds_read_b128 v[150:153], v162
	ds_read_b128 v[154:157], v162 offset:1024
	ds_read_b128 v[158:161], v162 offset:2048
	ds_read_b128 v[162:165], v162 offset:3072
	ds_read_b128 v[166:169], v178
	ds_read_b128 v[170:173], v178 offset:1024
	ds_read_b128 v[174:177], v178 offset:2048
	ds_read_b128 v[178:181], v178 offset:3072
	s_add_u32 s22, s22, s6
	s_addc_u32 s23, s23, s7
	s_mov_b32 m0, s33
	v_lshl_add_u64 v[228:229], s[22:23], 0, v[128:129]
	ds_read_b128 v[182:185], v149 offset:32768
	ds_read_b128 v[186:189], v149 offset:33792
	ds_read_b128 v[190:193], v149 offset:34816
	ds_read_b128 v[194:197], v149 offset:35840
	ds_read_b128 v[202:205], v149 offset:36864
	ds_read_b128 v[206:209], v149 offset:37888
	ds_read_b128 v[210:213], v149 offset:38912
	ds_read_b128 v[214:217], v149 offset:39936
	global_load_lds_dwordx4 v[228:229], off
	v_lshl_add_u64 v[228:229], s[22:23], 0, v[132:133]
	s_mov_b32 m0, s34
	s_nop 0
	global_load_lds_dwordx4 v[228:229], off
	s_cmp_eq_u32 s99, 0
	s_cbranch_scc1 .Lw8_6_2
	s_waitcnt vmcnt(16)
	s_branch .Lwj_6_2

; #define PG8_STAGE(bufoff, gbase, voff) do { _Pragma("unroll") for (int _i = 0; _i < 2; ++_i) \
;         __builtin_amdgcn_global_load_lds((const unsigned*)((const char*)(gbase) + (voff)[_i]), (PG8_LAS unsigned*)(lds + (bufoff) + ldsw + _i * 8192), 16, 0, 0); } while (0)
; #define PG8_LDA(dst, b, h) do { _Pragma("unroll") for (int m = 0; m < 4; ++m) _Pragma("unroll") for (int k = 0; k < 2; ++k) dst[m][k] = *(const PG8_LAS bf16x8*)(lds + PG8_SA(b, h) + aoff + m * 2048 + k * 1024); } while (0)
; #define PG8_LDB(dst, b, h) do { _Pragma("unroll") for (int n = 0; n < 2; ++n) _Pragma("unroll") for (int k = 0; k < 2; ++k) dst[n][k] = *(const PG8_LAS bf16x8*)(lds + PG8_SB(b, h) + boff + n * 2048 + k * 1024); } while (0)
; #define PG8_MMA(ai, bj, At, Bt) do { __builtin_amdgcn_s_setprio(1); _Pragma("unroll") for (int m = 0; m < 4; ++m) _Pragma("unroll") for (int n = 0; n < 2; ++n) _Pragma("unroll") for (int k = 0; k < 2; ++k) \
;         acc[ai][bj][m][n] = __builtin_amdgcn_mfma_f32_16x16x32_bf16(Bt[n][k], At[m][k], acc[ai][bj][m][n], 0, 0, 0); __builtin_amdgcn_s_setprio(0); } while (0)
; #define PG8_WAIT_V(n) asm volatile("s_waitcnt vmcnt(" #n ")" ::: "memory")
; #define PG8_WAIT_L(n) asm volatile("s_waitcnt lgkmcnt(" #n ")" ::: "memory")
; #define PG8_BAR __builtin_amdgcn_s_barrier()
; #define PG8_SCHED __builtin_amdgcn_sched_barrier(0)
; template <class Epi, class Sched, bool ALIGN_EPI = false, bool SP2 = false>
; __device__ __forceinline__ void gemm_phase(PG8_LAS unsigned char* lds, const Gemm g, const Sched& S, const Epi& E) {
;     ...
;             PG8_WAIT_V(8); PG8_WAIT_L(0); PG8_BAR; PG8_MMA(1, 0, At, B0); PG8_MMA(1, 1, At, B1); PG8_BAR; PG8_SCHED;
;             PG8_LDB(B0, 1, 0); PG8_LDB(B1, 1, 1); PG8_SCHED; PG8_LDA(At, 1, 0); PG8_STAGE(PG8_SA(0, 1), a2 + hstep, voffA);
;             PG8_WAIT_V(8); PG8_WAIT_L(0); PG8_BAR; PG8_MMA(0, 0, At, B0); PG8_MMA(0, 1, At, B1); PG8_BAR; PG8_SCHED;
;             PG8_LDA(At, 1, 1); PG8_STAGE(PG8_SB(1, 0), b3, voffB); PG8_STAGE(PG8_SB(1, 1), b3 + hstep, voffB); PG8_STAGE(PG8_SA(1, 0), a3, voffA);
;             PG8_WAIT_V(8); PG8_WAIT_L(0); PG8_BAR; PG8_MMA(1, 0, At, B0); PG8_MMA(1, 1, At, B1); PG8_BAR; PG8_SCHED;
.Lwj_6_2:
	s_waitcnt lgkmcnt(0)
	s_barrier
	s_setprio 1
	s_waitcnt lgkmcnt(0)
	v_mfma_f32_16x16x32_bf16 v[120:123], v[150:153], v[182:185], v[120:123]
	v_mfma_f32_16x16x32_bf16 v[124:127], v[158:161], v[182:185], v[124:127]
	v_mfma_f32_16x16x32_bf16 v[108:111], v[150:153], v[190:193], v[108:111]
	v_mfma_f32_16x16x32_bf16 v[104:107], v[158:161], v[190:193], v[104:107]
	v_mfma_f32_16x16x32_bf16 v[92:95], v[150:153], v[202:205], v[92:95]
	v_mfma_f32_16x16x32_bf16 v[88:91], v[158:161], v[202:205], v[88:91]
	v_mfma_f32_16x16x32_bf16 v[76:79], v[150:153], v[210:213], v[76:79]
	v_mfma_f32_16x16x32_bf16 v[72:75], v[158:161], v[210:213], v[72:75]
	v_mfma_f32_16x16x32_bf16 v[120:123], v[154:157], v[186:189], v[120:123]
	v_mfma_f32_16x16x32_bf16 v[124:127], v[162:165], v[186:189], v[124:127]
	v_mfma_f32_16x16x32_bf16 v[108:111], v[154:157], v[194:197], v[108:111]
	v_mfma_f32_16x16x32_bf16 v[104:107], v[162:165], v[194:197], v[104:107]
	v_mfma_f32_16x16x32_bf16 v[92:95], v[154:157], v[206:209], v[92:95]
	v_mfma_f32_16x16x32_bf16 v[88:91], v[162:165], v[206:209], v[88:91]
	v_mfma_f32_16x16x32_bf16 v[76:79], v[154:157], v[214:217], v[76:79]
	v_mfma_f32_16x16x32_bf16 v[72:75], v[162:165], v[214:217], v[72:75]
	s_setprio 0
	s_setprio 1
	v_mfma_f32_16x16x32_bf16 v[116:119], v[166:169], v[182:185], v[116:119]
	v_mfma_f32_16x16x32_bf16 v[112:115], v[174:177], v[182:185], v[112:115]
	v_mfma_f32_16x16x32_bf16 v[100:103], v[166:169], v[190:193], v[100:103]
	v_mfma_f32_16x16x32_bf16 v[96:99], v[174:177], v[190:193], v[96:99]
	v_mfma_f32_16x16x32_bf16 v[84:87], v[166:169], v[202:205], v[84:87]
	v_mfma_f32_16x16x32_bf16 v[80:83], v[174:177], v[202:205], v[80:83]
	v_mfma_f32_16x16x32_bf16 v[68:71], v[166:169], v[210:213], v[68:71]
	v_mfma_f32_16x16x32_bf16 v[64:67], v[174:177], v[210:213], v[64:67]
	v_mfma_f32_16x16x32_bf16 v[116:119], v[170:173], v[186:189], v[116:119]
	v_mfma_f32_16x16x32_bf16 v[112:115], v[178:181], v[186:189], v[112:115]
	v_mfma_f32_16x16x32_bf16 v[100:103], v[170:173], v[194:197], v[100:103]
	v_mfma_f32_16x16x32_bf16 v[96:99], v[178:181], v[194:197], v[96:99]
	v_mfma_f32_16x16x32_bf16 v[84:87], v[170:173], v[206:209], v[84:87]
	v_mfma_f32_16x16x32_bf16 v[80:83], v[178:181], v[206:209], v[80:83]
	v_mfma_f32_16x16x32_bf16 v[68:71], v[170:173], v[214:217], v[68:71]
	v_mfma_f32_16x16x32_bf16 v[64:67], v[178:181], v[214:217], v[64:67]
	s_setprio 0
	s_barrier
	s_add_i32 s22, s53, s29
	v_lshl_add_u64 v[198:199], v[198:199], 0, s[12:13]
	s_mov_b32 m0, s22
	ds_read_b128 v[182:185], v149 offset:49152
	ds_read_b128 v[186:189], v149 offset:50176
	ds_read_b128 v[190:193], v149 offset:51200
	ds_read_b128 v[194:197], v149 offset:52224
	ds_read_b128 v[202:205], v149 offset:53248
	ds_read_b128 v[206:209], v149 offset:54272
	ds_read_b128 v[210:213], v149 offset:55296
	ds_read_b128 v[214:217], v149 offset:56320
	global_load_lds_dwordx4 v[198:199], off
	v_lshl_add_u64 v[198:199], v[218:219], 0, s[12:13]
	s_add_i32 m0, s22, 0x2000
	s_add_i32 s22, s54, s29
	global_load_lds_dwordx4 v[198:199], off
	v_lshl_add_u64 v[198:199], v[220:221], 0, s[12:13]
	s_mov_b32 m0, s22
	s_nop 0
	global_load_lds_dwordx4 v[198:199], off
	v_lshl_add_u64 v[198:199], v[222:223], 0, s[12:13]
	s_add_i32 m0, s22, 0x2000
	s_nop 0
	global_load_lds_dwordx4 v[198:199], off
	v_lshl_add_u64 v[198:199], v[224:225], 0, s[12:13]
	s_mov_b32 m0, s36
	s_nop 0
	global_load_lds_dwordx4 v[198:199], off
	v_lshl_add_u64 v[198:199], v[226:227], 0, s[12:13]
	s_mov_b32 m0, s37
	s_nop 0
	global_load_lds_dwordx4 v[198:199], off
	s_waitcnt vmcnt(8)
	s_waitcnt lgkmcnt(0)
	s_barrier
	s_setprio 1
	s_waitcnt lgkmcnt(0)
	v_mfma_f32_16x16x32_bf16 v[60:63], v[150:153], v[182:185], v[60:63]
	v_mfma_f32_16x16x32_bf16 v[56:59], v[158:161], v[182:185], v[56:59]
	v_mfma_f32_16x16x32_bf16 v[44:47], v[150:153], v[190:193], v[44:47]
	v_mfma_f32_16x16x32_bf16 v[40:43], v[158:161], v[190:193], v[40:43]
	v_mfma_f32_16x16x32_bf16 v[28:31], v[150:153], v[202:205], v[28:31]
	v_mfma_f32_16x16x32_bf16 v[24:27], v[158:161], v[202:205], v[24:27]
	v_mfma_f32_16x16x32_bf16 v[12:15], v[150:153], v[210:213], v[12:15]
	v_mfma_f32_16x16x32_bf16 v[8:11], v[158:161], v[210:213], v[8:11]
	v_mfma_f32_16x16x32_bf16 v[60:63], v[154:157], v[186:189], v[60:63]
	v_mfma_f32_16x16x32_bf16 v[56:59], v[162:165], v[186:189], v[56:59]
	v_mfma_f32_16x16x32_bf16 v[44:47], v[154:157], v[194:197], v[44:47]
	v_mfma_f32_16x16x32_bf16 v[40:43], v[162:165], v[194:197], v[40:43]
	v_mfma_f32_16x16x32_bf16 v[28:31], v[154:157], v[206:209], v[28:31]
	v_mfma_f32_16x16x32_bf16 v[24:27], v[162:165], v[206:209], v[24:27]
	v_mfma_f32_16x16x32_bf16 v[12:15], v[154:157], v[214:217], v[12:15]
	v_mfma_f32_16x16x32_bf16 v[8:11], v[162:165], v[214:217], v[8:11]
	s_setprio 0
	s_setprio 1
	v_mfma_f32_16x16x32_bf16 v[52:55], v[166:169], v[182:185], v[52:55]
	v_mfma_f32_16x16x32_bf16 v[48:51], v[174:177], v[182:185], v[48:51]
	v_mfma_f32_16x16x32_bf16 v[36:39], v[166:169], v[190:193], v[36:39]
	v_mfma_f32_16x16x32_bf16 v[32:35], v[174:177], v[190:193], v[32:35]
	v_mfma_f32_16x16x32_bf16 v[20:23], v[166:169], v[202:205], v[20:23]
	v_mfma_f32_16x16x32_bf16 v[16:19], v[174:177], v[202:205], v[16:19]
	v_mfma_f32_16x16x32_bf16 v[4:7], v[166:169], v[210:213], v[4:7]
	v_mfma_f32_16x16x32_bf16 v[0:3], v[174:177], v[210:213], v[0:3]
	v_mfma_f32_16x16x32_bf16 v[52:55], v[170:173], v[186:189], v[52:55]
	v_mfma_f32_16x16x32_bf16 v[48:51], v[178:181], v[186:189], v[48:51]
	v_mfma_f32_16x16x32_bf16 v[36:39], v[170:173], v[194:197], v[36:39]
	v_mfma_f32_16x16x32_bf16 v[32:35], v[178:181], v[194:197], v[32:35]
	v_mfma_f32_16x16x32_bf16 v[20:23], v[170:173], v[206:209], v[20:23]
	v_mfma_f32_16x16x32_bf16 v[16:19], v[178:181], v[206:209], v[16:19]
	v_mfma_f32_16x16x32_bf16 v[4:7], v[170:173], v[214:217], v[4:7]
	v_mfma_f32_16x16x32_bf16 v[0:3], v[178:181], v[214:217], v[0:3]
	s_setprio 0
	s_barrier
	s_add_u32 s20, s20, 0x100
	s_addc_u32 s21, s21, 0
	s_add_u32 s50, s50, 0x100
	s_addc_u32 s51, s51, 0
	s_cmp_ge_i32 s52, s38
	s_mov_b32 s22, s52
	s_cbranch_scc1 .LBB0_1398

; #define PG8_STAGE(bufoff, gbase, voff) do { _Pragma("unroll") for (int _i = 0; _i < 2; ++_i) \
;         __builtin_amdgcn_global_load_lds((const unsigned*)((const char*)(gbase) + (voff)[_i]), (PG8_LAS unsigned*)(lds + (bufoff) + ldsw + _i * 8192), 16, 0, 0); } while (0)
; #define PG8_LDA(dst, b, h) do { _Pragma("unroll") for (int m = 0; m < 4; ++m) _Pragma("unroll") for (int k = 0; k < 2; ++k) dst[m][k] = *(const PG8_LAS bf16x8*)(lds + PG8_SA(b, h) + aoff + m * 2048 + k * 1024); } while (0)
; #define PG8_LDB(dst, b, h) do { _Pragma("unroll") for (int n = 0; n < 2; ++n) _Pragma("unroll") for (int k = 0; k < 2; ++k) dst[n][k] = *(const PG8_LAS bf16x8*)(lds + PG8_SB(b, h) + boff + n * 2048 + k * 1024); } while (0)
; #define PG8_SCHED __builtin_amdgcn_sched_barrier(0)
; __device__ __forceinline__ u32x4 pk8(f32x4 a, f32x4 b) { u32x4 w; w.x = pk2(a[0], a[1]); w.y = pk2(a[2], a[3]); w.z = pk2(b[0], b[1]); w.w = pk2(b[2], b[3]); return w; }
; template <class Epi, class Sched, bool ALIGN_EPI = false, bool SP2 = false>
; __device__ __forceinline__ void gemm_phase(PG8_LAS unsigned char* lds, const Gemm g, const Sched& S, const Epi& E) {
;     ...
;             const char* a1 = cA + (size_t)(t + 1) * kstep;
;             const char* a2 = last ? nA : cA + (size_t)(t + 2) * kstep; const char* b2 = last ? nB : cB + (size_t)(t + 2) * kstep;
;             const char* a3 = a2 + kstep; const char* b3 = b2 + kstep;
;             if (last && has_next) S.a_ready(nxt);
;             if constexpr (SP2) {
;             PG8_LDB(B0, 0, 0); PG8_LDB(B1, 0, 1); PG8_SCHED; PG8_LDA(At, 0, 0); PG8_STAGE(PG8_SA(1, 1), a1 + hstep, voffA);
;     __device__ __forceinline__ void operator()(const AccT& acc, const Unit& u, int wr, int wc, int fr_, int fq_) const {
;         int fr = fr_, fq = fq_; asm volatile("" : "+v"(fr), "+v"(fq));
;         bf16_t* const O = (bf16_t*)(ws + WS_RB);
; #pragma unroll
;         for (int ai = 0; ai < 2; ++ai)
; #pragma unroll
;             for (int m = 0; m < 4; ++m) {
;                 const size_t row = (size_t)ROW_OF(ai, m);
; #pragma unroll
;                 for (int bj = 0; bj < 2; ++bj)
;                     st16c(O + row * 1024 + u.pn * 256 + bj * 128 + wc * 32 + 8 * fq, pk8(acc[ai][bj][m][0], acc[ai][bj][m][1]));
;             }
.LBB0_1400:
	s_mov_b32 s99, 1
	v_lshl_add_u64 v[198:199], s[0:1], 0, v[136:137]
	v_lshl_add_u64 v[198:199], v[198:199], 0, 64
	v_lshl_add_u64 v[198:199], v[198:199], 0, 64
	s_add_i32 m0, s30, 0xc000
	s_mov_b32 s101, 1
	global_load_lds_dwordx4 v[198:199], off
	v_lshl_add_u64 v[198:199], s[0:1], 0, v[138:139]
	v_lshl_add_u64 v[198:199], v[198:199], 0, 64
	v_lshl_add_u64 v[198:199], v[198:199], 0, 64
	s_add_i32 m0, s30, 0xe000
	s_nop 0
	global_load_lds_dwordx4 v[198:199], off
	v_mov_b32_e32 v150, v144
	v_mov_b32_e32 v151, v145
	s_lshl_b32 s20, s46, 8
	s_add_i32 s20, s20, s39
	v_add_u32_e32 v150, s20, v150
	s_lshl_b32 s20, s49, 8
	s_ashr_i32 s21, s20, 31
	s_lshl_b64 s[20:21], s[20:21], 1
	s_add_u32 s20, s41, s20
	v_lshlrev_b32_e32 v152, 3, v151
	v_cvt_pk_bf16_f32 v116, v116, v117
	v_cvt_pk_bf16_f32 v117, v118, v119
	v_cvt_pk_bf16_f32 v118, v112, v113
	v_add_u32_e32 v112, 16, v150
	v_cvt_pk_bf16_f32 v100, v100, v101
	v_cvt_pk_bf16_f32 v101, v102, v103
	v_cvt_pk_bf16_f32 v102, v96, v97
	v_add_u32_e32 v96, 32, v150
	v_cvt_pk_bf16_f32 v84, v84, v85
	v_cvt_pk_bf16_f32 v85, v86, v87
	v_cvt_pk_bf16_f32 v86, v80, v81
	v_add_u32_e32 v80, 48, v150
	v_cvt_pk_bf16_f32 v68, v68, v69
	v_cvt_pk_bf16_f32 v69, v70, v71
	v_cvt_pk_bf16_f32 v70, v64, v65
	v_add_u32_e32 v64, 0x80, v150
	v_cvt_pk_bf16_f32 v52, v52, v53
	v_cvt_pk_bf16_f32 v53, v54, v55
	v_cvt_pk_bf16_f32 v54, v48, v49
	v_add_u32_e32 v48, 0x90, v150
	v_cvt_pk_bf16_f32 v36, v36, v37
	v_cvt_pk_bf16_f32 v37, v38, v39
	v_cvt_pk_bf16_f32 v38, v32, v33
	v_add_u32_e32 v32, 0xa0, v150
	v_cvt_pk_bf16_f32 v20, v20, v21
	v_cvt_pk_bf16_f32 v21, v22, v23
	v_cvt_pk_bf16_f32 v22, v16, v17
	v_add_u32_e32 v16, 0xb0, v150
	s_addc_u32 s21, s42, s21
	v_ashrrev_i32_e32 v153, 31, v152
	v_ashrrev_i32_e32 v151, 31, v150
	v_ashrrev_i32_e32 v113, 31, v112
	v_ashrrev_i32_e32 v97, 31, v96
	v_ashrrev_i32_e32 v81, 31, v80
	v_ashrrev_i32_e32 v65, 31, v64
	v_ashrrev_i32_e32 v49, 31, v48
	v_ashrrev_i32_e32 v33, 31, v32
	v_ashrrev_i32_e32 v17, 31, v16
	v_lshl_add_u64 v[152:153], v[152:153], 1, s[20:21]
	v_lshlrev_b64 v[154:155], 11, v[150:151]
	v_lshlrev_b64 v[112:113], 11, v[112:113]
	v_lshlrev_b64 v[96:97], 11, v[96:97]
	v_lshlrev_b64 v[80:81], 11, v[80:81]
	v_lshlrev_b64 v[64:65], 11, v[64:65]
	v_lshlrev_b64 v[48:49], 11, v[48:49]
	v_lshlrev_b64 v[32:33], 11, v[32:33]
	v_lshlrev_b64 v[16:17], 11, v[16:17]
	v_lshl_add_u64 v[154:155], v[152:153], 0, v[154:155]
	v_cvt_pk_bf16_f32 v120, v120, v121
	v_cvt_pk_bf16_f32 v121, v122, v123
	v_cvt_pk_bf16_f32 v122, v124, v125
	v_cvt_pk_bf16_f32 v123, v126, v127
	v_cvt_pk_bf16_f32 v119, v114, v115
	v_lshl_add_u64 v[112:113], v[152:153], 0, v[112:113]
	v_cvt_pk_bf16_f32 v108, v108, v109
	v_cvt_pk_bf16_f32 v109, v110, v111
	v_cvt_pk_bf16_f32 v110, v104, v105
	v_cvt_pk_bf16_f32 v111, v106, v107
	v_cvt_pk_bf16_f32 v103, v98, v99
	v_lshl_add_u64 v[96:97], v[152:153], 0, v[96:97]
	v_cvt_pk_bf16_f32 v92, v92, v93
	v_cvt_pk_bf16_f32 v93, v94, v95
	v_cvt_pk_bf16_f32 v94, v88, v89
	v_cvt_pk_bf16_f32 v95, v90, v91
	v_cvt_pk_bf16_f32 v87, v82, v83
	v_lshl_add_u64 v[80:81], v[152:153], 0, v[80:81]
	v_cvt_pk_bf16_f32 v76, v76, v77
	v_cvt_pk_bf16_f32 v77, v78, v79
	v_cvt_pk_bf16_f32 v78, v72, v73
	v_cvt_pk_bf16_f32 v79, v74, v75
	v_cvt_pk_bf16_f32 v71, v66, v67
	v_lshl_add_u64 v[64:65], v[152:153], 0, v[64:65]
	v_cvt_pk_bf16_f32 v60, v60, v61
	v_cvt_pk_bf16_f32 v61, v62, v63
	v_cvt_pk_bf16_f32 v62, v56, v57
	v_cvt_pk_bf16_f32 v63, v58, v59
	v_cvt_pk_bf16_f32 v55, v50, v51
	v_lshl_add_u64 v[48:49], v[152:153], 0, v[48:49]
	v_cvt_pk_bf16_f32 v44, v44, v45
	v_cvt_pk_bf16_f32 v45, v46, v47
	v_cvt_pk_bf16_f32 v46, v40, v41
	v_cvt_pk_bf16_f32 v47, v42, v43
	v_cvt_pk_bf16_f32 v39, v34, v35
	v_lshl_add_u64 v[32:33], v[152:153], 0, v[32:33]
	v_cvt_pk_bf16_f32 v28, v28, v29
	v_cvt_pk_bf16_f32 v29, v30, v31
	v_cvt_pk_bf16_f32 v30, v24, v25
	v_cvt_pk_bf16_f32 v31, v26, v27
	v_cvt_pk_bf16_f32 v23, v18, v19
	v_lshl_add_u64 v[16:17], v[152:153], 0, v[16:17]
	v_cvt_pk_bf16_f32 v12, v12, v13
	v_cvt_pk_bf16_f32 v13, v14, v15
	v_cvt_pk_bf16_f32 v14, v8, v9
	v_cvt_pk_bf16_f32 v15, v10, v11
	v_cvt_pk_bf16_f32 v4, v4, v5
	v_cvt_pk_bf16_f32 v5, v6, v7
	v_cvt_pk_bf16_f32 v6, v0, v1
	v_cvt_pk_bf16_f32 v7, v2, v3
	s_and_b64 vcc, exec, s[2:3]
	s_mov_b64 s[2:3], -1
	global_store_dwordx4 v[154:155], v[120:123], off
	global_store_dwordx4 v[154:155], v[116:119], off offset:256
	global_store_dwordx4 v[112:113], v[108:111], off
	global_store_dwordx4 v[112:113], v[100:103], off offset:256
	global_store_dwordx4 v[96:97], v[92:95], off
	global_store_dwordx4 v[96:97], v[84:87], off offset:256
	global_store_dwordx4 v[80:81], v[76:79], off
	global_store_dwordx4 v[80:81], v[68:71], off offset:256
	global_store_dwordx4 v[64:65], v[60:63], off
	global_store_dwordx4 v[64:65], v[52:55], off offset:256
	global_store_dwordx4 v[48:49], v[44:47], off
	global_store_dwordx4 v[48:49], v[36:39], off offset:256
	global_store_dwordx4 v[32:33], v[28:31], off
	global_store_dwordx4 v[32:33], v[20:23], off offset:256
	global_store_dwordx4 v[16:17], v[12:15], off
	global_store_dwordx4 v[16:17], v[4:7], off offset:256
	s_cbranch_vccnz .LBB0_1384
	s_andn2_b64 vcc, exec, s[10:11]
	s_cbranch_vccnz .LBB0_1383
	s_barrier
	s_branch .LBB0_1383
